# all GEMMs: skip first two K-loop vmcnt waits after an epilogue (stores drain under MFMA); column remap extended to P5/P7/P10/P12 residual GEMMs
# speedup vs baseline: 1.0103x; 1.0036x over previous
.LBB0_27:
	s_lshl_b32 s26, s24, 1
	s_lshl_b32 s27, s4, 1
	v_or_b32_e32 v4, s27, v52
	s_add_i32 s62, s26, 4
	s_add_i32 s63, s27, 4
	v_mov_b32_e32 v57, v5
	s_add_i32 s65, s27, 8
	v_lshlrev_b64 v[82:83], 12, v[4:5]
	v_or_b32_e32 v56, s62, v11
	v_or_b32_e32 v4, s63, v52
	v_mov_b32_e32 v55, v5
	v_or_b32_e32 v54, s26, v11
	s_add_i32 s67, s27, 12
	v_lshlrev_b64 v[56:57], 12, v[56:57]
	v_lshlrev_b64 v[84:85], 12, v[4:5]
	v_or_b32_e32 v4, s65, v52
	s_add_i32 s64, s26, 8
	s_add_i32 s66, s26, 12
	s_add_i32 s69, s27, 16
	v_lshlrev_b64 v[54:55], 12, v[54:55]
	v_lshl_add_u64 v[82:83], v[50:51], 0, v[82:83]
	v_lshl_add_u64 v[56:57], v[50:51], 0, v[56:57]
	v_lshlrev_b64 v[86:87], 12, v[4:5]
	v_or_b32_e32 v4, s67, v52
	v_mov_b32_e32 v59, v5
	v_mov_b32_e32 v61, v5
	s_add_i32 s71, s27, 20
	v_or_b32_e32 v58, s64, v11
	v_or_b32_e32 v60, s66, v11
	v_lshl_add_u64 v[54:55], v[50:51], 0, v[54:55]
	v_lshl_add_u64 v[84:85], v[50:51], 0, v[84:85]
	global_load_dword v53, v[82:83], off
	global_load_dword v98, v[54:55], off
	global_load_dword v99, v[84:85], off
	global_load_dword v100, v[56:57], off
	v_lshlrev_b64 v[56:57], 12, v[4:5]
	v_or_b32_e32 v4, s69, v52
	s_add_i32 s68, s26, 16
	s_add_i32 s70, s26, 20
	s_add_i32 s73, s27, 24
	v_lshlrev_b64 v[58:59], 12, v[58:59]
	v_lshlrev_b64 v[60:61], 12, v[60:61]
	v_lshl_add_u64 v[54:55], v[50:51], 0, v[86:87]
	v_lshl_add_u64 v[56:57], v[50:51], 0, v[56:57]
	v_lshlrev_b64 v[82:83], 12, v[4:5]
	v_or_b32_e32 v4, s71, v52
	v_mov_b32_e32 v63, v5
	v_mov_b32_e32 v65, v5
	s_add_i32 s72, s26, 24
	s_add_i32 s74, s26, 28
	s_add_i32 s75, s27, 28
	v_or_b32_e32 v62, s68, v11
	v_or_b32_e32 v64, s70, v11
	v_lshl_add_u64 v[58:59], v[50:51], 0, v[58:59]
	v_lshl_add_u64 v[60:61], v[50:51], 0, v[60:61]
	global_load_dword v101, v[54:55], off
	global_load_dword v102, v[58:59], off
	global_load_dword v103, v[56:57], off
	global_load_dword v104, v[60:61], off
	v_lshlrev_b64 v[56:57], 12, v[4:5]
	v_or_b32_e32 v4, s73, v52
	v_mov_b32_e32 v67, v5
	v_mov_b32_e32 v69, v5
	v_or_b32_e32 v66, s72, v11
	v_or_b32_e32 v68, s74, v11
	v_lshlrev_b64 v[62:63], 12, v[62:63]
	v_lshlrev_b64 v[64:65], 12, v[64:65]
	v_lshl_add_u64 v[54:55], v[50:51], 0, v[82:83]
	v_lshl_add_u64 v[56:57], v[50:51], 0, v[56:57]
	v_lshlrev_b64 v[58:59], 12, v[4:5]
	v_or_b32_e32 v4, s75, v52
	v_lshlrev_b64 v[66:67], 12, v[66:67]
	v_lshlrev_b64 v[68:69], 12, v[68:69]
	v_lshl_add_u64 v[62:63], v[50:51], 0, v[62:63]
	v_lshl_add_u64 v[64:65], v[50:51], 0, v[64:65]
	global_load_dword v105, v[54:55], off
	global_load_dword v106, v[62:63], off
	global_load_dword v107, v[56:57], off
	global_load_dword v108, v[64:65], off
	v_lshl_add_u64 v[54:55], v[50:51], 0, v[58:59]
	v_lshlrev_b64 v[56:57], 12, v[4:5]
	v_lshl_add_u64 v[66:67], v[50:51], 0, v[66:67]
	v_lshl_add_u64 v[68:69], v[50:51], 0, v[68:69]
	v_lshl_add_u64 v[56:57], v[50:51], 0, v[56:57]
	global_load_dword v4, v[54:55], off
	global_load_dword v109, v[66:67], off
	global_load_dword v110, v[56:57], off
	global_load_dword v111, v[68:69], off
	v_or_b32_e32 v56, s26, v1
	v_or_b32_e32 v54, s27, v2
	s_add_i32 s4, s4, 16
	s_add_i32 s24, s24, 16
	s_add_i32 s25, s25, -16
	v_mad_u64_u32 v[54:55], s[26:27], v54, s3, v[10:11]
	v_mad_u64_u32 v[56:57], s[26:27], v56, s3, v[10:11]
	v_or_b32_e32 v55, s62, v1
	v_or_b32_e32 v57, s63, v2
	v_or_b32_e32 v64, s64, v1
	v_or_b32_e32 v62, s65, v2
	v_or_b32_e32 v68, s66, v1
	v_or_b32_e32 v66, s67, v2
	v_or_b32_e32 v84, s68, v1
	v_or_b32_e32 v82, s69, v2
	v_or_b32_e32 v88, s70, v1
	v_or_b32_e32 v86, s71, v2
	v_or_b32_e32 v92, s72, v1
	v_or_b32_e32 v90, s73, v2
	v_or_b32_e32 v96, s74, v1
	v_or_b32_e32 v94, s75, v2
	s_cmp_lg_u32 s25, 0
	v_mad_u64_u32 v[58:59], s[26:27], v57, s3, v[10:11]
	v_mad_u64_u32 v[60:61], s[26:27], v55, s3, v[10:11]
	v_mad_u64_u32 v[62:63], s[26:27], v62, s3, v[10:11]
	v_mad_u64_u32 v[64:65], s[26:27], v64, s3, v[10:11]
	v_mad_u64_u32 v[66:67], s[26:27], v66, s3, v[10:11]
	v_mad_u64_u32 v[68:69], s[26:27], v68, s3, v[10:11]
	v_mad_u64_u32 v[82:83], s[26:27], v82, s3, v[10:11]
	v_mad_u64_u32 v[84:85], s[26:27], v84, s3, v[10:11]
	v_mad_u64_u32 v[86:87], s[26:27], v86, s3, v[10:11]
	v_mad_u64_u32 v[88:89], s[26:27], v88, s3, v[10:11]
	v_mad_u64_u32 v[90:91], s[26:27], v90, s3, v[10:11]
	v_mad_u64_u32 v[92:93], s[26:27], v92, s3, v[10:11]
	v_mad_u64_u32 v[94:95], s[26:27], v94, s3, v[10:11]
	v_mad_u64_u32 v[96:97], s[26:27], v96, s3, v[10:11]
	s_waitcnt vmcnt(15)
	ds_write_b32 v54, v53
	s_waitcnt vmcnt(14)
	ds_write_b32 v56, v98
	s_waitcnt vmcnt(13)
	ds_write_b32 v58, v99
	s_waitcnt vmcnt(12)
	ds_write_b32 v60, v100
	s_waitcnt vmcnt(11)
	ds_write_b32 v62, v101
	s_waitcnt vmcnt(10)
	ds_write_b32 v64, v102
	s_waitcnt vmcnt(9)
	ds_write_b32 v66, v103
	s_waitcnt vmcnt(8)
	ds_write_b32 v68, v104
	s_waitcnt vmcnt(7)
	ds_write_b32 v82, v105
	s_waitcnt vmcnt(6)
	ds_write_b32 v84, v106
	s_waitcnt vmcnt(5)
	ds_write_b32 v86, v107
	s_waitcnt vmcnt(4)
	ds_write_b32 v88, v108
	s_waitcnt vmcnt(3)
	ds_write_b32 v90, v4
	s_waitcnt vmcnt(2)
	ds_write_b32 v92, v109
	s_waitcnt vmcnt(1)
	ds_write_b32 v94, v110
	s_waitcnt vmcnt(0)
	ds_write_b32 v96, v111
	s_cbranch_scc1 .LBB0_27
	s_waitcnt lgkmcnt(0)
	ds_read2_b32 v[50:51], v70 offset1:33
	s_waitcnt lgkmcnt(0)
	v_cvt_pk_bf16_f32 v50, v50, v51
	ds_read2_b32 v[52:53], v70 offset0:66 offset1:99
	s_lshl_b32 s4, s1, 1
	s_bfe_u32 s98, s0, 0x10005
	s_bfe_u32 s99, s0, 0x20006
	s_lshl_b32 s98, s98, 7
	s_lshl_b32 s99, s99, 5
	s_or_b32 s98, s98, s99
	s_andn2_b32 s99, s0, 0xe0
	s_or_b32 s98, s98, s99
	v_or_b32_e32 v4, s98, v45
	s_waitcnt lgkmcnt(0)
	v_cvt_pk_bf16_f32 v51, v52, v53
	ds_read2_b32 v[52:53], v70 offset0:132 offset1:165
	v_lshl_add_u64 v[56:57], v[12:13], 0, s[4:5]
	v_lshlrev_b32_e32 v4, 13, v4
	s_waitcnt lgkmcnt(0)
	v_cvt_pk_bf16_f32 v52, v52, v53
	ds_read2_b32 v[54:55], v70 offset0:198 offset1:231
	s_waitcnt lgkmcnt(0)
	v_cvt_pk_bf16_f32 v53, v54, v55
	v_lshl_add_u64 v[58:59], v[56:57], 0, v[4:5]
	ds_read2_b32 v[54:55], v70 offset0:8 offset1:41
	global_store_dwordx4 v[58:59], v[50:53], off
	v_or_b32_e32 v4, s98, v71
	v_lshlrev_b32_e32 v4, 13, v4
	s_waitcnt lgkmcnt(0)
	v_cvt_pk_bf16_f32 v50, v54, v55
	ds_read2_b32 v[52:53], v70 offset0:74 offset1:107
	s_waitcnt lgkmcnt(0)
	v_cvt_pk_bf16_f32 v51, v52, v53
	ds_read2_b32 v[52:53], v70 offset0:140 offset1:173
	s_waitcnt lgkmcnt(0)
	v_cvt_pk_bf16_f32 v52, v52, v53
	ds_read2_b32 v[54:55], v70 offset0:206 offset1:239
	s_waitcnt lgkmcnt(0)
	v_cvt_pk_bf16_f32 v53, v54, v55
	v_lshl_add_u64 v[58:59], v[56:57], 0, v[4:5]
	ds_read2_b32 v[54:55], v70 offset0:16 offset1:49
	global_store_dwordx4 v[58:59], v[50:53], off
	v_or_b32_e32 v4, s98, v72
	v_lshlrev_b32_e32 v4, 13, v4
	s_waitcnt lgkmcnt(0)
	v_cvt_pk_bf16_f32 v50, v54, v55
	ds_read2_b32 v[52:53], v70 offset0:82 offset1:115
	s_waitcnt lgkmcnt(0)
	v_cvt_pk_bf16_f32 v51, v52, v53
	ds_read2_b32 v[52:53], v70 offset0:148 offset1:181
	s_waitcnt lgkmcnt(0)
	v_cvt_pk_bf16_f32 v52, v52, v53
	ds_read2_b32 v[54:55], v70 offset0:214 offset1:247
	s_waitcnt lgkmcnt(0)
	v_cvt_pk_bf16_f32 v53, v54, v55
	v_lshl_add_u64 v[58:59], v[56:57], 0, v[4:5]
	ds_read2_b32 v[54:55], v70 offset0:24 offset1:57
	global_store_dwordx4 v[58:59], v[50:53], off
	v_or_b32_e32 v4, s98, v73
	v_lshlrev_b32_e32 v4, 13, v4
	s_waitcnt lgkmcnt(0)
	v_cvt_pk_bf16_f32 v50, v54, v55
	ds_read2_b32 v[52:53], v70 offset0:90 offset1:123
	s_waitcnt lgkmcnt(0)
	v_cvt_pk_bf16_f32 v51, v52, v53
	ds_read2_b32 v[52:53], v70 offset0:156 offset1:189
	s_waitcnt lgkmcnt(0)
	v_cvt_pk_bf16_f32 v52, v52, v53
	ds_read2_b32 v[54:55], v70 offset0:222 offset1:255
	s_waitcnt lgkmcnt(0)
	v_cvt_pk_bf16_f32 v53, v54, v55
	v_lshl_add_u64 v[54:55], v[56:57], 0, v[4:5]
	global_store_dwordx4 v[54:55], v[50:53], off
	s_waitcnt lgkmcnt(0)
	s_mov_b64 s[0:1], 0

.LBB0_36:
	s_lshl_b32 s26, s24, 1
	s_lshl_b32 s27, s4, 1
	v_or_b32_e32 v4, s27, v52
	s_add_i32 s62, s26, 4
	s_add_i32 s63, s27, 4
	v_mov_b32_e32 v57, v5
	s_add_i32 s65, s27, 8
	v_lshlrev_b64 v[82:83], 12, v[4:5]
	v_or_b32_e32 v56, s62, v11
	v_or_b32_e32 v4, s63, v52
	v_mov_b32_e32 v55, v5
	v_or_b32_e32 v54, s26, v11
	s_add_i32 s67, s27, 12
	v_lshlrev_b64 v[56:57], 12, v[56:57]
	v_lshlrev_b64 v[84:85], 12, v[4:5]
	v_or_b32_e32 v4, s65, v52
	s_add_i32 s64, s26, 8
	s_add_i32 s66, s26, 12
	s_add_i32 s69, s27, 16
	v_lshlrev_b64 v[54:55], 12, v[54:55]
	v_lshl_add_u64 v[82:83], v[50:51], 0, v[82:83]
	v_lshl_add_u64 v[56:57], v[50:51], 0, v[56:57]
	v_lshlrev_b64 v[86:87], 12, v[4:5]
	v_or_b32_e32 v4, s67, v52
	v_mov_b32_e32 v59, v5
	v_mov_b32_e32 v61, v5
	s_add_i32 s71, s27, 20
	v_or_b32_e32 v58, s64, v11
	v_or_b32_e32 v60, s66, v11
	v_lshl_add_u64 v[54:55], v[50:51], 0, v[54:55]
	v_lshl_add_u64 v[84:85], v[50:51], 0, v[84:85]
	global_load_dword v53, v[82:83], off
	global_load_dword v98, v[54:55], off
	global_load_dword v99, v[84:85], off
	global_load_dword v100, v[56:57], off
	v_lshlrev_b64 v[56:57], 12, v[4:5]
	v_or_b32_e32 v4, s69, v52
	s_add_i32 s68, s26, 16
	s_add_i32 s70, s26, 20
	s_add_i32 s73, s27, 24
	v_lshlrev_b64 v[58:59], 12, v[58:59]
	v_lshlrev_b64 v[60:61], 12, v[60:61]
	v_lshl_add_u64 v[54:55], v[50:51], 0, v[86:87]
	v_lshl_add_u64 v[56:57], v[50:51], 0, v[56:57]
	v_lshlrev_b64 v[82:83], 12, v[4:5]
	v_or_b32_e32 v4, s71, v52
	v_mov_b32_e32 v63, v5
	v_mov_b32_e32 v65, v5
	s_add_i32 s72, s26, 24
	s_add_i32 s74, s26, 28
	s_add_i32 s75, s27, 28
	v_or_b32_e32 v62, s68, v11
	v_or_b32_e32 v64, s70, v11
	v_lshl_add_u64 v[58:59], v[50:51], 0, v[58:59]
	v_lshl_add_u64 v[60:61], v[50:51], 0, v[60:61]
	global_load_dword v101, v[54:55], off
	global_load_dword v102, v[58:59], off
	global_load_dword v103, v[56:57], off
	global_load_dword v104, v[60:61], off
	v_lshlrev_b64 v[56:57], 12, v[4:5]
	v_or_b32_e32 v4, s73, v52
	v_mov_b32_e32 v67, v5
	v_mov_b32_e32 v69, v5
	v_or_b32_e32 v66, s72, v11
	v_or_b32_e32 v68, s74, v11
	v_lshlrev_b64 v[62:63], 12, v[62:63]
	v_lshlrev_b64 v[64:65], 12, v[64:65]
	v_lshl_add_u64 v[54:55], v[50:51], 0, v[82:83]
	v_lshl_add_u64 v[56:57], v[50:51], 0, v[56:57]
	v_lshlrev_b64 v[58:59], 12, v[4:5]
	v_or_b32_e32 v4, s75, v52
	v_lshlrev_b64 v[66:67], 12, v[66:67]
	v_lshlrev_b64 v[68:69], 12, v[68:69]
	v_lshl_add_u64 v[62:63], v[50:51], 0, v[62:63]
	v_lshl_add_u64 v[64:65], v[50:51], 0, v[64:65]
	global_load_dword v105, v[54:55], off
	global_load_dword v106, v[62:63], off
	global_load_dword v107, v[56:57], off
	global_load_dword v108, v[64:65], off
	v_lshl_add_u64 v[54:55], v[50:51], 0, v[58:59]
	v_lshlrev_b64 v[56:57], 12, v[4:5]
	v_lshl_add_u64 v[66:67], v[50:51], 0, v[66:67]
	v_lshl_add_u64 v[68:69], v[50:51], 0, v[68:69]
	v_lshl_add_u64 v[56:57], v[50:51], 0, v[56:57]
	global_load_dword v4, v[54:55], off
	global_load_dword v109, v[66:67], off
	global_load_dword v110, v[56:57], off
	global_load_dword v111, v[68:69], off
	v_or_b32_e32 v56, s26, v1
	v_or_b32_e32 v54, s27, v2
	s_add_i32 s4, s4, 16
	s_add_i32 s24, s24, 16
	s_add_i32 s25, s25, -16
	v_mad_u64_u32 v[54:55], s[26:27], v54, s3, v[10:11]
	v_mad_u64_u32 v[56:57], s[26:27], v56, s3, v[10:11]
	v_or_b32_e32 v55, s62, v1
	v_or_b32_e32 v57, s63, v2
	v_or_b32_e32 v64, s64, v1
	v_or_b32_e32 v62, s65, v2
	v_or_b32_e32 v68, s66, v1
	v_or_b32_e32 v66, s67, v2
	v_or_b32_e32 v84, s68, v1
	v_or_b32_e32 v82, s69, v2
	v_or_b32_e32 v88, s70, v1
	v_or_b32_e32 v86, s71, v2
	v_or_b32_e32 v92, s72, v1
	v_or_b32_e32 v90, s73, v2
	v_or_b32_e32 v96, s74, v1
	v_or_b32_e32 v94, s75, v2
	s_cmp_lg_u32 s25, 0
	v_mad_u64_u32 v[58:59], s[26:27], v57, s3, v[10:11]
	v_mad_u64_u32 v[60:61], s[26:27], v55, s3, v[10:11]
	v_mad_u64_u32 v[62:63], s[26:27], v62, s3, v[10:11]
	v_mad_u64_u32 v[64:65], s[26:27], v64, s3, v[10:11]
	v_mad_u64_u32 v[66:67], s[26:27], v66, s3, v[10:11]
	v_mad_u64_u32 v[68:69], s[26:27], v68, s3, v[10:11]
	v_mad_u64_u32 v[82:83], s[26:27], v82, s3, v[10:11]
	v_mad_u64_u32 v[84:85], s[26:27], v84, s3, v[10:11]
	v_mad_u64_u32 v[86:87], s[26:27], v86, s3, v[10:11]
	v_mad_u64_u32 v[88:89], s[26:27], v88, s3, v[10:11]
	v_mad_u64_u32 v[90:91], s[26:27], v90, s3, v[10:11]
	v_mad_u64_u32 v[92:93], s[26:27], v92, s3, v[10:11]
	v_mad_u64_u32 v[94:95], s[26:27], v94, s3, v[10:11]
	v_mad_u64_u32 v[96:97], s[26:27], v96, s3, v[10:11]
	s_waitcnt vmcnt(15)
	ds_write_b32 v54, v53
	s_waitcnt vmcnt(14)
	ds_write_b32 v56, v98
	s_waitcnt vmcnt(13)
	ds_write_b32 v58, v99
	s_waitcnt vmcnt(12)
	ds_write_b32 v60, v100
	s_waitcnt vmcnt(11)
	ds_write_b32 v62, v101
	s_waitcnt vmcnt(10)
	ds_write_b32 v64, v102
	s_waitcnt vmcnt(9)
	ds_write_b32 v66, v103
	s_waitcnt vmcnt(8)
	ds_write_b32 v68, v104
	s_waitcnt vmcnt(7)
	ds_write_b32 v82, v105
	s_waitcnt vmcnt(6)
	ds_write_b32 v84, v106
	s_waitcnt vmcnt(5)
	ds_write_b32 v86, v107
	s_waitcnt vmcnt(4)
	ds_write_b32 v88, v108
	s_waitcnt vmcnt(3)
	ds_write_b32 v90, v4
	s_waitcnt vmcnt(2)
	ds_write_b32 v92, v109
	s_waitcnt vmcnt(1)
	ds_write_b32 v94, v110
	s_waitcnt vmcnt(0)
	ds_write_b32 v96, v111
	s_cbranch_scc1 .LBB0_36
	s_waitcnt lgkmcnt(0)
	ds_read2_b32 v[50:51], v70 offset1:33
	s_waitcnt lgkmcnt(0)
	v_cvt_pk_bf16_f32 v50, v50, v51
	ds_read2_b32 v[52:53], v70 offset0:66 offset1:99
	s_lshl_b32 s4, s1, 1
	s_bfe_u32 s98, s0, 0x10005
	s_bfe_u32 s99, s0, 0x20006
	s_lshl_b32 s98, s98, 7
	s_lshl_b32 s99, s99, 5
	s_or_b32 s98, s98, s99
	s_andn2_b32 s99, s0, 0xe0
	s_or_b32 s98, s98, s99
	v_or_b32_e32 v4, s98, v45
	s_waitcnt lgkmcnt(0)
	v_cvt_pk_bf16_f32 v51, v52, v53
	ds_read2_b32 v[52:53], v70 offset0:132 offset1:165
	v_lshl_add_u64 v[56:57], v[22:23], 0, s[4:5]
	v_lshlrev_b32_e32 v4, 11, v4
	s_waitcnt lgkmcnt(0)
	v_cvt_pk_bf16_f32 v52, v52, v53
	ds_read2_b32 v[54:55], v70 offset0:198 offset1:231
	s_waitcnt lgkmcnt(0)
	v_cvt_pk_bf16_f32 v53, v54, v55
	v_lshl_add_u64 v[58:59], v[56:57], 0, v[4:5]
	ds_read2_b32 v[54:55], v70 offset0:8 offset1:41
	global_store_dwordx4 v[58:59], v[50:53], off
	v_or_b32_e32 v4, s98, v71
	v_lshlrev_b32_e32 v4, 11, v4
	s_waitcnt lgkmcnt(0)
	v_cvt_pk_bf16_f32 v50, v54, v55
	ds_read2_b32 v[52:53], v70 offset0:74 offset1:107
	s_waitcnt lgkmcnt(0)
	v_cvt_pk_bf16_f32 v51, v52, v53
	ds_read2_b32 v[52:53], v70 offset0:140 offset1:173
	s_waitcnt lgkmcnt(0)
	v_cvt_pk_bf16_f32 v52, v52, v53
	ds_read2_b32 v[54:55], v70 offset0:206 offset1:239
	s_waitcnt lgkmcnt(0)
	v_cvt_pk_bf16_f32 v53, v54, v55
	v_lshl_add_u64 v[58:59], v[56:57], 0, v[4:5]
	ds_read2_b32 v[54:55], v70 offset0:16 offset1:49
	global_store_dwordx4 v[58:59], v[50:53], off
	v_or_b32_e32 v4, s98, v72
	v_lshlrev_b32_e32 v4, 11, v4
	s_waitcnt lgkmcnt(0)
	v_cvt_pk_bf16_f32 v50, v54, v55
	ds_read2_b32 v[52:53], v70 offset0:82 offset1:115
	s_waitcnt lgkmcnt(0)
	v_cvt_pk_bf16_f32 v51, v52, v53
	ds_read2_b32 v[52:53], v70 offset0:148 offset1:181
	s_waitcnt lgkmcnt(0)
	v_cvt_pk_bf16_f32 v52, v52, v53
	ds_read2_b32 v[54:55], v70 offset0:214 offset1:247
	s_waitcnt lgkmcnt(0)
	v_cvt_pk_bf16_f32 v53, v54, v55
	v_lshl_add_u64 v[58:59], v[56:57], 0, v[4:5]
	ds_read2_b32 v[54:55], v70 offset0:24 offset1:57
	global_store_dwordx4 v[58:59], v[50:53], off
	v_or_b32_e32 v4, s98, v73
	v_lshlrev_b32_e32 v4, 11, v4
	s_waitcnt lgkmcnt(0)
	v_cvt_pk_bf16_f32 v50, v54, v55
	ds_read2_b32 v[52:53], v70 offset0:90 offset1:123
	s_waitcnt lgkmcnt(0)
	v_cvt_pk_bf16_f32 v51, v52, v53
	ds_read2_b32 v[52:53], v70 offset0:156 offset1:189
	s_waitcnt lgkmcnt(0)
	v_cvt_pk_bf16_f32 v52, v52, v53
	ds_read2_b32 v[54:55], v70 offset0:222 offset1:255
	s_waitcnt lgkmcnt(0)
	v_cvt_pk_bf16_f32 v53, v54, v55
	v_lshl_add_u64 v[54:55], v[56:57], 0, v[4:5]
	global_store_dwordx4 v[54:55], v[50:53], off
	s_waitcnt lgkmcnt(0)

.LBB0_46:
	s_lshl_b32 s26, s24, 1
	s_lshl_b32 s27, s4, 1
	v_or_b32_e32 v4, s27, v52
	s_add_i32 s62, s26, 4
	s_add_i32 s63, s27, 4
	v_mov_b32_e32 v57, v5
	s_add_i32 s65, s27, 8
	v_lshlrev_b64 v[82:83], 12, v[4:5]
	v_or_b32_e32 v56, s62, v11
	v_or_b32_e32 v4, s63, v52
	v_mov_b32_e32 v55, v5
	v_or_b32_e32 v54, s26, v11
	s_add_i32 s67, s27, 12
	v_lshlrev_b64 v[56:57], 12, v[56:57]
	v_lshlrev_b64 v[84:85], 12, v[4:5]
	v_or_b32_e32 v4, s65, v52
	s_add_i32 s64, s26, 8
	s_add_i32 s66, s26, 12
	s_add_i32 s69, s27, 16
	v_lshlrev_b64 v[54:55], 12, v[54:55]
	v_lshl_add_u64 v[82:83], v[50:51], 0, v[82:83]
	v_lshl_add_u64 v[56:57], v[50:51], 0, v[56:57]
	v_lshlrev_b64 v[86:87], 12, v[4:5]
	v_or_b32_e32 v4, s67, v52
	v_mov_b32_e32 v59, v5
	v_mov_b32_e32 v61, v5
	s_add_i32 s71, s27, 20
	v_or_b32_e32 v58, s64, v11
	v_or_b32_e32 v60, s66, v11
	v_lshl_add_u64 v[54:55], v[50:51], 0, v[54:55]
	v_lshl_add_u64 v[84:85], v[50:51], 0, v[84:85]
	global_load_dword v53, v[82:83], off
	global_load_dword v98, v[54:55], off
	global_load_dword v99, v[84:85], off
	global_load_dword v100, v[56:57], off
	v_lshlrev_b64 v[56:57], 12, v[4:5]
	v_or_b32_e32 v4, s69, v52
	s_add_i32 s68, s26, 16
	s_add_i32 s70, s26, 20
	s_add_i32 s73, s27, 24
	v_lshlrev_b64 v[58:59], 12, v[58:59]
	v_lshlrev_b64 v[60:61], 12, v[60:61]
	v_lshl_add_u64 v[54:55], v[50:51], 0, v[86:87]
	v_lshl_add_u64 v[56:57], v[50:51], 0, v[56:57]
	v_lshlrev_b64 v[82:83], 12, v[4:5]
	v_or_b32_e32 v4, s71, v52
	v_mov_b32_e32 v63, v5
	v_mov_b32_e32 v65, v5
	s_add_i32 s72, s26, 24
	s_add_i32 s74, s26, 28
	s_add_i32 s75, s27, 28
	v_or_b32_e32 v62, s68, v11
	v_or_b32_e32 v64, s70, v11
	v_lshl_add_u64 v[58:59], v[50:51], 0, v[58:59]
	v_lshl_add_u64 v[60:61], v[50:51], 0, v[60:61]
	global_load_dword v101, v[54:55], off
	global_load_dword v102, v[58:59], off
	global_load_dword v103, v[56:57], off
	global_load_dword v104, v[60:61], off
	v_lshlrev_b64 v[56:57], 12, v[4:5]
	v_or_b32_e32 v4, s73, v52
	v_mov_b32_e32 v67, v5
	v_mov_b32_e32 v69, v5
	v_or_b32_e32 v66, s72, v11
	v_or_b32_e32 v68, s74, v11
	v_lshlrev_b64 v[62:63], 12, v[62:63]
	v_lshlrev_b64 v[64:65], 12, v[64:65]
	v_lshl_add_u64 v[54:55], v[50:51], 0, v[82:83]
	v_lshl_add_u64 v[56:57], v[50:51], 0, v[56:57]
	v_lshlrev_b64 v[58:59], 12, v[4:5]
	v_or_b32_e32 v4, s75, v52
	v_lshlrev_b64 v[66:67], 12, v[66:67]
	v_lshlrev_b64 v[68:69], 12, v[68:69]
	v_lshl_add_u64 v[62:63], v[50:51], 0, v[62:63]
	v_lshl_add_u64 v[64:65], v[50:51], 0, v[64:65]
	global_load_dword v105, v[54:55], off
	global_load_dword v106, v[62:63], off
	global_load_dword v107, v[56:57], off
	global_load_dword v108, v[64:65], off
	v_lshl_add_u64 v[54:55], v[50:51], 0, v[58:59]
	v_lshlrev_b64 v[56:57], 12, v[4:5]
	v_lshl_add_u64 v[66:67], v[50:51], 0, v[66:67]
	v_lshl_add_u64 v[68:69], v[50:51], 0, v[68:69]
	v_lshl_add_u64 v[56:57], v[50:51], 0, v[56:57]
	global_load_dword v4, v[54:55], off
	global_load_dword v109, v[66:67], off
	global_load_dword v110, v[56:57], off
	global_load_dword v111, v[68:69], off
	v_or_b32_e32 v56, s26, v1
	v_or_b32_e32 v54, s27, v2
	s_add_i32 s4, s4, 16
	s_add_i32 s24, s24, 16
	s_add_i32 s25, s25, -16
	v_mad_u64_u32 v[54:55], s[26:27], v54, s3, v[10:11]
	v_mad_u64_u32 v[56:57], s[26:27], v56, s3, v[10:11]
	v_or_b32_e32 v55, s62, v1
	v_or_b32_e32 v57, s63, v2
	v_or_b32_e32 v64, s64, v1
	v_or_b32_e32 v62, s65, v2
	v_or_b32_e32 v68, s66, v1
	v_or_b32_e32 v66, s67, v2
	v_or_b32_e32 v84, s68, v1
	v_or_b32_e32 v82, s69, v2
	v_or_b32_e32 v88, s70, v1
	v_or_b32_e32 v86, s71, v2
	v_or_b32_e32 v92, s72, v1
	v_or_b32_e32 v90, s73, v2
	v_or_b32_e32 v96, s74, v1
	v_or_b32_e32 v94, s75, v2
	s_cmp_lg_u32 s25, 0
	v_mad_u64_u32 v[58:59], s[26:27], v57, s3, v[10:11]
	v_mad_u64_u32 v[60:61], s[26:27], v55, s3, v[10:11]
	v_mad_u64_u32 v[62:63], s[26:27], v62, s3, v[10:11]
	v_mad_u64_u32 v[64:65], s[26:27], v64, s3, v[10:11]
	v_mad_u64_u32 v[66:67], s[26:27], v66, s3, v[10:11]
	v_mad_u64_u32 v[68:69], s[26:27], v68, s3, v[10:11]
	v_mad_u64_u32 v[82:83], s[26:27], v82, s3, v[10:11]
	v_mad_u64_u32 v[84:85], s[26:27], v84, s3, v[10:11]
	v_mad_u64_u32 v[86:87], s[26:27], v86, s3, v[10:11]
	v_mad_u64_u32 v[88:89], s[26:27], v88, s3, v[10:11]
	v_mad_u64_u32 v[90:91], s[26:27], v90, s3, v[10:11]
	v_mad_u64_u32 v[92:93], s[26:27], v92, s3, v[10:11]
	v_mad_u64_u32 v[94:95], s[26:27], v94, s3, v[10:11]
	v_mad_u64_u32 v[96:97], s[26:27], v96, s3, v[10:11]
	s_waitcnt vmcnt(15)
	ds_write_b32 v54, v53
	s_waitcnt vmcnt(14)
	ds_write_b32 v56, v98
	s_waitcnt vmcnt(13)
	ds_write_b32 v58, v99
	s_waitcnt vmcnt(12)
	ds_write_b32 v60, v100
	s_waitcnt vmcnt(11)
	ds_write_b32 v62, v101
	s_waitcnt vmcnt(10)
	ds_write_b32 v64, v102
	s_waitcnt vmcnt(9)
	ds_write_b32 v66, v103
	s_waitcnt vmcnt(8)
	ds_write_b32 v68, v104
	s_waitcnt vmcnt(7)
	ds_write_b32 v82, v105
	s_waitcnt vmcnt(6)
	ds_write_b32 v84, v106
	s_waitcnt vmcnt(5)
	ds_write_b32 v86, v107
	s_waitcnt vmcnt(4)
	ds_write_b32 v88, v108
	s_waitcnt vmcnt(3)
	ds_write_b32 v90, v4
	s_waitcnt vmcnt(2)
	ds_write_b32 v92, v109
	s_waitcnt vmcnt(1)
	ds_write_b32 v94, v110
	s_waitcnt vmcnt(0)
	ds_write_b32 v96, v111
	s_cbranch_scc1 .LBB0_46
	s_waitcnt lgkmcnt(0)
	ds_read2_b32 v[50:51], v70 offset1:33
	s_waitcnt lgkmcnt(0)
	v_cvt_pk_bf16_f32 v50, v50, v51
	ds_read2_b32 v[52:53], v70 offset0:66 offset1:99
	s_lshl_b32 s4, s1, 1
	s_bfe_u32 s98, s0, 0x10005
	s_bfe_u32 s99, s0, 0x20006
	s_lshl_b32 s98, s98, 7
	s_lshl_b32 s99, s99, 5
	s_or_b32 s98, s98, s99
	s_andn2_b32 s99, s0, 0xe0
	s_or_b32 s98, s98, s99
	v_or_b32_e32 v4, s98, v45
	s_waitcnt lgkmcnt(0)
	v_cvt_pk_bf16_f32 v51, v52, v53
	ds_read2_b32 v[52:53], v70 offset0:132 offset1:165
	v_lshl_add_u64 v[56:57], v[28:29], 0, s[4:5]
	v_lshlrev_b32_e32 v4, 13, v4
	s_waitcnt lgkmcnt(0)
	v_cvt_pk_bf16_f32 v52, v52, v53
	ds_read2_b32 v[54:55], v70 offset0:198 offset1:231
	s_waitcnt lgkmcnt(0)
	v_cvt_pk_bf16_f32 v53, v54, v55
	v_lshl_add_u64 v[58:59], v[56:57], 0, v[4:5]
	ds_read2_b32 v[54:55], v70 offset0:8 offset1:41
	global_store_dwordx4 v[58:59], v[50:53], off
	v_or_b32_e32 v4, s98, v71
	v_lshlrev_b32_e32 v4, 13, v4
	s_waitcnt lgkmcnt(0)
	v_cvt_pk_bf16_f32 v50, v54, v55
	ds_read2_b32 v[52:53], v70 offset0:74 offset1:107
	s_waitcnt lgkmcnt(0)
	v_cvt_pk_bf16_f32 v51, v52, v53
	ds_read2_b32 v[52:53], v70 offset0:140 offset1:173
	s_waitcnt lgkmcnt(0)
	v_cvt_pk_bf16_f32 v52, v52, v53
	ds_read2_b32 v[54:55], v70 offset0:206 offset1:239
	s_waitcnt lgkmcnt(0)
	v_cvt_pk_bf16_f32 v53, v54, v55
	v_lshl_add_u64 v[58:59], v[56:57], 0, v[4:5]
	ds_read2_b32 v[54:55], v70 offset0:16 offset1:49
	global_store_dwordx4 v[58:59], v[50:53], off
	v_or_b32_e32 v4, s98, v72
	v_lshlrev_b32_e32 v4, 13, v4
	s_waitcnt lgkmcnt(0)
	v_cvt_pk_bf16_f32 v50, v54, v55
	ds_read2_b32 v[52:53], v70 offset0:82 offset1:115
	s_waitcnt lgkmcnt(0)
	v_cvt_pk_bf16_f32 v51, v52, v53
	ds_read2_b32 v[52:53], v70 offset0:148 offset1:181
	s_waitcnt lgkmcnt(0)
	v_cvt_pk_bf16_f32 v52, v52, v53
	ds_read2_b32 v[54:55], v70 offset0:214 offset1:247
	s_waitcnt lgkmcnt(0)
	v_cvt_pk_bf16_f32 v53, v54, v55
	v_lshl_add_u64 v[58:59], v[56:57], 0, v[4:5]
	ds_read2_b32 v[54:55], v70 offset0:24 offset1:57
	global_store_dwordx4 v[58:59], v[50:53], off
	v_or_b32_e32 v4, s98, v73
	v_lshlrev_b32_e32 v4, 13, v4
	s_waitcnt lgkmcnt(0)
	v_cvt_pk_bf16_f32 v50, v54, v55
	ds_read2_b32 v[52:53], v70 offset0:90 offset1:123
	s_waitcnt lgkmcnt(0)
	v_cvt_pk_bf16_f32 v51, v52, v53
	ds_read2_b32 v[52:53], v70 offset0:156 offset1:189
	s_waitcnt lgkmcnt(0)
	v_cvt_pk_bf16_f32 v52, v52, v53
	ds_read2_b32 v[54:55], v70 offset0:222 offset1:255
	s_waitcnt lgkmcnt(0)
	v_cvt_pk_bf16_f32 v53, v54, v55
	v_lshl_add_u64 v[54:55], v[56:57], 0, v[4:5]
	global_store_dwordx4 v[54:55], v[50:53], off
	s_waitcnt lgkmcnt(0)

.LBB0_72:
	s_lshl_b32 s26, s24, 1
	s_lshl_b32 s27, s4, 1
	v_or_b32_e32 v4, s27, v52
	s_add_i32 s62, s26, 4
	s_add_i32 s63, s27, 4
	v_mov_b32_e32 v57, v5
	s_add_i32 s65, s27, 8
	v_lshlrev_b64 v[82:83], 12, v[4:5]
	v_or_b32_e32 v56, s62, v11
	v_or_b32_e32 v4, s63, v52
	v_mov_b32_e32 v55, v5
	v_or_b32_e32 v54, s26, v11
	s_add_i32 s67, s27, 12
	v_lshlrev_b64 v[56:57], 12, v[56:57]
	v_lshlrev_b64 v[84:85], 12, v[4:5]
	v_or_b32_e32 v4, s65, v52
	s_add_i32 s64, s26, 8
	s_add_i32 s66, s26, 12
	s_add_i32 s69, s27, 16
	v_lshlrev_b64 v[54:55], 12, v[54:55]
	v_lshl_add_u64 v[82:83], v[50:51], 0, v[82:83]
	v_lshl_add_u64 v[56:57], v[50:51], 0, v[56:57]
	v_lshlrev_b64 v[86:87], 12, v[4:5]
	v_or_b32_e32 v4, s67, v52
	v_mov_b32_e32 v59, v5
	v_mov_b32_e32 v61, v5
	s_add_i32 s71, s27, 20
	v_or_b32_e32 v58, s64, v11
	v_or_b32_e32 v60, s66, v11
	v_lshl_add_u64 v[54:55], v[50:51], 0, v[54:55]
	v_lshl_add_u64 v[84:85], v[50:51], 0, v[84:85]
	global_load_dword v53, v[82:83], off
	global_load_dword v98, v[54:55], off
	global_load_dword v99, v[84:85], off
	global_load_dword v100, v[56:57], off
	v_lshlrev_b64 v[56:57], 12, v[4:5]
	v_or_b32_e32 v4, s69, v52
	s_add_i32 s68, s26, 16
	s_add_i32 s70, s26, 20
	s_add_i32 s73, s27, 24
	v_lshlrev_b64 v[58:59], 12, v[58:59]
	v_lshlrev_b64 v[60:61], 12, v[60:61]
	v_lshl_add_u64 v[54:55], v[50:51], 0, v[86:87]
	v_lshl_add_u64 v[56:57], v[50:51], 0, v[56:57]
	v_lshlrev_b64 v[82:83], 12, v[4:5]
	v_or_b32_e32 v4, s71, v52
	v_mov_b32_e32 v63, v5
	v_mov_b32_e32 v65, v5
	s_add_i32 s72, s26, 24
	s_add_i32 s74, s26, 28
	s_add_i32 s75, s27, 28
	v_or_b32_e32 v62, s68, v11
	v_or_b32_e32 v64, s70, v11
	v_lshl_add_u64 v[58:59], v[50:51], 0, v[58:59]
	v_lshl_add_u64 v[60:61], v[50:51], 0, v[60:61]
	global_load_dword v101, v[54:55], off
	global_load_dword v102, v[58:59], off
	global_load_dword v103, v[56:57], off
	global_load_dword v104, v[60:61], off
	v_lshlrev_b64 v[56:57], 12, v[4:5]
	v_or_b32_e32 v4, s73, v52
	v_mov_b32_e32 v67, v5
	v_mov_b32_e32 v69, v5
	v_or_b32_e32 v66, s72, v11
	v_or_b32_e32 v68, s74, v11
	v_lshlrev_b64 v[62:63], 12, v[62:63]
	v_lshlrev_b64 v[64:65], 12, v[64:65]
	v_lshl_add_u64 v[54:55], v[50:51], 0, v[82:83]
	v_lshl_add_u64 v[56:57], v[50:51], 0, v[56:57]
	v_lshlrev_b64 v[58:59], 12, v[4:5]
	v_or_b32_e32 v4, s75, v52
	v_lshlrev_b64 v[66:67], 12, v[66:67]
	v_lshlrev_b64 v[68:69], 12, v[68:69]
	v_lshl_add_u64 v[62:63], v[50:51], 0, v[62:63]
	v_lshl_add_u64 v[64:65], v[50:51], 0, v[64:65]
	global_load_dword v105, v[54:55], off
	global_load_dword v106, v[62:63], off
	global_load_dword v107, v[56:57], off
	global_load_dword v108, v[64:65], off
	v_lshl_add_u64 v[54:55], v[50:51], 0, v[58:59]
	v_lshlrev_b64 v[56:57], 12, v[4:5]
	v_lshl_add_u64 v[66:67], v[50:51], 0, v[66:67]
	v_lshl_add_u64 v[68:69], v[50:51], 0, v[68:69]
	v_lshl_add_u64 v[56:57], v[50:51], 0, v[56:57]
	global_load_dword v4, v[54:55], off
	global_load_dword v109, v[66:67], off
	global_load_dword v110, v[56:57], off
	global_load_dword v111, v[68:69], off
	v_or_b32_e32 v56, s26, v1
	v_or_b32_e32 v54, s27, v2
	s_add_i32 s4, s4, 16
	s_add_i32 s24, s24, 16
	s_add_i32 s25, s25, -16
	v_mad_u64_u32 v[54:55], s[26:27], v54, s3, v[10:11]
	v_mad_u64_u32 v[56:57], s[26:27], v56, s3, v[10:11]
	v_or_b32_e32 v55, s62, v1
	v_or_b32_e32 v57, s63, v2
	v_or_b32_e32 v64, s64, v1
	v_or_b32_e32 v62, s65, v2
	v_or_b32_e32 v68, s66, v1
	v_or_b32_e32 v66, s67, v2
	v_or_b32_e32 v84, s68, v1
	v_or_b32_e32 v82, s69, v2
	v_or_b32_e32 v88, s70, v1
	v_or_b32_e32 v86, s71, v2
	v_or_b32_e32 v92, s72, v1
	v_or_b32_e32 v90, s73, v2
	v_or_b32_e32 v96, s74, v1
	v_or_b32_e32 v94, s75, v2
	s_cmp_lg_u32 s25, 0
	v_mad_u64_u32 v[58:59], s[26:27], v57, s3, v[10:11]
	v_mad_u64_u32 v[60:61], s[26:27], v55, s3, v[10:11]
	v_mad_u64_u32 v[62:63], s[26:27], v62, s3, v[10:11]
	v_mad_u64_u32 v[64:65], s[26:27], v64, s3, v[10:11]
	v_mad_u64_u32 v[66:67], s[26:27], v66, s3, v[10:11]
	v_mad_u64_u32 v[68:69], s[26:27], v68, s3, v[10:11]
	v_mad_u64_u32 v[82:83], s[26:27], v82, s3, v[10:11]
	v_mad_u64_u32 v[84:85], s[26:27], v84, s3, v[10:11]
	v_mad_u64_u32 v[86:87], s[26:27], v86, s3, v[10:11]
	v_mad_u64_u32 v[88:89], s[26:27], v88, s3, v[10:11]
	v_mad_u64_u32 v[90:91], s[26:27], v90, s3, v[10:11]
	v_mad_u64_u32 v[92:93], s[26:27], v92, s3, v[10:11]
	v_mad_u64_u32 v[94:95], s[26:27], v94, s3, v[10:11]
	v_mad_u64_u32 v[96:97], s[26:27], v96, s3, v[10:11]
	s_waitcnt vmcnt(15)
	ds_write_b32 v54, v53
	s_waitcnt vmcnt(14)
	ds_write_b32 v56, v98
	s_waitcnt vmcnt(13)
	ds_write_b32 v58, v99
	s_waitcnt vmcnt(12)
	ds_write_b32 v60, v100
	s_waitcnt vmcnt(11)
	ds_write_b32 v62, v101
	s_waitcnt vmcnt(10)
	ds_write_b32 v64, v102
	s_waitcnt vmcnt(9)
	ds_write_b32 v66, v103
	s_waitcnt vmcnt(8)
	ds_write_b32 v68, v104
	s_waitcnt vmcnt(7)
	ds_write_b32 v82, v105
	s_waitcnt vmcnt(6)
	ds_write_b32 v84, v106
	s_waitcnt vmcnt(5)
	ds_write_b32 v86, v107
	s_waitcnt vmcnt(4)
	ds_write_b32 v88, v108
	s_waitcnt vmcnt(3)
	ds_write_b32 v90, v4
	s_waitcnt vmcnt(2)
	ds_write_b32 v92, v109
	s_waitcnt vmcnt(1)
	ds_write_b32 v94, v110
	s_waitcnt vmcnt(0)
	ds_write_b32 v96, v111
	s_cbranch_scc1 .LBB0_72
	s_waitcnt lgkmcnt(0)
	ds_read2_b32 v[50:51], v70 offset1:33
	s_waitcnt lgkmcnt(0)
	v_cvt_pk_bf16_f32 v50, v50, v51
	ds_read2_b32 v[52:53], v70 offset0:66 offset1:99
	s_lshl_b32 s4, s1, 1
	s_bfe_u32 s98, s0, 0x10005
	s_bfe_u32 s99, s0, 0x20006
	s_lshl_b32 s98, s98, 7
	s_lshl_b32 s99, s99, 5
	s_or_b32 s98, s98, s99
	s_andn2_b32 s99, s0, 0xe0
	s_or_b32 s98, s98, s99
	v_or_b32_e32 v4, s98, v45
	s_waitcnt lgkmcnt(0)
	v_cvt_pk_bf16_f32 v51, v52, v53
	ds_read2_b32 v[52:53], v70 offset0:132 offset1:165
	v_lshl_add_u64 v[56:57], v[34:35], 0, s[4:5]
	v_lshlrev_b32_e32 v4, 11, v4
	s_waitcnt lgkmcnt(0)
	v_cvt_pk_bf16_f32 v52, v52, v53
	ds_read2_b32 v[54:55], v70 offset0:198 offset1:231
	s_waitcnt lgkmcnt(0)
	v_cvt_pk_bf16_f32 v53, v54, v55
	v_lshl_add_u64 v[58:59], v[56:57], 0, v[4:5]
	ds_read2_b32 v[54:55], v70 offset0:8 offset1:41
	global_store_dwordx4 v[58:59], v[50:53], off
	v_or_b32_e32 v4, s98, v71
	v_lshlrev_b32_e32 v4, 11, v4
	s_waitcnt lgkmcnt(0)
	v_cvt_pk_bf16_f32 v50, v54, v55
	ds_read2_b32 v[52:53], v70 offset0:74 offset1:107
	s_waitcnt lgkmcnt(0)
	v_cvt_pk_bf16_f32 v51, v52, v53
	ds_read2_b32 v[52:53], v70 offset0:140 offset1:173
	s_waitcnt lgkmcnt(0)
	v_cvt_pk_bf16_f32 v52, v52, v53
	ds_read2_b32 v[54:55], v70 offset0:206 offset1:239
	s_waitcnt lgkmcnt(0)
	v_cvt_pk_bf16_f32 v53, v54, v55
	v_lshl_add_u64 v[58:59], v[56:57], 0, v[4:5]
	ds_read2_b32 v[54:55], v70 offset0:16 offset1:49
	global_store_dwordx4 v[58:59], v[50:53], off
	v_or_b32_e32 v4, s98, v72
	v_lshlrev_b32_e32 v4, 11, v4
	s_waitcnt lgkmcnt(0)
	v_cvt_pk_bf16_f32 v50, v54, v55
	ds_read2_b32 v[52:53], v70 offset0:82 offset1:115
	s_waitcnt lgkmcnt(0)
	v_cvt_pk_bf16_f32 v51, v52, v53
	ds_read2_b32 v[52:53], v70 offset0:148 offset1:181
	s_waitcnt lgkmcnt(0)
	v_cvt_pk_bf16_f32 v52, v52, v53
	ds_read2_b32 v[54:55], v70 offset0:214 offset1:247
	s_waitcnt lgkmcnt(0)
	v_cvt_pk_bf16_f32 v53, v54, v55
	v_lshl_add_u64 v[58:59], v[56:57], 0, v[4:5]
	ds_read2_b32 v[54:55], v70 offset0:24 offset1:57
	global_store_dwordx4 v[58:59], v[50:53], off
	v_or_b32_e32 v4, s98, v73
	v_lshlrev_b32_e32 v4, 11, v4
	s_waitcnt lgkmcnt(0)
	v_cvt_pk_bf16_f32 v50, v54, v55
	ds_read2_b32 v[52:53], v70 offset0:90 offset1:123
	s_waitcnt lgkmcnt(0)
	v_cvt_pk_bf16_f32 v51, v52, v53
	ds_read2_b32 v[52:53], v70 offset0:156 offset1:189
	s_waitcnt lgkmcnt(0)
	v_cvt_pk_bf16_f32 v52, v52, v53
	ds_read2_b32 v[54:55], v70 offset0:222 offset1:255
	s_waitcnt lgkmcnt(0)
	v_cvt_pk_bf16_f32 v53, v54, v55
	v_lshl_add_u64 v[54:55], v[56:57], 0, v[4:5]
	global_store_dwordx4 v[54:55], v[50:53], off
	s_waitcnt lgkmcnt(0)

.LBB0_174:
	s_add_i32 s71, s71, 1
	s_cmp_gt_u32 s71, 1
	s_cselect_b32 s101, 1, 0
	s_mul_i32 s6, s71, s24
	s_mul_hi_u32 s7, s71, s25
	s_add_i32 s7, s7, s6
	s_mul_i32 s6, s71, s25
	s_add_u32 s20, s6, s2
	s_addc_u32 s21, s7, s73
	v_mov_b64_e32 v[0:1], 0x300
	v_cmp_lt_i64_e64 s[6:7], s[20:21], v[0:1]
	v_mov_b64_e32 v[0:1], 0x2ff
	v_cmp_gt_i64_e32 vcc, s[20:21], v[0:1]
	s_cbranch_vccnz .LBB0_176
	s_mul_i32 s30, s21, 0xaaaaaaab
	s_mul_hi_u32 s34, s20, 0xaaaaaaab
	s_mul_hi_u32 s19, s21, 0xaaaaaaab
	s_add_u32 s30, s30, s34
	s_mul_i32 s18, s20, 0x2aaaaaaa
	s_addc_u32 s19, s19, 0
	s_mul_hi_u32 s9, s20, 0x2aaaaaaa
	s_add_u32 s18, s18, s30
	s_addc_u32 s9, s9, 0
	s_add_u32 s9, s19, s9
	s_addc_u32 s18, 0, 0
	s_mul_i32 s30, s21, 0x2aaaaaaa
	s_mul_hi_u32 s19, s21, 0x2aaaaaaa
	s_add_u32 s9, s30, s9
	s_addc_u32 s19, s19, s18
	s_ashr_i32 s18, s21, 31
	s_mul_i32 s21, s18, 0x2aaaaaaa
	s_mul_hi_u32 s30, s18, 0xaaaaaaab
	s_add_i32 s21, s30, s21
	s_mul_i32 s18, s18, 0xaaaaaaab
	s_add_i32 s21, s21, s18
	s_add_u32 s18, s9, s18
	s_addc_u32 s19, s19, s21
	s_ashr_i64 s[34:35], s[18:19], 7
	s_lshr_b32 s9, s19, 31
	s_add_u32 s9, s34, s9
	s_mulk_i32 s9, 0x300
	s_sub_i32 s9, s20, s9
	s_sext_i32_i16 s18, s9
	s_bfe_u32 s18, s18, 0x3001c
	s_add_i32 s18, s9, s18
	s_sext_i32_i16 s19, s18
	s_and_b32 s18, s18, 0xfff8
	s_sub_i32 s9, s9, s18
	s_ashr_i32 s19, s19, 3
	s_sext_i32_i16 s18, s9
	s_cmp_lt_i32 s18, 0
	s_movk_i32 s18, 0x61
	s_cselect_b32 s18, s18, 0x60
	s_mul_i32 s9, s9, s18
	s_add_i32 s9, s9, s19
	s_sext_i32_i16 s18, s9
	s_mulk_i32 s18, 0x2aab
	s_lshr_b32 s19, s18, 31
	s_ashr_i32 s18, s18, 19
	s_add_i32 s18, s18, s19
	s_lshl_b32 s19, s18, 3
	s_mul_i32 s18, s18, 48
	s_sub_i32 s9, s9, s18
	s_bfe_i32 s18, s9, 0x80000
	s_bfe_u32 s18, s18, 0x3000c
	s_add_i32 s18, s9, s18
	s_bfe_i32 s20, s18, 0x80000
	s_and_b32 s18, s18, 0xf8
	s_sub_i32 s9, s9, s18
	s_sext_i32_i16 s20, s20
	s_sext_i32_i8 s9, s9
	s_add_i32 s90, s19, s9
	s_ashr_i32 s18, s20, 3

.LBB0_177:
	s_cmp_eq_u32 s75, -2
	s_cselect_b32 s100, s101, 0
	v_add_u32_e32 v144, s65, v191
	ds_read_b128 v[128:131], v144
	ds_read_b128 v[132:135], v144 offset:1024
	ds_read_b128 v[176:179], v144 offset:2048
	ds_read_b128 v[180:183], v144 offset:3072
	v_add_u32_e32 v144, s40, v191
	ds_read_b128 v[184:187], v144
	ds_read_b128 v[194:197], v144 offset:1024
	ds_read_b128 v[208:211], v144 offset:2048
	ds_read_b128 v[212:215], v144 offset:3072
	s_add_u32 s14, s10, 0xfffc0080
	s_addc_u32 s15, s11, -1
	s_cmp_eq_u32 s75, 12
	s_cselect_b32 s21, s9, s15
	s_cselect_b32 s20, s30, s14
	s_cselect_b32 s15, s19, s74
	s_cselect_b32 s14, s34, s35
	v_lshl_add_u64 v[188:189], s[10:11], 0, v[172:173]
	s_add_i32 m0, s67, 0xc000
	ds_read_b128 v[216:219], v203
	ds_read_b128 v[220:223], v203 offset:1024
	ds_read_b128 v[224:227], v203 offset:2048
	ds_read_b128 v[228:231], v203 offset:3072
	ds_read_b128 v[232:235], v203 offset:4096
	ds_read_b128 v[236:239], v203 offset:5120
	ds_read_b128 v[240:243], v203 offset:6144
	ds_read_b128 v[244:247], v203 offset:7168
	global_load_lds_dwordx4 v[188:189], off
	v_lshl_add_u64 v[188:189], s[10:11], 0, v[174:175]
	s_add_i32 m0, s67, 0xe000
	s_nop 0
	global_load_lds_dwordx4 v[188:189], off
	s_cmp_lg_u32 s100, 0
	s_cbranch_scc1 .Lrw_g0_0
	s_waitcnt vmcnt(8)
.Lrw_g0_0:
	s_waitcnt lgkmcnt(0)
	s_barrier
	s_setprio 1
	s_waitcnt lgkmcnt(0)
	v_mfma_f32_16x16x32_bf16 v[124:127], v[128:131], v[216:219], v[124:127]
	v_mfma_f32_16x16x32_bf16 v[120:123], v[176:179], v[216:219], v[120:123]
	v_mfma_f32_16x16x32_bf16 v[108:111], v[128:131], v[224:227], v[108:111]
	v_mfma_f32_16x16x32_bf16 v[104:107], v[176:179], v[224:227], v[104:107]
	v_mfma_f32_16x16x32_bf16 v[92:95], v[128:131], v[232:235], v[92:95]
	v_mfma_f32_16x16x32_bf16 v[88:91], v[176:179], v[232:235], v[88:91]
	v_mfma_f32_16x16x32_bf16 v[76:79], v[128:131], v[240:243], v[76:79]
	v_mfma_f32_16x16x32_bf16 v[72:75], v[176:179], v[240:243], v[72:75]
	v_mfma_f32_16x16x32_bf16 v[124:127], v[132:135], v[220:223], v[124:127]
	v_mfma_f32_16x16x32_bf16 v[120:123], v[180:183], v[220:223], v[120:123]
	v_mfma_f32_16x16x32_bf16 v[108:111], v[132:135], v[228:231], v[108:111]
	v_mfma_f32_16x16x32_bf16 v[104:107], v[180:183], v[228:231], v[104:107]
	v_mfma_f32_16x16x32_bf16 v[92:95], v[132:135], v[236:239], v[92:95]
	v_mfma_f32_16x16x32_bf16 v[88:91], v[180:183], v[236:239], v[88:91]
	v_mfma_f32_16x16x32_bf16 v[76:79], v[132:135], v[244:247], v[76:79]
	v_mfma_f32_16x16x32_bf16 v[72:75], v[180:183], v[244:247], v[72:75]
	s_setprio 0
	s_setprio 1
	v_mfma_f32_16x16x32_bf16 v[116:119], v[184:187], v[216:219], v[116:119]
	v_mfma_f32_16x16x32_bf16 v[112:115], v[208:211], v[216:219], v[112:115]
	v_mfma_f32_16x16x32_bf16 v[100:103], v[184:187], v[224:227], v[100:103]
	v_mfma_f32_16x16x32_bf16 v[96:99], v[208:211], v[224:227], v[96:99]
	v_mfma_f32_16x16x32_bf16 v[84:87], v[184:187], v[232:235], v[84:87]
	v_mfma_f32_16x16x32_bf16 v[80:83], v[208:211], v[232:235], v[80:83]
	v_mfma_f32_16x16x32_bf16 v[68:71], v[184:187], v[240:243], v[68:71]
	v_mfma_f32_16x16x32_bf16 v[64:67], v[208:211], v[240:243], v[64:67]
	v_mfma_f32_16x16x32_bf16 v[116:119], v[194:197], v[220:223], v[116:119]
	v_mfma_f32_16x16x32_bf16 v[112:115], v[212:215], v[220:223], v[112:115]
	v_mfma_f32_16x16x32_bf16 v[100:103], v[194:197], v[228:231], v[100:103]
	v_mfma_f32_16x16x32_bf16 v[96:99], v[212:215], v[228:231], v[96:99]
	v_mfma_f32_16x16x32_bf16 v[84:87], v[194:197], v[236:239], v[84:87]
	v_mfma_f32_16x16x32_bf16 v[80:83], v[212:215], v[236:239], v[80:83]
	v_mfma_f32_16x16x32_bf16 v[68:71], v[194:197], v[244:247], v[68:71]
	v_mfma_f32_16x16x32_bf16 v[64:67], v[212:215], v[244:247], v[64:67]
	s_setprio 0
	s_barrier
	s_add_i32 s91, s65, s66
	v_lshl_add_u64 v[188:189], s[14:15], 0, v[138:139]
	s_mov_b32 m0, s91
	ds_read_b128 v[216:219], v203 offset:16384
	ds_read_b128 v[220:223], v203 offset:17408
	ds_read_b128 v[224:227], v203 offset:18432
	ds_read_b128 v[228:231], v203 offset:19456
	ds_read_b128 v[232:235], v203 offset:20480
	ds_read_b128 v[236:239], v203 offset:21504
	ds_read_b128 v[240:243], v203 offset:22528
	ds_read_b128 v[244:247], v203 offset:23552
	global_load_lds_dwordx4 v[188:189], off
	s_add_i32 m0, s91, 0x2000
	s_add_u32 vcc_lo, s14, 0x40000
	v_lshl_add_u64 v[198:199], s[14:15], 0, v[142:143]
	s_addc_u32 vcc_hi, s15, 0
	s_add_i32 s91, s40, s66
	global_load_lds_dwordx4 v[198:199], off
	v_lshl_add_u64 v[248:249], vcc, 0, v[138:139]
	s_mov_b32 m0, s91
	v_lshl_add_u64 v[250:251], s[20:21], 0, v[140:141]
	global_load_lds_dwordx4 v[248:249], off
	v_lshl_add_u64 v[248:249], vcc, 0, v[142:143]
	s_add_i32 m0, s91, 0x2000
	s_nop 0
	global_load_lds_dwordx4 v[248:249], off
	v_lshl_add_u64 v[248:249], s[20:21], 0, v[136:137]
	s_mov_b32 m0, s67
	s_nop 0
	global_load_lds_dwordx4 v[248:249], off
	s_mov_b32 m0, s68
	s_nop 0
	global_load_lds_dwordx4 v[250:251], off
	s_cmp_lg_u32 s100, 0
	s_cbranch_scc1 .Lrw_g0_1
	s_waitcnt vmcnt(8)
.Lrw_g0_1:
	s_waitcnt lgkmcnt(0)
	s_barrier
	s_setprio 1
	s_waitcnt lgkmcnt(0)
	v_mfma_f32_16x16x32_bf16 v[60:63], v[128:131], v[216:219], v[60:63]
	v_mfma_f32_16x16x32_bf16 v[56:59], v[176:179], v[216:219], v[56:59]
	v_mfma_f32_16x16x32_bf16 v[44:47], v[128:131], v[224:227], v[44:47]
	v_mfma_f32_16x16x32_bf16 v[40:43], v[176:179], v[224:227], v[40:43]
	v_mfma_f32_16x16x32_bf16 v[28:31], v[128:131], v[232:235], v[28:31]
	v_mfma_f32_16x16x32_bf16 v[24:27], v[176:179], v[232:235], v[24:27]
	v_mfma_f32_16x16x32_bf16 v[12:15], v[128:131], v[240:243], v[12:15]
	v_mfma_f32_16x16x32_bf16 v[8:11], v[176:179], v[240:243], v[8:11]
	v_mfma_f32_16x16x32_bf16 v[60:63], v[132:135], v[220:223], v[60:63]
	v_mfma_f32_16x16x32_bf16 v[56:59], v[180:183], v[220:223], v[56:59]
	v_mfma_f32_16x16x32_bf16 v[44:47], v[132:135], v[228:231], v[44:47]
	v_mfma_f32_16x16x32_bf16 v[40:43], v[180:183], v[228:231], v[40:43]
	v_mfma_f32_16x16x32_bf16 v[28:31], v[132:135], v[236:239], v[28:31]
	v_mfma_f32_16x16x32_bf16 v[24:27], v[180:183], v[236:239], v[24:27]
	v_mfma_f32_16x16x32_bf16 v[12:15], v[132:135], v[244:247], v[12:15]
	v_mfma_f32_16x16x32_bf16 v[8:11], v[180:183], v[244:247], v[8:11]
	s_setprio 0
	s_setprio 1
	v_mfma_f32_16x16x32_bf16 v[52:55], v[184:187], v[216:219], v[52:55]
	v_mfma_f32_16x16x32_bf16 v[48:51], v[208:211], v[216:219], v[48:51]
	v_mfma_f32_16x16x32_bf16 v[36:39], v[184:187], v[224:227], v[36:39]
	v_mfma_f32_16x16x32_bf16 v[32:35], v[208:211], v[224:227], v[32:35]
	v_mfma_f32_16x16x32_bf16 v[20:23], v[184:187], v[232:235], v[20:23]
	v_mfma_f32_16x16x32_bf16 v[16:19], v[208:211], v[232:235], v[16:19]
	v_mfma_f32_16x16x32_bf16 v[4:7], v[184:187], v[240:243], v[4:7]
	v_mfma_f32_16x16x32_bf16 v[0:3], v[208:211], v[240:243], v[0:3]
	v_mfma_f32_16x16x32_bf16 v[52:55], v[194:197], v[220:223], v[52:55]
	v_mfma_f32_16x16x32_bf16 v[48:51], v[212:215], v[220:223], v[48:51]
	v_mfma_f32_16x16x32_bf16 v[36:39], v[194:197], v[228:231], v[36:39]
	v_mfma_f32_16x16x32_bf16 v[32:35], v[212:215], v[228:231], v[32:35]
	v_mfma_f32_16x16x32_bf16 v[20:23], v[194:197], v[236:239], v[20:23]
	v_mfma_f32_16x16x32_bf16 v[16:19], v[212:215], v[236:239], v[16:19]
	v_mfma_f32_16x16x32_bf16 v[4:7], v[194:197], v[244:247], v[4:7]
	v_mfma_f32_16x16x32_bf16 v[0:3], v[212:215], v[244:247], v[0:3]
	s_setprio 0
	s_barrier
	s_add_i32 s91, 0, 0x18000
	v_add_u32_e32 v144, s91, v191
	s_add_i32 vcc_lo, 0, 0x1c000
	ds_read_b128 v[128:131], v144
	ds_read_b128 v[132:135], v144 offset:1024
	ds_read_b128 v[176:179], v144 offset:2048
	ds_read_b128 v[180:183], v144 offset:3072
	v_add_u32_e32 v144, vcc_lo, v191
	ds_read_b128 v[184:187], v144
	ds_read_b128 v[194:197], v144 offset:1024
	ds_read_b128 v[208:211], v144 offset:2048
	ds_read_b128 v[212:215], v144 offset:3072
	s_add_u32 s20, s20, 0x40000
	s_addc_u32 s21, s21, 0
	s_mov_b32 m0, s69
	v_lshl_add_u64 v[252:253], s[20:21], 0, v[136:137]
	ds_read_b128 v[216:219], v203 offset:32768
	ds_read_b128 v[220:223], v203 offset:33792
	ds_read_b128 v[224:227], v203 offset:34816
	ds_read_b128 v[228:231], v203 offset:35840
	ds_read_b128 v[232:235], v203 offset:36864
	ds_read_b128 v[236:239], v203 offset:37888
	ds_read_b128 v[240:243], v203 offset:38912
	ds_read_b128 v[244:247], v203 offset:39936
	global_load_lds_dwordx4 v[252:253], off
	v_lshl_add_u64 v[252:253], s[20:21], 0, v[140:141]
	s_mov_b32 m0, s70
	s_nop 0
	global_load_lds_dwordx4 v[252:253], off
	s_waitcnt vmcnt(8)
	s_waitcnt lgkmcnt(0)
	s_barrier
	s_setprio 1
	s_waitcnt lgkmcnt(0)
	v_mfma_f32_16x16x32_bf16 v[124:127], v[128:131], v[216:219], v[124:127]
	v_mfma_f32_16x16x32_bf16 v[120:123], v[176:179], v[216:219], v[120:123]
	v_mfma_f32_16x16x32_bf16 v[108:111], v[128:131], v[224:227], v[108:111]
	v_mfma_f32_16x16x32_bf16 v[104:107], v[176:179], v[224:227], v[104:107]
	v_mfma_f32_16x16x32_bf16 v[92:95], v[128:131], v[232:235], v[92:95]
	v_mfma_f32_16x16x32_bf16 v[88:91], v[176:179], v[232:235], v[88:91]
	v_mfma_f32_16x16x32_bf16 v[76:79], v[128:131], v[240:243], v[76:79]
	v_mfma_f32_16x16x32_bf16 v[72:75], v[176:179], v[240:243], v[72:75]
	v_mfma_f32_16x16x32_bf16 v[124:127], v[132:135], v[220:223], v[124:127]
	v_mfma_f32_16x16x32_bf16 v[120:123], v[180:183], v[220:223], v[120:123]
	v_mfma_f32_16x16x32_bf16 v[108:111], v[132:135], v[228:231], v[108:111]
	v_mfma_f32_16x16x32_bf16 v[104:107], v[180:183], v[228:231], v[104:107]
	v_mfma_f32_16x16x32_bf16 v[92:95], v[132:135], v[236:239], v[92:95]
	v_mfma_f32_16x16x32_bf16 v[88:91], v[180:183], v[236:239], v[88:91]
	v_mfma_f32_16x16x32_bf16 v[76:79], v[132:135], v[244:247], v[76:79]
	v_mfma_f32_16x16x32_bf16 v[72:75], v[180:183], v[244:247], v[72:75]
	s_setprio 0
	s_setprio 1
	v_mfma_f32_16x16x32_bf16 v[116:119], v[184:187], v[216:219], v[116:119]
	v_mfma_f32_16x16x32_bf16 v[112:115], v[208:211], v[216:219], v[112:115]
	v_mfma_f32_16x16x32_bf16 v[100:103], v[184:187], v[224:227], v[100:103]
	v_mfma_f32_16x16x32_bf16 v[96:99], v[208:211], v[224:227], v[96:99]
	v_mfma_f32_16x16x32_bf16 v[84:87], v[184:187], v[232:235], v[84:87]
	v_mfma_f32_16x16x32_bf16 v[80:83], v[208:211], v[232:235], v[80:83]
	v_mfma_f32_16x16x32_bf16 v[68:71], v[184:187], v[240:243], v[68:71]
	v_mfma_f32_16x16x32_bf16 v[64:67], v[208:211], v[240:243], v[64:67]
	v_mfma_f32_16x16x32_bf16 v[116:119], v[194:197], v[220:223], v[116:119]
	v_mfma_f32_16x16x32_bf16 v[112:115], v[212:215], v[220:223], v[112:115]
	v_mfma_f32_16x16x32_bf16 v[100:103], v[194:197], v[228:231], v[100:103]
	v_mfma_f32_16x16x32_bf16 v[96:99], v[212:215], v[228:231], v[96:99]
	v_mfma_f32_16x16x32_bf16 v[84:87], v[194:197], v[236:239], v[84:87]
	v_mfma_f32_16x16x32_bf16 v[80:83], v[212:215], v[236:239], v[80:83]
	v_mfma_f32_16x16x32_bf16 v[68:71], v[194:197], v[244:247], v[68:71]
	v_mfma_f32_16x16x32_bf16 v[64:67], v[212:215], v[244:247], v[64:67]
	s_setprio 0
	s_barrier
	s_add_i32 s20, s91, s66
	v_lshl_add_u64 v[188:189], v[188:189], 0, s[48:49]
	s_mov_b32 m0, s20
	ds_read_b128 v[216:219], v203 offset:49152
	ds_read_b128 v[220:223], v203 offset:50176
	ds_read_b128 v[224:227], v203 offset:51200
	ds_read_b128 v[228:231], v203 offset:52224
	ds_read_b128 v[232:235], v203 offset:53248
	ds_read_b128 v[236:239], v203 offset:54272
	ds_read_b128 v[240:243], v203 offset:55296
	ds_read_b128 v[244:247], v203 offset:56320
	global_load_lds_dwordx4 v[188:189], off
	s_add_i32 m0, s20, 0x2000
	s_add_u32 s14, s14, 0x40080
	v_lshl_add_u64 v[188:189], v[198:199], 0, s[48:49]
	s_addc_u32 s15, s15, 0
	s_add_i32 s20, vcc_lo, s66
	global_load_lds_dwordx4 v[188:189], off
	v_lshl_add_u64 v[188:189], s[14:15], 0, v[138:139]
	s_mov_b32 m0, s20
	s_nop 0
	global_load_lds_dwordx4 v[188:189], off
	v_lshl_add_u64 v[188:189], s[14:15], 0, v[142:143]
	s_add_i32 m0, s20, 0x2000
	s_nop 0
	global_load_lds_dwordx4 v[188:189], off
	v_lshl_add_u64 v[188:189], v[248:249], 0, s[48:49]
	s_mov_b32 m0, s93
	s_nop 0
	global_load_lds_dwordx4 v[188:189], off
	v_lshl_add_u64 v[188:189], v[250:251], 0, s[48:49]
	s_mov_b32 m0, s22
	s_nop 0
	global_load_lds_dwordx4 v[188:189], off
	s_waitcnt vmcnt(8)
	s_waitcnt lgkmcnt(0)
	s_barrier
	s_setprio 1
	s_waitcnt lgkmcnt(0)
	v_mfma_f32_16x16x32_bf16 v[60:63], v[128:131], v[216:219], v[60:63]
	v_mfma_f32_16x16x32_bf16 v[56:59], v[176:179], v[216:219], v[56:59]
	v_mfma_f32_16x16x32_bf16 v[44:47], v[128:131], v[224:227], v[44:47]
	v_mfma_f32_16x16x32_bf16 v[40:43], v[176:179], v[224:227], v[40:43]
	v_mfma_f32_16x16x32_bf16 v[28:31], v[128:131], v[232:235], v[28:31]
	v_mfma_f32_16x16x32_bf16 v[24:27], v[176:179], v[232:235], v[24:27]
	v_mfma_f32_16x16x32_bf16 v[12:15], v[128:131], v[240:243], v[12:15]
	v_mfma_f32_16x16x32_bf16 v[8:11], v[176:179], v[240:243], v[8:11]
	v_mfma_f32_16x16x32_bf16 v[60:63], v[132:135], v[220:223], v[60:63]
	v_mfma_f32_16x16x32_bf16 v[56:59], v[180:183], v[220:223], v[56:59]
	v_mfma_f32_16x16x32_bf16 v[44:47], v[132:135], v[228:231], v[44:47]
	v_mfma_f32_16x16x32_bf16 v[40:43], v[180:183], v[228:231], v[40:43]
	v_mfma_f32_16x16x32_bf16 v[28:31], v[132:135], v[236:239], v[28:31]
	v_mfma_f32_16x16x32_bf16 v[24:27], v[180:183], v[236:239], v[24:27]
	v_mfma_f32_16x16x32_bf16 v[12:15], v[132:135], v[244:247], v[12:15]
	v_mfma_f32_16x16x32_bf16 v[8:11], v[180:183], v[244:247], v[8:11]
	s_setprio 0
	s_setprio 1
	v_mfma_f32_16x16x32_bf16 v[52:55], v[184:187], v[216:219], v[52:55]
	v_mfma_f32_16x16x32_bf16 v[48:51], v[208:211], v[216:219], v[48:51]
	v_mfma_f32_16x16x32_bf16 v[36:39], v[184:187], v[224:227], v[36:39]
	v_mfma_f32_16x16x32_bf16 v[32:35], v[208:211], v[224:227], v[32:35]
	v_mfma_f32_16x16x32_bf16 v[20:23], v[184:187], v[232:235], v[20:23]
	v_mfma_f32_16x16x32_bf16 v[16:19], v[208:211], v[232:235], v[16:19]
	v_mfma_f32_16x16x32_bf16 v[4:7], v[184:187], v[240:243], v[4:7]
	v_mfma_f32_16x16x32_bf16 v[0:3], v[208:211], v[240:243], v[0:3]
	v_mfma_f32_16x16x32_bf16 v[52:55], v[194:197], v[220:223], v[52:55]
	v_mfma_f32_16x16x32_bf16 v[48:51], v[212:215], v[220:223], v[48:51]
	v_mfma_f32_16x16x32_bf16 v[36:39], v[194:197], v[228:231], v[36:39]
	v_mfma_f32_16x16x32_bf16 v[32:35], v[212:215], v[228:231], v[32:35]
	v_mfma_f32_16x16x32_bf16 v[20:23], v[194:197], v[236:239], v[20:23]
	v_mfma_f32_16x16x32_bf16 v[16:19], v[212:215], v[236:239], v[16:19]
	v_mfma_f32_16x16x32_bf16 v[4:7], v[194:197], v[244:247], v[4:7]
	v_mfma_f32_16x16x32_bf16 v[0:3], v[212:215], v[244:247], v[0:3]
	s_setprio 0
	s_barrier
	s_add_i32 s75, s75, 2
	s_add_u32 s10, s10, 0x100
	s_addc_u32 s11, s11, 0
	s_add_u32 s35, s35, 0x100
	s_addc_u32 s74, s74, 0
	s_cmp_gt_u32 s75, 13
	s_cbranch_scc0 .LBB0_177
	s_and_b64 vcc, exec, s[50:51]
	s_cbranch_vccz .LBB0_180
	s_barrier

.LBB0_425:
	s_add_i32 s39, s39, 1
	s_cmp_gt_u32 s39, 1
	s_cselect_b32 s101, 1, 0
	s_mul_i32 s0, s39, s42
	s_mul_hi_u32 s1, s39, s43
	s_add_i32 s1, s1, s0
	s_mul_i32 s0, s39, s43
	s_add_u32 s0, s0, s2
	s_addc_u32 s1, s1, s30
	v_cmp_gt_i64_e32 vcc, s[0:1], v[146:147]
	v_cmp_lt_i64_e64 s[4:5], s[0:1], v[144:145]
	s_cbranch_vccnz .LBB0_427
	s_mul_i32 s23, s1, 0xaaaaaaab
	s_mul_hi_u32 s48, s0, 0xaaaaaaab
	s_mul_hi_u32 s22, s1, 0xaaaaaaab
	s_add_u32 s23, s23, s48
	s_mul_i32 s21, s0, 0x2aaaaaaa
	s_addc_u32 s22, s22, 0
	s_mul_hi_u32 s20, s0, 0x2aaaaaaa
	s_add_u32 s21, s21, s23
	s_addc_u32 s20, s20, 0
	s_add_u32 s20, s22, s20
	s_addc_u32 s21, 0, 0
	s_mul_i32 s23, s1, 0x2aaaaaaa
	s_mul_hi_u32 s22, s1, 0x2aaaaaaa
	s_add_u32 s20, s23, s20
	s_addc_u32 s21, s22, s21
	s_ashr_i32 s1, s1, 31
	s_mul_i32 s22, s1, 0x2aaaaaaa
	s_mul_hi_u32 s23, s1, 0xaaaaaaab
	s_add_i32 s22, s23, s22
	s_mul_i32 s1, s1, 0xaaaaaaab
	s_add_i32 s22, s22, s1
	s_add_u32 s20, s20, s1
	s_addc_u32 s21, s21, s22
	s_ashr_i64 s[22:23], s[20:21], 6
	s_lshr_b32 s1, s21, 31
	s_add_u32 s1, s22, s1
	s_mulk_i32 s1, 0x180
	s_sub_i32 s0, s0, s1
	s_sext_i32_i16 s1, s0
	s_bfe_u32 s1, s1, 0x3001c
	s_add_i32 s1, s0, s1
	s_sext_i32_i16 s20, s1
	s_and_b32 s1, s1, 0xfff8
	s_sub_i32 s0, s0, s1
	s_ashr_i32 s20, s20, 3
	s_sext_i32_i16 s1, s0
	s_cmp_lt_i32 s1, 0
	s_cselect_b32 s1, 49, 48
	s_mul_i32 s0, s0, s1
	s_add_i32 s0, s0, s20
	s_sext_i32_i16 s1, s0
	s_mulk_i32 s1, 0x2aab
	s_lshr_b32 s20, s1, 31
	s_ashr_i32 s1, s1, 18
	s_add_i32 s1, s1, s20
	s_lshl_b32 s20, s1, 3
	s_mul_i32 s1, s1, 24
	s_sub_i32 s0, s0, s1
	s_bfe_i32 s1, s0, 0x80000
	s_bfe_u32 s1, s1, 0x3000c
	s_add_i32 s1, s0, s1
	s_bfe_i32 s21, s1, 0x80000
	s_and_b32 s1, s1, 0xf8
	s_sub_i32 s0, s0, s1
	s_sext_i32_i16 s21, s21
	s_sext_i32_i8 s0, s0
	s_add_i32 s49, s20, s0
	s_ashr_i32 s48, s21, 3

.LBB0_432:
	s_cmp_eq_u32 s66, -2
	s_cselect_b32 s100, s101, 0
	ds_read_b128 v[148:151], v164
	ds_read_b128 v[170:173], v164 offset:1024
	ds_read_b128 v[174:177], v164 offset:2048
	ds_read_b128 v[178:181], v164 offset:3072
	ds_read_b128 v[182:185], v165
	ds_read_b128 v[186:189], v165 offset:1024
	ds_read_b128 v[194:197], v165 offset:2048
	ds_read_b128 v[198:201], v165 offset:3072
	s_add_u32 s24, s4, 0xfffe8080
	s_addc_u32 s25, s5, -1
	s_cmp_eq_u32 s66, 2
	s_cselect_b32 s27, s21, s25
	s_cselect_b32 s26, s20, s24
	s_cselect_b32 s25, s23, s65
	s_cselect_b32 s24, s22, s64
	v_lshl_add_u64 v[152:153], s[4:5], 0, v[140:141]
	s_add_i32 m0, s35, 0xc000
	ds_read_b128 v[202:205], v166
	ds_read_b128 v[206:209], v166 offset:1024
	ds_read_b128 v[210:213], v166 offset:2048
	ds_read_b128 v[214:217], v166 offset:3072
	ds_read_b128 v[218:221], v166 offset:4096
	ds_read_b128 v[222:225], v166 offset:5120
	ds_read_b128 v[226:229], v166 offset:6144
	ds_read_b128 v[230:233], v166 offset:7168
	global_load_lds_dwordx4 v[152:153], off
	v_lshl_add_u64 v[152:153], s[4:5], 0, v[142:143]
	s_add_i32 m0, s35, 0xe000
	s_nop 0
	global_load_lds_dwordx4 v[152:153], off
	s_cmp_lg_u32 s100, 0
	s_cbranch_scc1 .Lrw_g1_0
	s_waitcnt vmcnt(8)
.Lrw_g1_0:
	s_waitcnt lgkmcnt(0)
	s_barrier
	s_setprio 1
	s_waitcnt lgkmcnt(0)
	v_mfma_f32_16x16x32_bf16 v[124:127], v[148:151], v[202:205], v[124:127]
	v_mfma_f32_16x16x32_bf16 v[120:123], v[174:177], v[202:205], v[120:123]
	v_mfma_f32_16x16x32_bf16 v[108:111], v[148:151], v[210:213], v[108:111]
	v_mfma_f32_16x16x32_bf16 v[104:107], v[174:177], v[210:213], v[104:107]
	v_mfma_f32_16x16x32_bf16 v[92:95], v[148:151], v[218:221], v[92:95]
	v_mfma_f32_16x16x32_bf16 v[88:91], v[174:177], v[218:221], v[88:91]
	v_mfma_f32_16x16x32_bf16 v[76:79], v[148:151], v[226:229], v[76:79]
	v_mfma_f32_16x16x32_bf16 v[72:75], v[174:177], v[226:229], v[72:75]
	v_mfma_f32_16x16x32_bf16 v[124:127], v[170:173], v[206:209], v[124:127]
	v_mfma_f32_16x16x32_bf16 v[120:123], v[178:181], v[206:209], v[120:123]
	v_mfma_f32_16x16x32_bf16 v[108:111], v[170:173], v[214:217], v[108:111]
	v_mfma_f32_16x16x32_bf16 v[104:107], v[178:181], v[214:217], v[104:107]
	v_mfma_f32_16x16x32_bf16 v[92:95], v[170:173], v[222:225], v[92:95]
	v_mfma_f32_16x16x32_bf16 v[88:91], v[178:181], v[222:225], v[88:91]
	v_mfma_f32_16x16x32_bf16 v[76:79], v[170:173], v[230:233], v[76:79]
	v_mfma_f32_16x16x32_bf16 v[72:75], v[178:181], v[230:233], v[72:75]
	s_setprio 0
	s_setprio 1
	v_mfma_f32_16x16x32_bf16 v[116:119], v[182:185], v[202:205], v[116:119]
	v_mfma_f32_16x16x32_bf16 v[112:115], v[194:197], v[202:205], v[112:115]
	v_mfma_f32_16x16x32_bf16 v[100:103], v[182:185], v[210:213], v[100:103]
	v_mfma_f32_16x16x32_bf16 v[96:99], v[194:197], v[210:213], v[96:99]
	v_mfma_f32_16x16x32_bf16 v[84:87], v[182:185], v[218:221], v[84:87]
	v_mfma_f32_16x16x32_bf16 v[80:83], v[194:197], v[218:221], v[80:83]
	v_mfma_f32_16x16x32_bf16 v[68:71], v[182:185], v[226:229], v[68:71]
	v_mfma_f32_16x16x32_bf16 v[64:67], v[194:197], v[226:229], v[64:67]
	v_mfma_f32_16x16x32_bf16 v[116:119], v[186:189], v[206:209], v[116:119]
	v_mfma_f32_16x16x32_bf16 v[112:115], v[198:201], v[206:209], v[112:115]
	v_mfma_f32_16x16x32_bf16 v[100:103], v[186:189], v[214:217], v[100:103]
	v_mfma_f32_16x16x32_bf16 v[96:99], v[198:201], v[214:217], v[96:99]
	v_mfma_f32_16x16x32_bf16 v[84:87], v[186:189], v[222:225], v[84:87]
	v_mfma_f32_16x16x32_bf16 v[80:83], v[198:201], v[222:225], v[80:83]
	v_mfma_f32_16x16x32_bf16 v[68:71], v[186:189], v[230:233], v[68:71]
	v_mfma_f32_16x16x32_bf16 v[64:67], v[198:201], v[230:233], v[64:67]
	s_setprio 0
	s_barrier
	s_add_i32 s67, s44, s34
	v_lshl_add_u64 v[152:153], s[24:25], 0, v[134:135]
	s_mov_b32 m0, s67
	ds_read_b128 v[202:205], v166 offset:16384
	ds_read_b128 v[206:209], v166 offset:17408
	ds_read_b128 v[210:213], v166 offset:18432
	ds_read_b128 v[214:217], v166 offset:19456
	ds_read_b128 v[218:221], v166 offset:20480
	ds_read_b128 v[222:225], v166 offset:21504
	ds_read_b128 v[226:229], v166 offset:22528
	ds_read_b128 v[230:233], v166 offset:23552
	global_load_lds_dwordx4 v[152:153], off
	s_add_i32 m0, s67, 0x2000
	s_add_u32 s68, s24, 0x18000
	v_lshl_add_u64 v[234:235], s[24:25], 0, v[130:131]
	s_addc_u32 s69, s25, 0
	s_add_i32 s67, s45, s34
	global_load_lds_dwordx4 v[234:235], off
	v_lshl_add_u64 v[236:237], s[68:69], 0, v[134:135]
	s_mov_b32 m0, s67
	v_lshl_add_u64 v[238:239], s[26:27], 0, v[132:133]
	global_load_lds_dwordx4 v[236:237], off
	v_lshl_add_u64 v[236:237], s[68:69], 0, v[130:131]
	s_add_i32 m0, s67, 0x2000
	s_nop 0
	global_load_lds_dwordx4 v[236:237], off
	v_lshl_add_u64 v[236:237], s[26:27], 0, v[136:137]
	s_mov_b32 m0, s35
	s_nop 0
	global_load_lds_dwordx4 v[236:237], off
	s_mov_b32 m0, s36
	s_nop 0
	global_load_lds_dwordx4 v[238:239], off
	s_cmp_lg_u32 s100, 0
	s_cbranch_scc1 .Lrw_g1_1
	s_waitcnt vmcnt(8)
.Lrw_g1_1:
	s_waitcnt lgkmcnt(0)
	s_barrier
	s_setprio 1
	s_waitcnt lgkmcnt(0)
	v_mfma_f32_16x16x32_bf16 v[60:63], v[148:151], v[202:205], v[60:63]
	v_mfma_f32_16x16x32_bf16 v[56:59], v[174:177], v[202:205], v[56:59]
	v_mfma_f32_16x16x32_bf16 v[44:47], v[148:151], v[210:213], v[44:47]
	v_mfma_f32_16x16x32_bf16 v[40:43], v[174:177], v[210:213], v[40:43]
	v_mfma_f32_16x16x32_bf16 v[28:31], v[148:151], v[218:221], v[28:31]
	v_mfma_f32_16x16x32_bf16 v[24:27], v[174:177], v[218:221], v[24:27]
	v_mfma_f32_16x16x32_bf16 v[12:15], v[148:151], v[226:229], v[12:15]
	v_mfma_f32_16x16x32_bf16 v[8:11], v[174:177], v[226:229], v[8:11]
	v_mfma_f32_16x16x32_bf16 v[60:63], v[170:173], v[206:209], v[60:63]
	v_mfma_f32_16x16x32_bf16 v[56:59], v[178:181], v[206:209], v[56:59]
	v_mfma_f32_16x16x32_bf16 v[44:47], v[170:173], v[214:217], v[44:47]
	v_mfma_f32_16x16x32_bf16 v[40:43], v[178:181], v[214:217], v[40:43]
	v_mfma_f32_16x16x32_bf16 v[28:31], v[170:173], v[222:225], v[28:31]
	v_mfma_f32_16x16x32_bf16 v[24:27], v[178:181], v[222:225], v[24:27]
	v_mfma_f32_16x16x32_bf16 v[12:15], v[170:173], v[230:233], v[12:15]
	v_mfma_f32_16x16x32_bf16 v[8:11], v[178:181], v[230:233], v[8:11]
	s_setprio 0
	s_setprio 1
	v_mfma_f32_16x16x32_bf16 v[52:55], v[182:185], v[202:205], v[52:55]
	v_mfma_f32_16x16x32_bf16 v[48:51], v[194:197], v[202:205], v[48:51]
	v_mfma_f32_16x16x32_bf16 v[36:39], v[182:185], v[210:213], v[36:39]
	v_mfma_f32_16x16x32_bf16 v[32:35], v[194:197], v[210:213], v[32:35]
	v_mfma_f32_16x16x32_bf16 v[20:23], v[182:185], v[218:221], v[20:23]
	v_mfma_f32_16x16x32_bf16 v[16:19], v[194:197], v[218:221], v[16:19]
	v_mfma_f32_16x16x32_bf16 v[4:7], v[182:185], v[226:229], v[4:7]
	v_mfma_f32_16x16x32_bf16 v[0:3], v[194:197], v[226:229], v[0:3]
	v_mfma_f32_16x16x32_bf16 v[52:55], v[186:189], v[206:209], v[52:55]
	v_mfma_f32_16x16x32_bf16 v[48:51], v[198:201], v[206:209], v[48:51]
	v_mfma_f32_16x16x32_bf16 v[36:39], v[186:189], v[214:217], v[36:39]
	v_mfma_f32_16x16x32_bf16 v[32:35], v[198:201], v[214:217], v[32:35]
	v_mfma_f32_16x16x32_bf16 v[20:23], v[186:189], v[222:225], v[20:23]
	v_mfma_f32_16x16x32_bf16 v[16:19], v[198:201], v[222:225], v[16:19]
	v_mfma_f32_16x16x32_bf16 v[4:7], v[186:189], v[230:233], v[4:7]
	v_mfma_f32_16x16x32_bf16 v[0:3], v[198:201], v[230:233], v[0:3]
	s_setprio 0
	s_barrier
	s_add_i32 s67, 0, 0x18000
	s_add_i32 s68, 0, 0x1c000
	v_add_u32_e32 v178, s67, v163
	v_add_u32_e32 v191, s68, v163
	ds_read_b128 v[148:151], v178
	ds_read_b128 v[170:173], v178 offset:1024
	ds_read_b128 v[174:177], v178 offset:2048
	ds_read_b128 v[178:181], v178 offset:3072
	ds_read_b128 v[182:185], v191
	ds_read_b128 v[186:189], v191 offset:1024
	ds_read_b128 v[194:197], v191 offset:2048
	ds_read_b128 v[198:201], v191 offset:3072
	s_add_u32 s26, s26, 0x18000
	s_addc_u32 s27, s27, 0
	s_mov_b32 m0, s37
	v_lshl_add_u64 v[240:241], s[26:27], 0, v[136:137]
	ds_read_b128 v[202:205], v166 offset:32768
	ds_read_b128 v[206:209], v166 offset:33792
	ds_read_b128 v[210:213], v166 offset:34816
	ds_read_b128 v[214:217], v166 offset:35840
	ds_read_b128 v[218:221], v166 offset:36864
	ds_read_b128 v[222:225], v166 offset:37888
	ds_read_b128 v[226:229], v166 offset:38912
	ds_read_b128 v[230:233], v166 offset:39936
	global_load_lds_dwordx4 v[240:241], off
	v_lshl_add_u64 v[240:241], s[26:27], 0, v[132:133]
	s_mov_b32 m0, s38
	s_nop 0
	global_load_lds_dwordx4 v[240:241], off
	s_waitcnt vmcnt(8)
	s_waitcnt lgkmcnt(0)
	s_barrier
	s_setprio 1
	s_waitcnt lgkmcnt(0)
	v_mfma_f32_16x16x32_bf16 v[124:127], v[148:151], v[202:205], v[124:127]
	v_mfma_f32_16x16x32_bf16 v[120:123], v[174:177], v[202:205], v[120:123]
	v_mfma_f32_16x16x32_bf16 v[108:111], v[148:151], v[210:213], v[108:111]
	v_mfma_f32_16x16x32_bf16 v[104:107], v[174:177], v[210:213], v[104:107]
	v_mfma_f32_16x16x32_bf16 v[92:95], v[148:151], v[218:221], v[92:95]
	v_mfma_f32_16x16x32_bf16 v[88:91], v[174:177], v[218:221], v[88:91]
	v_mfma_f32_16x16x32_bf16 v[76:79], v[148:151], v[226:229], v[76:79]
	v_mfma_f32_16x16x32_bf16 v[72:75], v[174:177], v[226:229], v[72:75]
	v_mfma_f32_16x16x32_bf16 v[124:127], v[170:173], v[206:209], v[124:127]
	v_mfma_f32_16x16x32_bf16 v[120:123], v[178:181], v[206:209], v[120:123]
	v_mfma_f32_16x16x32_bf16 v[108:111], v[170:173], v[214:217], v[108:111]
	v_mfma_f32_16x16x32_bf16 v[104:107], v[178:181], v[214:217], v[104:107]
	v_mfma_f32_16x16x32_bf16 v[92:95], v[170:173], v[222:225], v[92:95]
	v_mfma_f32_16x16x32_bf16 v[88:91], v[178:181], v[222:225], v[88:91]
	v_mfma_f32_16x16x32_bf16 v[76:79], v[170:173], v[230:233], v[76:79]
	v_mfma_f32_16x16x32_bf16 v[72:75], v[178:181], v[230:233], v[72:75]
	s_setprio 0
	s_setprio 1
	v_mfma_f32_16x16x32_bf16 v[116:119], v[182:185], v[202:205], v[116:119]
	v_mfma_f32_16x16x32_bf16 v[112:115], v[194:197], v[202:205], v[112:115]
	v_mfma_f32_16x16x32_bf16 v[100:103], v[182:185], v[210:213], v[100:103]
	v_mfma_f32_16x16x32_bf16 v[96:99], v[194:197], v[210:213], v[96:99]
	v_mfma_f32_16x16x32_bf16 v[84:87], v[182:185], v[218:221], v[84:87]
	v_mfma_f32_16x16x32_bf16 v[80:83], v[194:197], v[218:221], v[80:83]
	v_mfma_f32_16x16x32_bf16 v[68:71], v[182:185], v[226:229], v[68:71]
	v_mfma_f32_16x16x32_bf16 v[64:67], v[194:197], v[226:229], v[64:67]
	v_mfma_f32_16x16x32_bf16 v[116:119], v[186:189], v[206:209], v[116:119]
	v_mfma_f32_16x16x32_bf16 v[112:115], v[198:201], v[206:209], v[112:115]
	v_mfma_f32_16x16x32_bf16 v[100:103], v[186:189], v[214:217], v[100:103]
	v_mfma_f32_16x16x32_bf16 v[96:99], v[198:201], v[214:217], v[96:99]
	v_mfma_f32_16x16x32_bf16 v[84:87], v[186:189], v[222:225], v[84:87]
	v_mfma_f32_16x16x32_bf16 v[80:83], v[198:201], v[222:225], v[80:83]
	v_mfma_f32_16x16x32_bf16 v[68:71], v[186:189], v[230:233], v[68:71]
	v_mfma_f32_16x16x32_bf16 v[64:67], v[198:201], v[230:233], v[64:67]
	s_setprio 0
	s_barrier
	s_add_i32 s26, s67, s34
	v_lshl_add_u64 v[152:153], v[152:153], 0, s[14:15]
	s_mov_b32 m0, s26
	ds_read_b128 v[202:205], v166 offset:49152
	ds_read_b128 v[206:209], v166 offset:50176
	ds_read_b128 v[210:213], v166 offset:51200
	ds_read_b128 v[214:217], v166 offset:52224
	ds_read_b128 v[218:221], v166 offset:53248
	ds_read_b128 v[222:225], v166 offset:54272
	ds_read_b128 v[226:229], v166 offset:55296
	ds_read_b128 v[230:233], v166 offset:56320
	global_load_lds_dwordx4 v[152:153], off
	s_add_i32 m0, s26, 0x2000
	s_add_u32 s24, s24, 0x18080
	v_lshl_add_u64 v[152:153], v[234:235], 0, s[14:15]
	s_addc_u32 s25, s25, 0
	s_add_i32 s26, s68, s34
	global_load_lds_dwordx4 v[152:153], off
	v_lshl_add_u64 v[152:153], s[24:25], 0, v[134:135]
	s_mov_b32 m0, s26
	s_nop 0
	global_load_lds_dwordx4 v[152:153], off
	v_lshl_add_u64 v[152:153], s[24:25], 0, v[130:131]
	s_add_i32 m0, s26, 0x2000
	s_nop 0
	global_load_lds_dwordx4 v[152:153], off
	v_lshl_add_u64 v[152:153], v[236:237], 0, s[14:15]
	s_mov_b32 m0, s40
	s_nop 0
	global_load_lds_dwordx4 v[152:153], off
	v_lshl_add_u64 v[152:153], v[238:239], 0, s[14:15]
	s_mov_b32 m0, s41
	s_nop 0
	global_load_lds_dwordx4 v[152:153], off
	s_waitcnt vmcnt(8)
	s_waitcnt lgkmcnt(0)
	s_barrier
	s_setprio 1
	s_waitcnt lgkmcnt(0)
	v_mfma_f32_16x16x32_bf16 v[60:63], v[148:151], v[202:205], v[60:63]
	v_mfma_f32_16x16x32_bf16 v[56:59], v[174:177], v[202:205], v[56:59]
	v_mfma_f32_16x16x32_bf16 v[44:47], v[148:151], v[210:213], v[44:47]
	v_mfma_f32_16x16x32_bf16 v[40:43], v[174:177], v[210:213], v[40:43]
	v_mfma_f32_16x16x32_bf16 v[28:31], v[148:151], v[218:221], v[28:31]
	v_mfma_f32_16x16x32_bf16 v[24:27], v[174:177], v[218:221], v[24:27]
	v_mfma_f32_16x16x32_bf16 v[12:15], v[148:151], v[226:229], v[12:15]
	v_mfma_f32_16x16x32_bf16 v[8:11], v[174:177], v[226:229], v[8:11]
	v_mfma_f32_16x16x32_bf16 v[60:63], v[170:173], v[206:209], v[60:63]
	v_mfma_f32_16x16x32_bf16 v[56:59], v[178:181], v[206:209], v[56:59]
	v_mfma_f32_16x16x32_bf16 v[44:47], v[170:173], v[214:217], v[44:47]
	v_mfma_f32_16x16x32_bf16 v[40:43], v[178:181], v[214:217], v[40:43]
	v_mfma_f32_16x16x32_bf16 v[28:31], v[170:173], v[222:225], v[28:31]
	v_mfma_f32_16x16x32_bf16 v[24:27], v[178:181], v[222:225], v[24:27]
	v_mfma_f32_16x16x32_bf16 v[12:15], v[170:173], v[230:233], v[12:15]
	v_mfma_f32_16x16x32_bf16 v[8:11], v[178:181], v[230:233], v[8:11]
	s_setprio 0
	s_setprio 1
	v_mfma_f32_16x16x32_bf16 v[52:55], v[182:185], v[202:205], v[52:55]
	v_mfma_f32_16x16x32_bf16 v[48:51], v[194:197], v[202:205], v[48:51]
	v_mfma_f32_16x16x32_bf16 v[36:39], v[182:185], v[210:213], v[36:39]
	v_mfma_f32_16x16x32_bf16 v[32:35], v[194:197], v[210:213], v[32:35]
	v_mfma_f32_16x16x32_bf16 v[20:23], v[182:185], v[218:221], v[20:23]
	v_mfma_f32_16x16x32_bf16 v[16:19], v[194:197], v[218:221], v[16:19]
	v_mfma_f32_16x16x32_bf16 v[4:7], v[182:185], v[226:229], v[4:7]
	v_mfma_f32_16x16x32_bf16 v[0:3], v[194:197], v[226:229], v[0:3]
	v_mfma_f32_16x16x32_bf16 v[52:55], v[186:189], v[206:209], v[52:55]
	v_mfma_f32_16x16x32_bf16 v[48:51], v[198:201], v[206:209], v[48:51]
	v_mfma_f32_16x16x32_bf16 v[36:39], v[186:189], v[214:217], v[36:39]
	v_mfma_f32_16x16x32_bf16 v[32:35], v[198:201], v[214:217], v[32:35]
	v_mfma_f32_16x16x32_bf16 v[20:23], v[186:189], v[222:225], v[20:23]
	v_mfma_f32_16x16x32_bf16 v[16:19], v[198:201], v[222:225], v[16:19]
	v_mfma_f32_16x16x32_bf16 v[4:7], v[186:189], v[230:233], v[4:7]
	v_mfma_f32_16x16x32_bf16 v[0:3], v[198:201], v[230:233], v[0:3]
	s_setprio 0
	s_barrier
	s_add_i32 s66, s66, 2
	s_add_u32 s4, s4, 0x100
	s_addc_u32 s5, s5, 0
	s_add_u32 s64, s64, 0x100
	s_addc_u32 s65, s65, 0
	s_cmp_gt_u32 s66, 3
	s_cbranch_scc0 .LBB0_432
	s_and_b64 vcc, exec, s[18:19]
	s_cbranch_vccz .LBB0_435
	s_barrier

.LBB0_675:
	s_add_u32 s14, s56, 0x400000
	s_mov_b64 s[18:19], 0x80
	s_addc_u32 s15, s57, 0
	s_and_b32 s44, s1, 3
	s_add_i32 m0, s29, 0x18000
	v_lshl_add_u64 v[6:7], v[6:7], 0, s[18:19]
	s_lshl_b32 s1, s0, 13
	s_lshl_b32 s21, s44, 12
	s_ashr_i32 s45, s2, 31
	s_waitcnt vmcnt(2)
	s_barrier
	global_load_lds_dwordx4 v[6:7], off
	v_lshl_add_u64 v[4:5], v[4:5], 0, s[18:19]
	s_add_i32 m0, s29, 0x1a000
	s_add_i32 s46, s29, 0x8000
	s_add_i32 s47, s29, 0xa000
	global_load_lds_dwordx4 v[4:5], off
	v_lshl_add_u64 v[0:1], v[0:1], 0, s[18:19]
	s_mov_b32 m0, s46
	s_add_u32 s4, s40, 0x40080
	global_load_lds_dwordx4 v[0:1], off
	v_lshl_add_u64 v[0:1], v[2:3], 0, s[18:19]
	s_mov_b32 m0, s47
	s_addc_u32 s5, s41, 0
	global_load_lds_dwordx4 v[0:1], off
	s_add_i32 m0, s29, 0x1c000
	v_lshl_add_u64 v[0:1], s[4:5], 0, v[130:131]
	global_load_lds_dwordx4 v[0:1], off
	v_lshl_add_u64 v[0:1], s[4:5], 0, v[134:135]
	s_add_i32 m0, s29, 0x1e000
	v_lshlrev_b32_e32 v4, 2, v192
	global_load_lds_dwordx4 v[0:1], off
	v_bfe_u32 v0, v192, 4, 2
	v_and_b32_e32 v1, 15, v192
	v_lshlrev_b32_e32 v3, 4, v0
	v_lshl_or_b32 v148, s0, 6, v1
	v_lshl_or_b32 v1, v1, 6, v3
	v_and_b32_e32 v4, 32, v4
	v_lshlrev_b32_e32 v5, 6, v192
	s_movk_i32 s0, 0x3c0
	v_lshlrev_b32_e32 v2, 3, v0
	v_bitop3_b32 v1, v1, s1, v4 bitop3:0xde
	v_and_or_b32 v3, v5, s0, v3
	v_cmp_eq_u32_e64 s[0:1], 0, v0
	v_lshlrev_b32_e32 v0, 8, v192
	v_lshl_or_b32 v150, s44, 6, v2
	v_and_b32_e32 v0, 0x38000, v0
	v_lshlrev_b32_e32 v2, 11, v10
	v_or3_b32 v0, v8, v0, v2
	v_add_u32_e32 v136, v0, v9
	v_lshlrev_b32_e32 v0, 4, v11
	v_and_b32_e32 v0, 0x78000, v0
	s_waitcnt vmcnt(6)
	s_cmpk_lt_u32 s20, 0x100
	v_or3_b32 v0, v8, v0, v2
	v_bitop3_b32 v149, s21, v3, v4 bitop3:0xf6
	s_cselect_b64 s[20:21], -1, 0
	v_add_u32_e32 v138, v0, v9
	s_add_i32 s50, 0, 0x10000
	s_add_i32 s51, 0, 0x14000
	v_mbcnt_lo_u32_b32 v0, -1, 0
	s_ashr_i32 s48, s60, 31
	s_mov_b32 s49, s60
	v_mov_b32_e32 v137, v131
	v_mov_b32_e32 v139, v131
	v_mov_b64_e32 v[140:141], 0x200
	v_mov_b64_e32 v[142:143], 0x1ff
	v_add_u32_e32 v151, s50, v149
	v_add_u32_e32 v152, s51, v149
	v_add_u32_e32 v153, 0, v1
	v_mbcnt_hi_u32_b32 v154, -1, v0
	s_mov_b32 s62, 0
	s_barrier
	s_branch .LBB0_678

.LBB0_678:
	s_add_i32 s62, s62, 1
	s_cmp_gt_u32 s62, 1
	s_cselect_b32 s101, 1, 0
	s_mul_i32 s4, s62, s48
	s_mul_hi_u32 s5, s62, s49
	s_add_i32 s5, s5, s4
	s_mul_i32 s4, s62, s49
	s_add_u32 s26, s4, s2
	s_addc_u32 s27, s5, s45
	v_cmp_gt_i64_e32 vcc, s[26:27], v[142:143]
	v_cmp_lt_i64_e64 s[4:5], s[26:27], v[140:141]
	s_cbranch_vccnz .LBB0_684
	s_ashr_i32 s22, s27, 31
	s_lshr_b32 s22, s22, 23
	s_add_i32 s22, s26, s22
	s_and_b32 s22, s22, 0xfe00
	s_sub_i32 s22, s26, s22
	s_sext_i32_i16 s23, s22
	s_bfe_u32 s23, s23, 0x3001c
	s_add_i32 s24, s22, s23
	s_and_b32 s23, s24, 0xfff8
	s_sub_i32 s26, s22, s23
	s_sext_i32_i16 s22, s26
	s_cmp_gt_i32 s22, -1
	s_mov_b64 s[22:23], -1
	s_cbranch_scc0 .LBB0_681
	s_lshl_b32 s25, s26, 6
	s_mov_b64 s[22:23], 0

.LBB0_685:
	s_cmp_eq_u32 s66, -2
	s_cselect_b32 s100, s101, 0
	ds_read_b128 v[144:147], v151
	ds_read_b128 v[156:159], v151 offset:1024
	ds_read_b128 v[160:163], v151 offset:2048
	ds_read_b128 v[164:167], v151 offset:3072
	ds_read_b128 v[168:171], v152
	ds_read_b128 v[172:175], v152 offset:1024
	ds_read_b128 v[176:179], v152 offset:2048
	ds_read_b128 v[180:183], v152 offset:3072
	s_add_u32 s40, s38, 0xfffc0080
	s_addc_u32 s41, s39, -1
	s_cmp_eq_u32 s66, 12
	s_cselect_b32 s43, s23, s41
	s_cselect_b32 s42, s37, s40
	s_cselect_b32 s41, s25, s65
	s_cselect_b32 s40, s63, s64
	v_lshl_add_u64 v[188:189], s[38:39], 0, v[136:137]
	s_add_i32 m0, s29, 0xc000
	ds_read_b128 v[184:187], v153
	ds_read_b128 v[194:197], v153 offset:1024
	ds_read_b128 v[206:209], v153 offset:2048
	ds_read_b128 v[210:213], v153 offset:3072
	ds_read_b128 v[214:217], v153 offset:4096
	ds_read_b128 v[218:221], v153 offset:5120
	ds_read_b128 v[222:225], v153 offset:6144
	ds_read_b128 v[226:229], v153 offset:7168
	global_load_lds_dwordx4 v[188:189], off
	v_lshl_add_u64 v[188:189], s[38:39], 0, v[138:139]
	s_add_i32 m0, s29, 0xe000
	s_nop 0
	global_load_lds_dwordx4 v[188:189], off
	s_cmp_lg_u32 s100, 0
	s_cbranch_scc1 .Lrw_g2_0
	s_waitcnt vmcnt(8)
.Lrw_g2_0:
	s_waitcnt lgkmcnt(0)
	s_barrier
	s_setprio 1
	s_waitcnt lgkmcnt(0)
	v_mfma_f32_16x16x32_bf16 v[124:127], v[144:147], v[184:187], v[124:127]
	v_mfma_f32_16x16x32_bf16 v[120:123], v[160:163], v[184:187], v[120:123]
	v_mfma_f32_16x16x32_bf16 v[108:111], v[144:147], v[206:209], v[108:111]
	v_mfma_f32_16x16x32_bf16 v[104:107], v[160:163], v[206:209], v[104:107]
	v_mfma_f32_16x16x32_bf16 v[92:95], v[144:147], v[214:217], v[92:95]
	v_mfma_f32_16x16x32_bf16 v[88:91], v[160:163], v[214:217], v[88:91]
	v_mfma_f32_16x16x32_bf16 v[76:79], v[144:147], v[222:225], v[76:79]
	v_mfma_f32_16x16x32_bf16 v[72:75], v[160:163], v[222:225], v[72:75]
	v_mfma_f32_16x16x32_bf16 v[124:127], v[156:159], v[194:197], v[124:127]
	v_mfma_f32_16x16x32_bf16 v[120:123], v[164:167], v[194:197], v[120:123]
	v_mfma_f32_16x16x32_bf16 v[108:111], v[156:159], v[210:213], v[108:111]
	v_mfma_f32_16x16x32_bf16 v[104:107], v[164:167], v[210:213], v[104:107]
	v_mfma_f32_16x16x32_bf16 v[92:95], v[156:159], v[218:221], v[92:95]
	v_mfma_f32_16x16x32_bf16 v[88:91], v[164:167], v[218:221], v[88:91]
	v_mfma_f32_16x16x32_bf16 v[76:79], v[156:159], v[226:229], v[76:79]
	v_mfma_f32_16x16x32_bf16 v[72:75], v[164:167], v[226:229], v[72:75]
	s_setprio 0
	s_setprio 1
	v_mfma_f32_16x16x32_bf16 v[116:119], v[168:171], v[184:187], v[116:119]
	v_mfma_f32_16x16x32_bf16 v[112:115], v[176:179], v[184:187], v[112:115]
	v_mfma_f32_16x16x32_bf16 v[100:103], v[168:171], v[206:209], v[100:103]
	v_mfma_f32_16x16x32_bf16 v[96:99], v[176:179], v[206:209], v[96:99]
	v_mfma_f32_16x16x32_bf16 v[84:87], v[168:171], v[214:217], v[84:87]
	v_mfma_f32_16x16x32_bf16 v[80:83], v[176:179], v[214:217], v[80:83]
	v_mfma_f32_16x16x32_bf16 v[68:71], v[168:171], v[222:225], v[68:71]
	v_mfma_f32_16x16x32_bf16 v[64:67], v[176:179], v[222:225], v[64:67]
	v_mfma_f32_16x16x32_bf16 v[116:119], v[172:175], v[194:197], v[116:119]
	v_mfma_f32_16x16x32_bf16 v[112:115], v[180:183], v[194:197], v[112:115]
	v_mfma_f32_16x16x32_bf16 v[100:103], v[172:175], v[210:213], v[100:103]
	v_mfma_f32_16x16x32_bf16 v[96:99], v[180:183], v[210:213], v[96:99]
	v_mfma_f32_16x16x32_bf16 v[84:87], v[172:175], v[218:221], v[84:87]
	v_mfma_f32_16x16x32_bf16 v[80:83], v[180:183], v[218:221], v[80:83]
	v_mfma_f32_16x16x32_bf16 v[68:71], v[172:175], v[226:229], v[68:71]
	v_mfma_f32_16x16x32_bf16 v[64:67], v[180:183], v[226:229], v[64:67]
	s_setprio 0
	s_barrier
	s_add_i32 s67, s50, s3
	v_lshl_add_u64 v[188:189], s[40:41], 0, v[130:131]
	s_mov_b32 m0, s67
	ds_read_b128 v[184:187], v153 offset:16384
	ds_read_b128 v[194:197], v153 offset:17408
	ds_read_b128 v[206:209], v153 offset:18432
	ds_read_b128 v[210:213], v153 offset:19456
	ds_read_b128 v[214:217], v153 offset:20480
	ds_read_b128 v[218:221], v153 offset:21504
	ds_read_b128 v[222:225], v153 offset:22528
	ds_read_b128 v[226:229], v153 offset:23552
	global_load_lds_dwordx4 v[188:189], off
	s_add_i32 m0, s67, 0x2000
	s_add_u32 s68, s40, 0x40000
	v_lshl_add_u64 v[230:231], s[40:41], 0, v[134:135]
	s_addc_u32 s69, s41, 0
	s_add_i32 s67, s51, s3
	global_load_lds_dwordx4 v[230:231], off
	v_lshl_add_u64 v[232:233], s[68:69], 0, v[130:131]
	s_mov_b32 m0, s67
	v_lshl_add_u64 v[234:235], s[42:43], 0, v[132:133]
	global_load_lds_dwordx4 v[232:233], off
	v_lshl_add_u64 v[232:233], s[68:69], 0, v[134:135]
	s_add_i32 m0, s67, 0x2000
	s_nop 0
	global_load_lds_dwordx4 v[232:233], off
	v_lshl_add_u64 v[232:233], s[42:43], 0, v[128:129]
	s_mov_b32 m0, s29
	s_nop 0
	global_load_lds_dwordx4 v[232:233], off
	s_mov_b32 m0, s30
	s_nop 0
	global_load_lds_dwordx4 v[234:235], off
	s_cmp_lg_u32 s100, 0
	s_cbranch_scc1 .Lrw_g2_1
	s_waitcnt vmcnt(8)
.Lrw_g2_1:
	s_waitcnt lgkmcnt(0)
	s_barrier
	s_setprio 1
	s_waitcnt lgkmcnt(0)
	v_mfma_f32_16x16x32_bf16 v[60:63], v[144:147], v[184:187], v[60:63]
	v_mfma_f32_16x16x32_bf16 v[56:59], v[160:163], v[184:187], v[56:59]
	v_mfma_f32_16x16x32_bf16 v[44:47], v[144:147], v[206:209], v[44:47]
	v_mfma_f32_16x16x32_bf16 v[40:43], v[160:163], v[206:209], v[40:43]
	v_mfma_f32_16x16x32_bf16 v[28:31], v[144:147], v[214:217], v[28:31]
	v_mfma_f32_16x16x32_bf16 v[24:27], v[160:163], v[214:217], v[24:27]
	v_mfma_f32_16x16x32_bf16 v[12:15], v[144:147], v[222:225], v[12:15]
	v_mfma_f32_16x16x32_bf16 v[8:11], v[160:163], v[222:225], v[8:11]
	v_mfma_f32_16x16x32_bf16 v[60:63], v[156:159], v[194:197], v[60:63]
	v_mfma_f32_16x16x32_bf16 v[56:59], v[164:167], v[194:197], v[56:59]
	v_mfma_f32_16x16x32_bf16 v[44:47], v[156:159], v[210:213], v[44:47]
	v_mfma_f32_16x16x32_bf16 v[40:43], v[164:167], v[210:213], v[40:43]
	v_mfma_f32_16x16x32_bf16 v[28:31], v[156:159], v[218:221], v[28:31]
	v_mfma_f32_16x16x32_bf16 v[24:27], v[164:167], v[218:221], v[24:27]
	v_mfma_f32_16x16x32_bf16 v[12:15], v[156:159], v[226:229], v[12:15]
	v_mfma_f32_16x16x32_bf16 v[8:11], v[164:167], v[226:229], v[8:11]
	s_setprio 0
	s_setprio 1
	v_mfma_f32_16x16x32_bf16 v[52:55], v[168:171], v[184:187], v[52:55]
	v_mfma_f32_16x16x32_bf16 v[48:51], v[176:179], v[184:187], v[48:51]
	v_mfma_f32_16x16x32_bf16 v[36:39], v[168:171], v[206:209], v[36:39]
	v_mfma_f32_16x16x32_bf16 v[32:35], v[176:179], v[206:209], v[32:35]
	v_mfma_f32_16x16x32_bf16 v[20:23], v[168:171], v[214:217], v[20:23]
	v_mfma_f32_16x16x32_bf16 v[16:19], v[176:179], v[214:217], v[16:19]
	v_mfma_f32_16x16x32_bf16 v[4:7], v[168:171], v[222:225], v[4:7]
	v_mfma_f32_16x16x32_bf16 v[0:3], v[176:179], v[222:225], v[0:3]
	v_mfma_f32_16x16x32_bf16 v[52:55], v[172:175], v[194:197], v[52:55]
	v_mfma_f32_16x16x32_bf16 v[48:51], v[180:183], v[194:197], v[48:51]
	v_mfma_f32_16x16x32_bf16 v[36:39], v[172:175], v[210:213], v[36:39]
	v_mfma_f32_16x16x32_bf16 v[32:35], v[180:183], v[210:213], v[32:35]
	v_mfma_f32_16x16x32_bf16 v[20:23], v[172:175], v[218:221], v[20:23]
	v_mfma_f32_16x16x32_bf16 v[16:19], v[180:183], v[218:221], v[16:19]
	v_mfma_f32_16x16x32_bf16 v[4:7], v[172:175], v[226:229], v[4:7]
	v_mfma_f32_16x16x32_bf16 v[0:3], v[180:183], v[226:229], v[0:3]
	s_setprio 0
	s_barrier
	s_add_i32 s67, 0, 0x18000
	v_add_u32_e32 v155, s67, v149
	s_add_i32 s68, 0, 0x1c000
	ds_read_b128 v[144:147], v155
	ds_read_b128 v[156:159], v155 offset:1024
	ds_read_b128 v[160:163], v155 offset:2048
	ds_read_b128 v[164:167], v155 offset:3072
	v_add_u32_e32 v155, s68, v149
	ds_read_b128 v[168:171], v155
	ds_read_b128 v[172:175], v155 offset:1024
	ds_read_b128 v[176:179], v155 offset:2048
	ds_read_b128 v[180:183], v155 offset:3072
	s_add_u32 s42, s42, 0x40000
	s_addc_u32 s43, s43, 0
	s_mov_b32 m0, s31
	v_lshl_add_u64 v[236:237], s[42:43], 0, v[128:129]
	ds_read_b128 v[184:187], v153 offset:32768
	ds_read_b128 v[194:197], v153 offset:33792
	ds_read_b128 v[206:209], v153 offset:34816
	ds_read_b128 v[210:213], v153 offset:35840
	ds_read_b128 v[214:217], v153 offset:36864
	ds_read_b128 v[218:221], v153 offset:37888
	ds_read_b128 v[222:225], v153 offset:38912
	ds_read_b128 v[226:229], v153 offset:39936
	global_load_lds_dwordx4 v[236:237], off
	v_lshl_add_u64 v[236:237], s[42:43], 0, v[132:133]
	s_mov_b32 m0, s33
	s_nop 0
	global_load_lds_dwordx4 v[236:237], off
	s_waitcnt vmcnt(8)
	s_waitcnt lgkmcnt(0)
	s_barrier
	s_setprio 1
	s_waitcnt lgkmcnt(0)
	v_mfma_f32_16x16x32_bf16 v[124:127], v[144:147], v[184:187], v[124:127]
	v_mfma_f32_16x16x32_bf16 v[120:123], v[160:163], v[184:187], v[120:123]
	v_mfma_f32_16x16x32_bf16 v[108:111], v[144:147], v[206:209], v[108:111]
	v_mfma_f32_16x16x32_bf16 v[104:107], v[160:163], v[206:209], v[104:107]
	v_mfma_f32_16x16x32_bf16 v[92:95], v[144:147], v[214:217], v[92:95]
	v_mfma_f32_16x16x32_bf16 v[88:91], v[160:163], v[214:217], v[88:91]
	v_mfma_f32_16x16x32_bf16 v[76:79], v[144:147], v[222:225], v[76:79]
	v_mfma_f32_16x16x32_bf16 v[72:75], v[160:163], v[222:225], v[72:75]
	v_mfma_f32_16x16x32_bf16 v[124:127], v[156:159], v[194:197], v[124:127]
	v_mfma_f32_16x16x32_bf16 v[120:123], v[164:167], v[194:197], v[120:123]
	v_mfma_f32_16x16x32_bf16 v[108:111], v[156:159], v[210:213], v[108:111]
	v_mfma_f32_16x16x32_bf16 v[104:107], v[164:167], v[210:213], v[104:107]
	v_mfma_f32_16x16x32_bf16 v[92:95], v[156:159], v[218:221], v[92:95]
	v_mfma_f32_16x16x32_bf16 v[88:91], v[164:167], v[218:221], v[88:91]
	v_mfma_f32_16x16x32_bf16 v[76:79], v[156:159], v[226:229], v[76:79]
	v_mfma_f32_16x16x32_bf16 v[72:75], v[164:167], v[226:229], v[72:75]
	s_setprio 0
	s_setprio 1
	v_mfma_f32_16x16x32_bf16 v[116:119], v[168:171], v[184:187], v[116:119]
	v_mfma_f32_16x16x32_bf16 v[112:115], v[176:179], v[184:187], v[112:115]
	v_mfma_f32_16x16x32_bf16 v[100:103], v[168:171], v[206:209], v[100:103]
	v_mfma_f32_16x16x32_bf16 v[96:99], v[176:179], v[206:209], v[96:99]
	v_mfma_f32_16x16x32_bf16 v[84:87], v[168:171], v[214:217], v[84:87]
	v_mfma_f32_16x16x32_bf16 v[80:83], v[176:179], v[214:217], v[80:83]
	v_mfma_f32_16x16x32_bf16 v[68:71], v[168:171], v[222:225], v[68:71]
	v_mfma_f32_16x16x32_bf16 v[64:67], v[176:179], v[222:225], v[64:67]
	v_mfma_f32_16x16x32_bf16 v[116:119], v[172:175], v[194:197], v[116:119]
	v_mfma_f32_16x16x32_bf16 v[112:115], v[180:183], v[194:197], v[112:115]
	v_mfma_f32_16x16x32_bf16 v[100:103], v[172:175], v[210:213], v[100:103]
	v_mfma_f32_16x16x32_bf16 v[96:99], v[180:183], v[210:213], v[96:99]
	v_mfma_f32_16x16x32_bf16 v[84:87], v[172:175], v[218:221], v[84:87]
	v_mfma_f32_16x16x32_bf16 v[80:83], v[180:183], v[218:221], v[80:83]
	v_mfma_f32_16x16x32_bf16 v[68:71], v[172:175], v[226:229], v[68:71]
	v_mfma_f32_16x16x32_bf16 v[64:67], v[180:183], v[226:229], v[64:67]
	s_setprio 0
	s_barrier
	s_add_i32 s42, s67, s3
	v_lshl_add_u64 v[188:189], v[188:189], 0, s[18:19]
	s_mov_b32 m0, s42
	ds_read_b128 v[184:187], v153 offset:49152
	ds_read_b128 v[194:197], v153 offset:50176
	ds_read_b128 v[206:209], v153 offset:51200
	ds_read_b128 v[210:213], v153 offset:52224
	ds_read_b128 v[214:217], v153 offset:53248
	ds_read_b128 v[218:221], v153 offset:54272
	ds_read_b128 v[222:225], v153 offset:55296
	ds_read_b128 v[226:229], v153 offset:56320
	global_load_lds_dwordx4 v[188:189], off
	s_add_i32 m0, s42, 0x2000
	s_add_u32 s40, s40, 0x40080
	v_lshl_add_u64 v[188:189], v[230:231], 0, s[18:19]
	s_addc_u32 s41, s41, 0
	s_add_i32 s42, s68, s3
	global_load_lds_dwordx4 v[188:189], off
	v_lshl_add_u64 v[188:189], s[40:41], 0, v[130:131]
	s_mov_b32 m0, s42
	s_nop 0
	global_load_lds_dwordx4 v[188:189], off
	v_lshl_add_u64 v[188:189], s[40:41], 0, v[134:135]
	s_add_i32 m0, s42, 0x2000
	s_nop 0
	global_load_lds_dwordx4 v[188:189], off
	v_lshl_add_u64 v[188:189], v[232:233], 0, s[18:19]
	s_mov_b32 m0, s46
	s_nop 0
	global_load_lds_dwordx4 v[188:189], off
	v_lshl_add_u64 v[188:189], v[234:235], 0, s[18:19]
	s_mov_b32 m0, s47
	s_nop 0
	global_load_lds_dwordx4 v[188:189], off
	s_waitcnt vmcnt(8)
	s_waitcnt lgkmcnt(0)
	s_barrier
	s_setprio 1
	s_waitcnt lgkmcnt(0)
	v_mfma_f32_16x16x32_bf16 v[60:63], v[144:147], v[184:187], v[60:63]
	v_mfma_f32_16x16x32_bf16 v[56:59], v[160:163], v[184:187], v[56:59]
	v_mfma_f32_16x16x32_bf16 v[44:47], v[144:147], v[206:209], v[44:47]
	v_mfma_f32_16x16x32_bf16 v[40:43], v[160:163], v[206:209], v[40:43]
	v_mfma_f32_16x16x32_bf16 v[28:31], v[144:147], v[214:217], v[28:31]
	v_mfma_f32_16x16x32_bf16 v[24:27], v[160:163], v[214:217], v[24:27]
	v_mfma_f32_16x16x32_bf16 v[12:15], v[144:147], v[222:225], v[12:15]
	v_mfma_f32_16x16x32_bf16 v[8:11], v[160:163], v[222:225], v[8:11]
	v_mfma_f32_16x16x32_bf16 v[60:63], v[156:159], v[194:197], v[60:63]
	v_mfma_f32_16x16x32_bf16 v[56:59], v[164:167], v[194:197], v[56:59]
	v_mfma_f32_16x16x32_bf16 v[44:47], v[156:159], v[210:213], v[44:47]
	v_mfma_f32_16x16x32_bf16 v[40:43], v[164:167], v[210:213], v[40:43]
	v_mfma_f32_16x16x32_bf16 v[28:31], v[156:159], v[218:221], v[28:31]
	v_mfma_f32_16x16x32_bf16 v[24:27], v[164:167], v[218:221], v[24:27]
	v_mfma_f32_16x16x32_bf16 v[12:15], v[156:159], v[226:229], v[12:15]
	v_mfma_f32_16x16x32_bf16 v[8:11], v[164:167], v[226:229], v[8:11]
	s_setprio 0
	s_setprio 1
	v_mfma_f32_16x16x32_bf16 v[52:55], v[168:171], v[184:187], v[52:55]
	v_mfma_f32_16x16x32_bf16 v[48:51], v[176:179], v[184:187], v[48:51]
	v_mfma_f32_16x16x32_bf16 v[36:39], v[168:171], v[206:209], v[36:39]
	v_mfma_f32_16x16x32_bf16 v[32:35], v[176:179], v[206:209], v[32:35]
	v_mfma_f32_16x16x32_bf16 v[20:23], v[168:171], v[214:217], v[20:23]
	v_mfma_f32_16x16x32_bf16 v[16:19], v[176:179], v[214:217], v[16:19]
	v_mfma_f32_16x16x32_bf16 v[4:7], v[168:171], v[222:225], v[4:7]
	v_mfma_f32_16x16x32_bf16 v[0:3], v[176:179], v[222:225], v[0:3]
	v_mfma_f32_16x16x32_bf16 v[52:55], v[172:175], v[194:197], v[52:55]
	v_mfma_f32_16x16x32_bf16 v[48:51], v[180:183], v[194:197], v[48:51]
	v_mfma_f32_16x16x32_bf16 v[36:39], v[172:175], v[210:213], v[36:39]
	v_mfma_f32_16x16x32_bf16 v[32:35], v[180:183], v[210:213], v[32:35]
	v_mfma_f32_16x16x32_bf16 v[20:23], v[172:175], v[218:221], v[20:23]
	v_mfma_f32_16x16x32_bf16 v[16:19], v[180:183], v[218:221], v[16:19]
	v_mfma_f32_16x16x32_bf16 v[4:7], v[172:175], v[226:229], v[4:7]
	v_mfma_f32_16x16x32_bf16 v[0:3], v[180:183], v[226:229], v[0:3]
	s_setprio 0
	s_barrier
	s_add_i32 s66, s66, 2
	s_add_u32 s38, s38, 0x100
	s_addc_u32 s39, s39, 0
	s_add_u32 s64, s64, 0x100
	s_addc_u32 s65, s65, 0
	s_cmp_gt_u32 s66, 13
	s_cbranch_scc0 .LBB0_685
	s_and_b64 vcc, exec, s[20:21]
	s_cbranch_vccz .LBB0_688
	s_barrier
.LBB0_688:
	v_lshl_add_u32 v146, s36, 8, v148
	v_ashrrev_i32_e32 v147, 31, v146
	v_lshl_or_b32 v144, s8, 8, v150
	v_lshlrev_b64 v[156:157], 11, v[146:147]
	v_ashrrev_i32_e32 v145, 31, v144
	v_lshl_add_u64 v[156:157], s[16:17], 0, v[156:157]
	v_lshl_add_u64 v[160:161], v[144:145], 1, v[156:157]
	global_load_dwordx4 v[156:159], v[160:161], off
	v_xor_b32_e32 v155, 32, v154
	s_lshl_b32 s36, s8, 2
	s_ashr_i32 s37, s36, 31
	s_waitcnt vmcnt(0)
	v_lshlrev_b32_e32 v162, 16, v156
	v_and_b32_e32 v163, 0xffff0000, v156
	v_lshlrev_b32_e32 v156, 16, v157
	v_and_b32_e32 v157, 0xffff0000, v157
	v_lshlrev_b32_e32 v164, 16, v158
	v_and_b32_e32 v165, 0xffff0000, v158
	v_lshlrev_b32_e32 v158, 16, v159
	v_and_b32_e32 v159, 0xffff0000, v159
	v_pk_add_f32 v[126:127], v[126:127], v[156:157]
	v_pk_add_f32 v[162:163], v[124:125], v[162:163]
	v_pk_add_f32 v[166:167], v[122:123], v[158:159]
	v_pk_add_f32 v[164:165], v[120:121], v[164:165]
	v_cvt_pk_bf16_f32 v122, v162, v163
	v_cvt_pk_bf16_f32 v123, v126, v127
	v_mul_f32_e32 v163, v163, v163
	v_cvt_pk_bf16_f32 v124, v164, v165
	v_cvt_pk_bf16_f32 v125, v166, v167
	global_load_dwordx4 v[156:159], v[160:161], off offset:64
	v_mul_f32_e32 v127, v127, v127
	v_mul_f32_e32 v165, v165, v165
	v_fmac_f32_e32 v163, v162, v162
	v_fmac_f32_e32 v127, v126, v126
	v_mul_f32_e32 v167, v167, v167
	v_fmac_f32_e32 v165, v164, v164
	v_add_f32_e32 v126, v163, v127
	v_fmac_f32_e32 v167, v166, v166
	v_add_f32_e32 v126, v165, v126
	v_add_f32_e32 v164, v167, v126
	v_and_b32_e32 v121, 64, v154
	v_xor_b32_e32 v120, 16, v154
	v_add_u32_e32 v121, 64, v121
	v_cmp_lt_i32_e32 vcc, v120, v121
	global_store_dwordx4 v[160:161], v[122:125], off
	s_waitcnt vmcnt(1)
	v_lshlrev_b32_e32 v162, 16, v156
	v_and_b32_e32 v163, 0xffff0000, v156
	v_lshlrev_b32_e32 v156, 16, v157
	v_and_b32_e32 v157, 0xffff0000, v157
	v_lshlrev_b32_e32 v126, 16, v158
	v_and_b32_e32 v127, 0xffff0000, v158
	v_pk_add_f32 v[118:119], v[118:119], v[156:157]
	v_pk_add_f32 v[116:117], v[116:117], v[162:163]
	v_lshlrev_b32_e32 v158, 16, v159
	v_and_b32_e32 v159, 0xffff0000, v159
	v_pk_add_f32 v[126:127], v[112:113], v[126:127]
	v_mul_f32_e32 v112, v117, v117
	v_mul_f32_e32 v113, v119, v119
	v_pk_add_f32 v[156:157], v[114:115], v[158:159]
	v_mul_f32_e32 v114, v127, v127
	v_fmac_f32_e32 v112, v116, v116
	v_fmac_f32_e32 v113, v118, v118
	v_mul_f32_e32 v115, v157, v157
	v_fmac_f32_e32 v114, v126, v126
	v_add_f32_e32 v112, v112, v113
	v_fmac_f32_e32 v115, v156, v156
	v_add_f32_e32 v112, v112, v114
	v_cndmask_b32_e32 v120, v154, v120, vcc
	v_add_f32_e32 v112, v115, v112
	v_lshlrev_b32_e32 v120, 2, v120
	v_add_f32_e32 v112, v164, v112
	ds_bpermute_b32 v113, v120, v112
	v_cmp_lt_i32_e32 vcc, v155, v121
	v_cvt_pk_bf16_f32 v116, v116, v117
	v_cvt_pk_bf16_f32 v117, v118, v119
	v_cvt_pk_bf16_f32 v118, v126, v127
	s_waitcnt lgkmcnt(0)
	v_add_f32_e32 v112, v112, v113
	v_cvt_pk_bf16_f32 v119, v156, v157
	v_cndmask_b32_e32 v114, v154, v155, vcc
	v_lshlrev_b32_e32 v114, 2, v114
	ds_bpermute_b32 v113, v114, v112
	global_store_dwordx4 v[160:161], v[116:119], off offset:64
	s_and_saveexec_b64 s[38:39], s[0:1]
	s_cbranch_execz .LBB0_690
	v_lshlrev_b64 v[116:117], 6, v[146:147]
	v_lshl_add_u64 v[116:117], s[14:15], 0, v[116:117]
	v_lshl_add_u64 v[116:117], s[36:37], 2, v[116:117]
	s_lshl_b32 s8, s44, 2
	v_lshl_add_u64 v[116:117], v[116:117], 0, s[8:9]
	s_waitcnt lgkmcnt(0)
	v_add_f32_e32 v112, v112, v113
	global_store_dword v[116:117], v112, off
.LBB0_690:
	s_or_b64 exec, exec, s[38:39]
	v_or_b32_e32 v112, 16, v146
	s_waitcnt lgkmcnt(0)
	v_ashrrev_i32_e32 v113, 31, v112
	v_lshlrev_b64 v[116:117], 11, v[112:113]
	v_lshl_add_u64 v[116:117], s[16:17], 0, v[116:117]
	v_lshl_add_u64 v[122:123], v[144:145], 1, v[116:117]
	global_load_dwordx4 v[116:119], v[122:123], off
	s_waitcnt vmcnt(0)
	v_lshlrev_b32_e32 v124, 16, v116
	v_and_b32_e32 v125, 0xffff0000, v116
	v_lshlrev_b32_e32 v116, 16, v117
	v_and_b32_e32 v117, 0xffff0000, v117
	v_lshlrev_b32_e32 v126, 16, v118
	v_and_b32_e32 v127, 0xffff0000, v118
	v_lshlrev_b32_e32 v118, 16, v119
	v_and_b32_e32 v119, 0xffff0000, v119
	v_pk_add_f32 v[116:117], v[110:111], v[116:117]
	v_pk_add_f32 v[124:125], v[108:109], v[124:125]
	v_pk_add_f32 v[118:119], v[106:107], v[118:119]
	v_pk_add_f32 v[126:127], v[104:105], v[126:127]
	v_cvt_pk_bf16_f32 v104, v124, v125
	v_cvt_pk_bf16_f32 v105, v116, v117
	v_mul_f32_e32 v115, v125, v125
	v_cvt_pk_bf16_f32 v106, v126, v127
	v_cvt_pk_bf16_f32 v107, v118, v119
	global_load_dwordx4 v[108:111], v[122:123], off offset:64
	v_mul_f32_e32 v117, v117, v117
	v_mul_f32_e32 v121, v127, v127
	v_fmac_f32_e32 v115, v124, v124
	v_fmac_f32_e32 v117, v116, v116
	v_mul_f32_e32 v119, v119, v119
	v_fmac_f32_e32 v121, v126, v126
	v_add_f32_e32 v115, v115, v117
	v_fmac_f32_e32 v119, v118, v118
	v_add_f32_e32 v115, v121, v115
	v_add_f32_e32 v115, v119, v115
	global_store_dwordx4 v[122:123], v[104:107], off
	s_waitcnt vmcnt(1)
	v_lshlrev_b32_e32 v118, 16, v108
	v_and_b32_e32 v119, 0xffff0000, v108
	v_lshlrev_b32_e32 v108, 16, v109
	v_and_b32_e32 v109, 0xffff0000, v109
	v_lshlrev_b32_e32 v116, 16, v110
	v_and_b32_e32 v117, 0xffff0000, v110
	v_lshlrev_b32_e32 v110, 16, v111
	v_and_b32_e32 v111, 0xffff0000, v111
	v_pk_add_f32 v[102:103], v[102:103], v[108:109]
	v_pk_add_f32 v[100:101], v[100:101], v[118:119]
	v_pk_add_f32 v[108:109], v[98:99], v[110:111]
	v_pk_add_f32 v[110:111], v[96:97], v[116:117]
	v_mul_f32_e32 v96, v101, v101
	v_mul_f32_e32 v97, v103, v103
	v_mul_f32_e32 v98, v111, v111
	v_fmac_f32_e32 v96, v100, v100
	v_fmac_f32_e32 v97, v102, v102
	v_mul_f32_e32 v99, v109, v109
	v_fmac_f32_e32 v98, v110, v110
	v_add_f32_e32 v96, v96, v97
	v_add_f32_e32 v96, v96, v98
	v_fmac_f32_e32 v99, v108, v108
	v_add_f32_e32 v96, v99, v96
	v_add_f32_e32 v96, v115, v96
	ds_bpermute_b32 v97, v120, v96
	v_cvt_pk_bf16_f32 v98, v100, v101
	v_cvt_pk_bf16_f32 v99, v102, v103
	v_cvt_pk_bf16_f32 v100, v110, v111
	v_cvt_pk_bf16_f32 v101, v108, v109
	s_waitcnt lgkmcnt(0)
	v_add_f32_e32 v96, v96, v97
	ds_bpermute_b32 v97, v114, v96
	global_store_dwordx4 v[122:123], v[98:101], off offset:64
	s_and_saveexec_b64 s[38:39], s[0:1]
	s_cbranch_execz .LBB0_692
	v_lshlrev_b64 v[98:99], 6, v[112:113]
	v_lshl_add_u64 v[98:99], s[14:15], 0, v[98:99]
	v_lshl_add_u64 v[98:99], s[36:37], 2, v[98:99]
	s_lshl_b32 s8, s44, 2
	v_lshl_add_u64 v[98:99], v[98:99], 0, s[8:9]
	s_waitcnt lgkmcnt(0)
	v_add_f32_e32 v96, v96, v97
	global_store_dword v[98:99], v96, off
.LBB0_692:
	s_or_b64 exec, exec, s[38:39]
	v_or_b32_e32 v96, 32, v146
	s_waitcnt lgkmcnt(0)
	v_ashrrev_i32_e32 v97, 31, v96
	v_lshlrev_b64 v[98:99], 11, v[96:97]
	v_lshl_add_u64 v[98:99], s[16:17], 0, v[98:99]
	v_lshl_add_u64 v[102:103], v[144:145], 1, v[98:99]
	global_load_dwordx4 v[98:101], v[102:103], off
	s_waitcnt vmcnt(0)
	v_lshlrev_b32_e32 v104, 16, v98
	v_and_b32_e32 v105, 0xffff0000, v98
	v_lshlrev_b32_e32 v98, 16, v99
	v_and_b32_e32 v99, 0xffff0000, v99
	v_lshlrev_b32_e32 v106, 16, v100
	v_and_b32_e32 v107, 0xffff0000, v100
	v_lshlrev_b32_e32 v100, 16, v101
	v_and_b32_e32 v101, 0xffff0000, v101
	v_pk_add_f32 v[98:99], v[94:95], v[98:99]
	v_pk_add_f32 v[104:105], v[92:93], v[104:105]
	v_pk_add_f32 v[100:101], v[90:91], v[100:101]
	v_pk_add_f32 v[106:107], v[88:89], v[106:107]
	v_cvt_pk_bf16_f32 v88, v104, v105
	v_cvt_pk_bf16_f32 v89, v98, v99
	v_mul_f32_e32 v105, v105, v105
	v_cvt_pk_bf16_f32 v90, v106, v107
	v_cvt_pk_bf16_f32 v91, v100, v101
	global_load_dwordx4 v[92:95], v[102:103], off offset:64
	v_mul_f32_e32 v99, v99, v99
	v_mul_f32_e32 v107, v107, v107
	v_fmac_f32_e32 v105, v104, v104
	v_fmac_f32_e32 v99, v98, v98
	v_mul_f32_e32 v101, v101, v101
	v_fmac_f32_e32 v107, v106, v106
	v_add_f32_e32 v98, v105, v99
	v_fmac_f32_e32 v101, v100, v100
	v_add_f32_e32 v98, v107, v98
	v_add_f32_e32 v104, v101, v98
	global_store_dwordx4 v[102:103], v[88:91], off
	s_waitcnt vmcnt(1)
	v_lshlrev_b32_e32 v100, 16, v92
	v_and_b32_e32 v101, 0xffff0000, v92
	v_lshlrev_b32_e32 v92, 16, v93
	v_and_b32_e32 v93, 0xffff0000, v93
	v_lshlrev_b32_e32 v98, 16, v94
	v_and_b32_e32 v99, 0xffff0000, v94
	v_lshlrev_b32_e32 v94, 16, v95
	v_and_b32_e32 v95, 0xffff0000, v95
	v_pk_add_f32 v[86:87], v[86:87], v[92:93]
	v_pk_add_f32 v[84:85], v[84:85], v[100:101]
	v_pk_add_f32 v[92:93], v[82:83], v[94:95]
	v_pk_add_f32 v[94:95], v[80:81], v[98:99]
	v_mul_f32_e32 v80, v85, v85
	v_mul_f32_e32 v81, v87, v87
	v_mul_f32_e32 v82, v95, v95
	v_fmac_f32_e32 v80, v84, v84
	v_fmac_f32_e32 v81, v86, v86
	v_mul_f32_e32 v83, v93, v93
	v_fmac_f32_e32 v82, v94, v94
	v_add_f32_e32 v80, v80, v81
	v_add_f32_e32 v80, v80, v82
	v_fmac_f32_e32 v83, v92, v92
	v_add_f32_e32 v80, v83, v80
	v_add_f32_e32 v80, v104, v80
	ds_bpermute_b32 v81, v120, v80
	v_cvt_pk_bf16_f32 v82, v84, v85
	v_cvt_pk_bf16_f32 v83, v86, v87
	v_cvt_pk_bf16_f32 v84, v94, v95
	v_cvt_pk_bf16_f32 v85, v92, v93
	s_waitcnt lgkmcnt(0)
	v_add_f32_e32 v80, v80, v81
	ds_bpermute_b32 v81, v114, v80
	global_store_dwordx4 v[102:103], v[82:85], off offset:64
	s_and_saveexec_b64 s[38:39], s[0:1]
	s_cbranch_execz .LBB0_694
	v_lshlrev_b64 v[82:83], 6, v[96:97]
	v_lshl_add_u64 v[82:83], s[14:15], 0, v[82:83]
	v_lshl_add_u64 v[82:83], s[36:37], 2, v[82:83]
	s_lshl_b32 s8, s44, 2
	v_lshl_add_u64 v[82:83], v[82:83], 0, s[8:9]
	s_waitcnt lgkmcnt(0)
	v_add_f32_e32 v80, v80, v81
	global_store_dword v[82:83], v80, off
.LBB0_694:
	s_or_b64 exec, exec, s[38:39]
	v_or_b32_e32 v80, 48, v146
	s_waitcnt lgkmcnt(0)
	v_ashrrev_i32_e32 v81, 31, v80
	v_lshlrev_b64 v[82:83], 11, v[80:81]
	v_lshl_add_u64 v[82:83], s[16:17], 0, v[82:83]
	v_lshl_add_u64 v[86:87], v[144:145], 1, v[82:83]
	global_load_dwordx4 v[82:85], v[86:87], off
	s_waitcnt vmcnt(0)
	v_lshlrev_b32_e32 v88, 16, v82
	v_and_b32_e32 v89, 0xffff0000, v82
	v_lshlrev_b32_e32 v82, 16, v83
	v_and_b32_e32 v83, 0xffff0000, v83
	v_lshlrev_b32_e32 v90, 16, v84
	v_and_b32_e32 v91, 0xffff0000, v84
	v_lshlrev_b32_e32 v84, 16, v85
	v_and_b32_e32 v85, 0xffff0000, v85
	v_pk_add_f32 v[82:83], v[78:79], v[82:83]
	v_pk_add_f32 v[88:89], v[76:77], v[88:89]
	v_pk_add_f32 v[84:85], v[74:75], v[84:85]
	v_pk_add_f32 v[90:91], v[72:73], v[90:91]
	v_cvt_pk_bf16_f32 v72, v88, v89
	v_cvt_pk_bf16_f32 v73, v82, v83
	v_mul_f32_e32 v89, v89, v89
	v_cvt_pk_bf16_f32 v74, v90, v91
	v_cvt_pk_bf16_f32 v75, v84, v85
	global_load_dwordx4 v[76:79], v[86:87], off offset:64
	v_mul_f32_e32 v83, v83, v83
	v_mul_f32_e32 v91, v91, v91
	v_fmac_f32_e32 v89, v88, v88
	v_fmac_f32_e32 v83, v82, v82
	v_mul_f32_e32 v85, v85, v85
	v_fmac_f32_e32 v91, v90, v90
	v_add_f32_e32 v82, v89, v83
	v_fmac_f32_e32 v85, v84, v84
	v_add_f32_e32 v82, v91, v82
	v_add_f32_e32 v88, v85, v82
	global_store_dwordx4 v[86:87], v[72:75], off
	s_waitcnt vmcnt(1)
	v_lshlrev_b32_e32 v84, 16, v76
	v_and_b32_e32 v85, 0xffff0000, v76
	v_lshlrev_b32_e32 v76, 16, v77
	v_and_b32_e32 v77, 0xffff0000, v77
	v_lshlrev_b32_e32 v82, 16, v78
	v_and_b32_e32 v83, 0xffff0000, v78
	v_lshlrev_b32_e32 v78, 16, v79
	v_and_b32_e32 v79, 0xffff0000, v79
	v_pk_add_f32 v[70:71], v[70:71], v[76:77]
	v_pk_add_f32 v[68:69], v[68:69], v[84:85]
	v_pk_add_f32 v[76:77], v[66:67], v[78:79]
	v_pk_add_f32 v[78:79], v[64:65], v[82:83]
	v_mul_f32_e32 v64, v69, v69
	v_mul_f32_e32 v65, v71, v71
	v_mul_f32_e32 v66, v79, v79
	v_fmac_f32_e32 v64, v68, v68
	v_fmac_f32_e32 v65, v70, v70
	v_mul_f32_e32 v67, v77, v77
	v_fmac_f32_e32 v66, v78, v78
	v_add_f32_e32 v64, v64, v65
	v_add_f32_e32 v64, v64, v66
	v_fmac_f32_e32 v67, v76, v76
	v_add_f32_e32 v64, v67, v64
	v_add_f32_e32 v64, v88, v64
	ds_bpermute_b32 v65, v120, v64
	v_cvt_pk_bf16_f32 v66, v68, v69
	v_cvt_pk_bf16_f32 v67, v70, v71
	v_cvt_pk_bf16_f32 v68, v78, v79
	v_cvt_pk_bf16_f32 v69, v76, v77
	s_waitcnt lgkmcnt(0)
	v_add_f32_e32 v64, v64, v65
	ds_bpermute_b32 v65, v114, v64
	global_store_dwordx4 v[86:87], v[66:69], off offset:64
	s_and_saveexec_b64 s[38:39], s[0:1]
	s_cbranch_execz .LBB0_696
	v_lshlrev_b64 v[66:67], 6, v[80:81]
	v_lshl_add_u64 v[66:67], s[14:15], 0, v[66:67]
	v_lshl_add_u64 v[66:67], s[36:37], 2, v[66:67]
	s_lshl_b32 s8, s44, 2
	v_lshl_add_u64 v[66:67], v[66:67], 0, s[8:9]
	s_waitcnt lgkmcnt(0)
	v_add_f32_e32 v64, v64, v65
	global_store_dword v[66:67], v64, off
.LBB0_696:
	s_or_b64 exec, exec, s[38:39]
	v_add_u32_e32 v64, 0x80, v146
	s_waitcnt lgkmcnt(0)
	v_ashrrev_i32_e32 v65, 31, v64
	v_lshlrev_b64 v[66:67], 11, v[64:65]
	v_lshl_add_u64 v[66:67], s[16:17], 0, v[66:67]
	v_lshl_add_u64 v[70:71], v[144:145], 1, v[66:67]
	global_load_dwordx4 v[66:69], v[70:71], off
	s_waitcnt vmcnt(0)
	v_lshlrev_b32_e32 v72, 16, v66
	v_and_b32_e32 v73, 0xffff0000, v66
	v_lshlrev_b32_e32 v66, 16, v67
	v_and_b32_e32 v67, 0xffff0000, v67
	v_lshlrev_b32_e32 v74, 16, v68
	v_and_b32_e32 v75, 0xffff0000, v68
	v_lshlrev_b32_e32 v68, 16, v69
	v_and_b32_e32 v69, 0xffff0000, v69
	v_pk_add_f32 v[66:67], v[62:63], v[66:67]
	v_pk_add_f32 v[72:73], v[60:61], v[72:73]
	v_pk_add_f32 v[68:69], v[58:59], v[68:69]
	v_pk_add_f32 v[74:75], v[56:57], v[74:75]
	v_cvt_pk_bf16_f32 v56, v72, v73
	v_cvt_pk_bf16_f32 v57, v66, v67
	v_mul_f32_e32 v73, v73, v73
	v_cvt_pk_bf16_f32 v58, v74, v75
	v_cvt_pk_bf16_f32 v59, v68, v69
	global_load_dwordx4 v[60:63], v[70:71], off offset:64
	v_mul_f32_e32 v67, v67, v67
	v_mul_f32_e32 v75, v75, v75
	v_fmac_f32_e32 v73, v72, v72
	v_fmac_f32_e32 v67, v66, v66
	v_mul_f32_e32 v69, v69, v69
	v_fmac_f32_e32 v75, v74, v74
	v_add_f32_e32 v66, v73, v67
	v_fmac_f32_e32 v69, v68, v68
	v_add_f32_e32 v66, v75, v66
	v_add_f32_e32 v72, v69, v66
	global_store_dwordx4 v[70:71], v[56:59], off
	s_waitcnt vmcnt(1)
	v_lshlrev_b32_e32 v68, 16, v60
	v_and_b32_e32 v69, 0xffff0000, v60
	v_lshlrev_b32_e32 v60, 16, v61
	v_and_b32_e32 v61, 0xffff0000, v61
	v_lshlrev_b32_e32 v66, 16, v62
	v_and_b32_e32 v67, 0xffff0000, v62
	v_lshlrev_b32_e32 v62, 16, v63
	v_and_b32_e32 v63, 0xffff0000, v63
	v_pk_add_f32 v[54:55], v[54:55], v[60:61]
	v_pk_add_f32 v[52:53], v[52:53], v[68:69]
	v_pk_add_f32 v[60:61], v[50:51], v[62:63]
	v_pk_add_f32 v[62:63], v[48:49], v[66:67]
	v_mul_f32_e32 v48, v53, v53
	v_mul_f32_e32 v49, v55, v55
	v_mul_f32_e32 v50, v63, v63
	v_fmac_f32_e32 v48, v52, v52
	v_fmac_f32_e32 v49, v54, v54
	v_mul_f32_e32 v51, v61, v61
	v_fmac_f32_e32 v50, v62, v62
	v_add_f32_e32 v48, v48, v49
	v_add_f32_e32 v48, v48, v50
	v_fmac_f32_e32 v51, v60, v60
	v_add_f32_e32 v48, v51, v48
	v_add_f32_e32 v48, v72, v48
	ds_bpermute_b32 v49, v120, v48
	v_cvt_pk_bf16_f32 v50, v52, v53
	v_cvt_pk_bf16_f32 v51, v54, v55
	v_cvt_pk_bf16_f32 v52, v62, v63
	v_cvt_pk_bf16_f32 v53, v60, v61
	s_waitcnt lgkmcnt(0)
	v_add_f32_e32 v48, v48, v49
	ds_bpermute_b32 v49, v114, v48
	global_store_dwordx4 v[70:71], v[50:53], off offset:64
	s_and_saveexec_b64 s[38:39], s[0:1]
	s_cbranch_execz .LBB0_698
	v_lshlrev_b64 v[50:51], 6, v[64:65]
	v_lshl_add_u64 v[50:51], s[14:15], 0, v[50:51]
	v_lshl_add_u64 v[50:51], s[36:37], 2, v[50:51]
	s_lshl_b32 s8, s44, 2
	v_lshl_add_u64 v[50:51], v[50:51], 0, s[8:9]
	s_waitcnt lgkmcnt(0)
	v_add_f32_e32 v48, v48, v49
	global_store_dword v[50:51], v48, off
.LBB0_698:
	s_or_b64 exec, exec, s[38:39]
	v_add_u32_e32 v48, 0x90, v146
	s_waitcnt lgkmcnt(0)
	v_ashrrev_i32_e32 v49, 31, v48
	v_lshlrev_b64 v[50:51], 11, v[48:49]
	v_lshl_add_u64 v[50:51], s[16:17], 0, v[50:51]
	v_lshl_add_u64 v[54:55], v[144:145], 1, v[50:51]
	global_load_dwordx4 v[50:53], v[54:55], off
	s_waitcnt vmcnt(0)
	v_lshlrev_b32_e32 v56, 16, v50
	v_and_b32_e32 v57, 0xffff0000, v50
	v_lshlrev_b32_e32 v50, 16, v51
	v_and_b32_e32 v51, 0xffff0000, v51
	v_lshlrev_b32_e32 v58, 16, v52
	v_and_b32_e32 v59, 0xffff0000, v52
	v_lshlrev_b32_e32 v52, 16, v53
	v_and_b32_e32 v53, 0xffff0000, v53
	v_pk_add_f32 v[50:51], v[46:47], v[50:51]
	v_pk_add_f32 v[56:57], v[44:45], v[56:57]
	v_pk_add_f32 v[52:53], v[42:43], v[52:53]
	v_pk_add_f32 v[58:59], v[40:41], v[58:59]
	v_cvt_pk_bf16_f32 v40, v56, v57
	v_cvt_pk_bf16_f32 v41, v50, v51
	v_mul_f32_e32 v57, v57, v57
	v_cvt_pk_bf16_f32 v42, v58, v59
	v_cvt_pk_bf16_f32 v43, v52, v53
	global_load_dwordx4 v[44:47], v[54:55], off offset:64
	v_mul_f32_e32 v51, v51, v51
	v_mul_f32_e32 v59, v59, v59
	v_fmac_f32_e32 v57, v56, v56
	v_fmac_f32_e32 v51, v50, v50
	v_mul_f32_e32 v53, v53, v53
	v_fmac_f32_e32 v59, v58, v58
	v_add_f32_e32 v50, v57, v51
	v_fmac_f32_e32 v53, v52, v52
	v_add_f32_e32 v50, v59, v50
	v_add_f32_e32 v56, v53, v50
	global_store_dwordx4 v[54:55], v[40:43], off
	s_waitcnt vmcnt(1)
	v_lshlrev_b32_e32 v52, 16, v44
	v_and_b32_e32 v53, 0xffff0000, v44
	v_lshlrev_b32_e32 v44, 16, v45
	v_and_b32_e32 v45, 0xffff0000, v45
	v_lshlrev_b32_e32 v50, 16, v46
	v_and_b32_e32 v51, 0xffff0000, v46
	v_lshlrev_b32_e32 v46, 16, v47
	v_and_b32_e32 v47, 0xffff0000, v47
	v_pk_add_f32 v[38:39], v[38:39], v[44:45]
	v_pk_add_f32 v[36:37], v[36:37], v[52:53]
	v_pk_add_f32 v[44:45], v[34:35], v[46:47]
	v_pk_add_f32 v[46:47], v[32:33], v[50:51]
	v_mul_f32_e32 v32, v37, v37
	v_mul_f32_e32 v33, v39, v39
	v_mul_f32_e32 v34, v47, v47
	v_fmac_f32_e32 v32, v36, v36
	v_fmac_f32_e32 v33, v38, v38
	v_mul_f32_e32 v35, v45, v45
	v_fmac_f32_e32 v34, v46, v46
	v_add_f32_e32 v32, v32, v33
	v_add_f32_e32 v32, v32, v34
	v_fmac_f32_e32 v35, v44, v44
	v_add_f32_e32 v32, v35, v32
	v_add_f32_e32 v32, v56, v32
	ds_bpermute_b32 v33, v120, v32
	v_cvt_pk_bf16_f32 v34, v36, v37
	v_cvt_pk_bf16_f32 v35, v38, v39
	v_cvt_pk_bf16_f32 v36, v46, v47
	v_cvt_pk_bf16_f32 v37, v44, v45
	s_waitcnt lgkmcnt(0)
	v_add_f32_e32 v32, v32, v33
	ds_bpermute_b32 v33, v114, v32
	global_store_dwordx4 v[54:55], v[34:37], off offset:64
	s_and_saveexec_b64 s[38:39], s[0:1]
	s_cbranch_execz .LBB0_700
	v_lshlrev_b64 v[34:35], 6, v[48:49]
	v_lshl_add_u64 v[34:35], s[14:15], 0, v[34:35]
	v_lshl_add_u64 v[34:35], s[36:37], 2, v[34:35]
	s_lshl_b32 s8, s44, 2
	v_lshl_add_u64 v[34:35], v[34:35], 0, s[8:9]
	s_waitcnt lgkmcnt(0)
	v_add_f32_e32 v32, v32, v33
	global_store_dword v[34:35], v32, off
.LBB0_700:
	s_or_b64 exec, exec, s[38:39]
	v_add_u32_e32 v32, 0xa0, v146
	s_waitcnt lgkmcnt(0)
	v_ashrrev_i32_e32 v33, 31, v32
	v_lshlrev_b64 v[34:35], 11, v[32:33]
	v_lshl_add_u64 v[34:35], s[16:17], 0, v[34:35]
	v_lshl_add_u64 v[38:39], v[144:145], 1, v[34:35]
	global_load_dwordx4 v[34:37], v[38:39], off
	s_waitcnt vmcnt(0)
	v_lshlrev_b32_e32 v40, 16, v34
	v_and_b32_e32 v41, 0xffff0000, v34
	v_lshlrev_b32_e32 v34, 16, v35
	v_and_b32_e32 v35, 0xffff0000, v35
	v_lshlrev_b32_e32 v42, 16, v36
	v_and_b32_e32 v43, 0xffff0000, v36
	v_lshlrev_b32_e32 v36, 16, v37
	v_and_b32_e32 v37, 0xffff0000, v37
	v_pk_add_f32 v[34:35], v[30:31], v[34:35]
	v_pk_add_f32 v[40:41], v[28:29], v[40:41]
	v_pk_add_f32 v[36:37], v[26:27], v[36:37]
	v_pk_add_f32 v[42:43], v[24:25], v[42:43]
	v_cvt_pk_bf16_f32 v24, v40, v41
	v_cvt_pk_bf16_f32 v25, v34, v35
	v_mul_f32_e32 v41, v41, v41
	v_cvt_pk_bf16_f32 v26, v42, v43
	v_cvt_pk_bf16_f32 v27, v36, v37
	global_load_dwordx4 v[28:31], v[38:39], off offset:64
	v_mul_f32_e32 v35, v35, v35
	v_mul_f32_e32 v43, v43, v43
	v_fmac_f32_e32 v41, v40, v40
	v_fmac_f32_e32 v35, v34, v34
	v_mul_f32_e32 v37, v37, v37
	v_fmac_f32_e32 v43, v42, v42
	v_add_f32_e32 v34, v41, v35
	v_fmac_f32_e32 v37, v36, v36
	v_add_f32_e32 v34, v43, v34
	v_add_f32_e32 v40, v37, v34
	global_store_dwordx4 v[38:39], v[24:27], off
	s_waitcnt vmcnt(1)
	v_lshlrev_b32_e32 v36, 16, v28
	v_and_b32_e32 v37, 0xffff0000, v28
	v_lshlrev_b32_e32 v28, 16, v29
	v_and_b32_e32 v29, 0xffff0000, v29
	v_lshlrev_b32_e32 v34, 16, v30
	v_and_b32_e32 v35, 0xffff0000, v30
	v_lshlrev_b32_e32 v30, 16, v31
	v_and_b32_e32 v31, 0xffff0000, v31
	v_pk_add_f32 v[22:23], v[22:23], v[28:29]
	v_pk_add_f32 v[20:21], v[20:21], v[36:37]
	v_pk_add_f32 v[28:29], v[18:19], v[30:31]
	v_pk_add_f32 v[30:31], v[16:17], v[34:35]
	v_mul_f32_e32 v16, v21, v21
	v_mul_f32_e32 v17, v23, v23
	v_mul_f32_e32 v18, v31, v31
	v_fmac_f32_e32 v16, v20, v20
	v_fmac_f32_e32 v17, v22, v22
	v_mul_f32_e32 v19, v29, v29
	v_fmac_f32_e32 v18, v30, v30
	v_add_f32_e32 v16, v16, v17
	v_add_f32_e32 v16, v16, v18
	v_fmac_f32_e32 v19, v28, v28
	v_add_f32_e32 v16, v19, v16
	v_add_f32_e32 v16, v40, v16
	ds_bpermute_b32 v17, v120, v16
	v_cvt_pk_bf16_f32 v18, v20, v21
	v_cvt_pk_bf16_f32 v19, v22, v23
	v_cvt_pk_bf16_f32 v20, v30, v31
	v_cvt_pk_bf16_f32 v21, v28, v29
	s_waitcnt lgkmcnt(0)
	v_add_f32_e32 v16, v16, v17
	ds_bpermute_b32 v17, v114, v16
	global_store_dwordx4 v[38:39], v[18:21], off offset:64
	s_and_saveexec_b64 s[38:39], s[0:1]
	s_cbranch_execz .LBB0_702
	v_lshlrev_b64 v[18:19], 6, v[32:33]
	v_lshl_add_u64 v[18:19], s[14:15], 0, v[18:19]
	v_lshl_add_u64 v[18:19], s[36:37], 2, v[18:19]
	s_lshl_b32 s8, s44, 2
	v_lshl_add_u64 v[18:19], v[18:19], 0, s[8:9]
	s_waitcnt lgkmcnt(0)
	v_add_f32_e32 v16, v16, v17
	global_store_dword v[18:19], v16, off
.LBB0_702:
	s_or_b64 exec, exec, s[38:39]
	v_add_u32_e32 v16, 0xb0, v146
	s_waitcnt lgkmcnt(0)
	v_ashrrev_i32_e32 v17, 31, v16
	v_lshlrev_b64 v[18:19], 11, v[16:17]
	v_lshl_add_u64 v[18:19], s[16:17], 0, v[18:19]
	v_lshl_add_u64 v[22:23], v[144:145], 1, v[18:19]
	global_load_dwordx4 v[18:21], v[22:23], off
	s_waitcnt vmcnt(0)
	v_lshlrev_b32_e32 v24, 16, v18
	v_and_b32_e32 v25, 0xffff0000, v18
	v_lshlrev_b32_e32 v18, 16, v19
	v_and_b32_e32 v19, 0xffff0000, v19
	v_lshlrev_b32_e32 v26, 16, v20
	v_and_b32_e32 v27, 0xffff0000, v20
	v_lshlrev_b32_e32 v20, 16, v21
	v_and_b32_e32 v21, 0xffff0000, v21
	v_pk_add_f32 v[18:19], v[14:15], v[18:19]
	v_pk_add_f32 v[24:25], v[12:13], v[24:25]
	v_pk_add_f32 v[20:21], v[10:11], v[20:21]
	v_pk_add_f32 v[26:27], v[8:9], v[26:27]
	v_cvt_pk_bf16_f32 v8, v24, v25
	v_cvt_pk_bf16_f32 v9, v18, v19
	v_mul_f32_e32 v25, v25, v25
	v_cvt_pk_bf16_f32 v10, v26, v27
	v_cvt_pk_bf16_f32 v11, v20, v21
	global_load_dwordx4 v[12:15], v[22:23], off offset:64
	v_mul_f32_e32 v19, v19, v19
	v_mul_f32_e32 v27, v27, v27
	v_fmac_f32_e32 v25, v24, v24
	v_fmac_f32_e32 v19, v18, v18
	v_mul_f32_e32 v21, v21, v21
	v_fmac_f32_e32 v27, v26, v26
	v_add_f32_e32 v18, v25, v19
	v_fmac_f32_e32 v21, v20, v20
	v_add_f32_e32 v18, v27, v18
	v_add_f32_e32 v24, v21, v18
	global_store_dwordx4 v[22:23], v[8:11], off
	s_waitcnt vmcnt(1)
	v_lshlrev_b32_e32 v20, 16, v12
	v_and_b32_e32 v21, 0xffff0000, v12
	v_lshlrev_b32_e32 v12, 16, v13
	v_and_b32_e32 v13, 0xffff0000, v13
	v_lshlrev_b32_e32 v18, 16, v14
	v_and_b32_e32 v19, 0xffff0000, v14
	v_lshlrev_b32_e32 v14, 16, v15
	v_and_b32_e32 v15, 0xffff0000, v15
	v_pk_add_f32 v[6:7], v[6:7], v[12:13]
	v_pk_add_f32 v[4:5], v[4:5], v[20:21]
	v_pk_add_f32 v[12:13], v[2:3], v[14:15]
	v_pk_add_f32 v[14:15], v[0:1], v[18:19]
	v_mul_f32_e32 v0, v5, v5
	v_mul_f32_e32 v1, v7, v7
	v_mul_f32_e32 v2, v15, v15
	v_fmac_f32_e32 v0, v4, v4
	v_fmac_f32_e32 v1, v6, v6
	v_mul_f32_e32 v3, v13, v13
	v_fmac_f32_e32 v2, v14, v14
	v_add_f32_e32 v0, v0, v1
	v_add_f32_e32 v0, v0, v2
	v_fmac_f32_e32 v3, v12, v12
	v_add_f32_e32 v0, v3, v0
	v_add_f32_e32 v0, v24, v0
	ds_bpermute_b32 v1, v120, v0
	v_cvt_pk_bf16_f32 v2, v4, v5
	v_cvt_pk_bf16_f32 v3, v6, v7
	v_cvt_pk_bf16_f32 v4, v14, v15
	v_cvt_pk_bf16_f32 v5, v12, v13
	s_waitcnt lgkmcnt(0)
	v_add_f32_e32 v0, v0, v1
	ds_bpermute_b32 v1, v114, v0
	global_store_dwordx4 v[22:23], v[2:5], off offset:64
	s_and_saveexec_b64 s[38:39], s[0:1]
	s_cbranch_execz .LBB0_704
	v_lshlrev_b64 v[2:3], 6, v[16:17]
	v_lshl_add_u64 v[2:3], s[14:15], 0, v[2:3]
	v_lshl_add_u64 v[2:3], s[36:37], 2, v[2:3]
	s_lshl_b32 s8, s44, 2
	v_lshl_add_u64 v[2:3], v[2:3], 0, s[8:9]
	s_waitcnt lgkmcnt(0)
	v_add_f32_e32 v0, v0, v1
	global_store_dword v[2:3], v0, off

.LBB0_769:
	s_add_i32 s39, s39, 1
	s_cmp_gt_u32 s39, 1
	s_cselect_b32 s101, 1, 0
	s_mul_i32 s0, s39, s42
	s_mul_hi_u32 s1, s39, s43
	s_add_i32 s1, s1, s0
	s_mul_i32 s0, s39, s43
	s_add_u32 s22, s0, s2
	s_addc_u32 s23, s1, s3
	v_cmp_gt_i64_e32 vcc, s[22:23], v[144:145]
	v_cmp_lt_i64_e64 s[0:1], s[22:23], v[142:143]
	s_cbranch_vccnz .LBB0_775
	s_ashr_i32 s18, s23, 31
	s_lshr_b32 s18, s18, 21
	s_add_i32 s18, s22, s18
	s_and_b32 s18, s18, 0xf800
	s_sub_i32 s18, s22, s18
	s_sext_i32_i16 s19, s18
	s_bfe_u32 s19, s19, 0x3001c
	s_add_i32 s20, s18, s19
	s_and_b32 s19, s20, 0xfff8
	s_sub_i32 s22, s18, s19
	s_sext_i32_i16 s18, s22
	s_cmp_gt_i32 s18, -1
	s_mov_b64 s[18:19], -1
	s_cbranch_scc0 .LBB0_772
	s_lshl_b32 s21, s22, 8
	s_mov_b64 s[18:19], 0

.LBB0_776:
	s_cmp_eq_u32 s51, -2
	s_cselect_b32 s100, s101, 0
	ds_read_b128 v[146:149], v153
	ds_read_b128 v[160:163], v153 offset:1024
	ds_read_b128 v[164:167], v153 offset:2048
	ds_read_b128 v[168:171], v153 offset:3072
	ds_read_b128 v[172:175], v154
	ds_read_b128 v[176:179], v154 offset:1024
	ds_read_b128 v[180:183], v154 offset:2048
	ds_read_b128 v[184:187], v154 offset:3072
	s_add_u32 s34, s26, 0xfffc0080
	s_addc_u32 s35, s27, -1
	s_cmp_eq_u32 s51, 12
	s_cselect_b32 s37, s19, s35
	s_cselect_b32 s36, s47, s34
	s_cselect_b32 s35, s21, s50
	s_cselect_b32 s34, s48, s49
	v_lshl_add_u64 v[188:189], s[26:27], 0, v[138:139]
	s_add_i32 m0, s30, 0xc000
	ds_read_b128 v[194:197], v155
	ds_read_b128 v[206:209], v155 offset:1024
	ds_read_b128 v[210:213], v155 offset:2048
	ds_read_b128 v[214:217], v155 offset:3072
	ds_read_b128 v[218:221], v155 offset:4096
	ds_read_b128 v[222:225], v155 offset:5120
	ds_read_b128 v[226:229], v155 offset:6144
	ds_read_b128 v[230:233], v155 offset:7168
	global_load_lds_dwordx4 v[188:189], off
	v_lshl_add_u64 v[188:189], s[26:27], 0, v[140:141]
	s_add_i32 m0, s30, 0xe000
	s_nop 0
	global_load_lds_dwordx4 v[188:189], off
	s_cmp_lg_u32 s100, 0
	s_cbranch_scc1 .Lrw_g3_0
	s_waitcnt vmcnt(8)
.Lrw_g3_0:
	s_waitcnt lgkmcnt(0)
	s_barrier
	s_setprio 1
	s_waitcnt lgkmcnt(0)
	v_mfma_f32_16x16x32_bf16 v[124:127], v[146:149], v[194:197], v[124:127]
	v_mfma_f32_16x16x32_bf16 v[120:123], v[164:167], v[194:197], v[120:123]
	v_mfma_f32_16x16x32_bf16 v[108:111], v[146:149], v[210:213], v[108:111]
	v_mfma_f32_16x16x32_bf16 v[104:107], v[164:167], v[210:213], v[104:107]
	v_mfma_f32_16x16x32_bf16 v[92:95], v[146:149], v[218:221], v[92:95]
	v_mfma_f32_16x16x32_bf16 v[88:91], v[164:167], v[218:221], v[88:91]
	v_mfma_f32_16x16x32_bf16 v[76:79], v[146:149], v[226:229], v[76:79]
	v_mfma_f32_16x16x32_bf16 v[72:75], v[164:167], v[226:229], v[72:75]
	v_mfma_f32_16x16x32_bf16 v[124:127], v[160:163], v[206:209], v[124:127]
	v_mfma_f32_16x16x32_bf16 v[120:123], v[168:171], v[206:209], v[120:123]
	v_mfma_f32_16x16x32_bf16 v[108:111], v[160:163], v[214:217], v[108:111]
	v_mfma_f32_16x16x32_bf16 v[104:107], v[168:171], v[214:217], v[104:107]
	v_mfma_f32_16x16x32_bf16 v[92:95], v[160:163], v[222:225], v[92:95]
	v_mfma_f32_16x16x32_bf16 v[88:91], v[168:171], v[222:225], v[88:91]
	v_mfma_f32_16x16x32_bf16 v[76:79], v[160:163], v[230:233], v[76:79]
	v_mfma_f32_16x16x32_bf16 v[72:75], v[168:171], v[230:233], v[72:75]
	s_setprio 0
	s_setprio 1
	v_mfma_f32_16x16x32_bf16 v[116:119], v[172:175], v[194:197], v[116:119]
	v_mfma_f32_16x16x32_bf16 v[112:115], v[180:183], v[194:197], v[112:115]
	v_mfma_f32_16x16x32_bf16 v[100:103], v[172:175], v[210:213], v[100:103]
	v_mfma_f32_16x16x32_bf16 v[96:99], v[180:183], v[210:213], v[96:99]
	v_mfma_f32_16x16x32_bf16 v[84:87], v[172:175], v[218:221], v[84:87]
	v_mfma_f32_16x16x32_bf16 v[80:83], v[180:183], v[218:221], v[80:83]
	v_mfma_f32_16x16x32_bf16 v[68:71], v[172:175], v[226:229], v[68:71]
	v_mfma_f32_16x16x32_bf16 v[64:67], v[180:183], v[226:229], v[64:67]
	v_mfma_f32_16x16x32_bf16 v[116:119], v[176:179], v[206:209], v[116:119]
	v_mfma_f32_16x16x32_bf16 v[112:115], v[184:187], v[206:209], v[112:115]
	v_mfma_f32_16x16x32_bf16 v[100:103], v[176:179], v[214:217], v[100:103]
	v_mfma_f32_16x16x32_bf16 v[96:99], v[184:187], v[214:217], v[96:99]
	v_mfma_f32_16x16x32_bf16 v[84:87], v[176:179], v[222:225], v[84:87]
	v_mfma_f32_16x16x32_bf16 v[80:83], v[184:187], v[222:225], v[80:83]
	v_mfma_f32_16x16x32_bf16 v[68:71], v[176:179], v[230:233], v[68:71]
	v_mfma_f32_16x16x32_bf16 v[64:67], v[184:187], v[230:233], v[64:67]
	s_setprio 0
	s_barrier
	s_add_i32 s62, s44, s29
	v_lshl_add_u64 v[188:189], s[34:35], 0, v[130:131]
	s_mov_b32 m0, s62
	ds_read_b128 v[194:197], v155 offset:16384
	ds_read_b128 v[206:209], v155 offset:17408
	ds_read_b128 v[210:213], v155 offset:18432
	ds_read_b128 v[214:217], v155 offset:19456
	ds_read_b128 v[218:221], v155 offset:20480
	ds_read_b128 v[222:225], v155 offset:21504
	ds_read_b128 v[226:229], v155 offset:22528
	ds_read_b128 v[230:233], v155 offset:23552
	global_load_lds_dwordx4 v[188:189], off
	s_add_i32 m0, s62, 0x2000
	s_add_u32 s62, s34, 0x40000
	v_lshl_add_u64 v[234:235], s[34:35], 0, v[134:135]
	s_addc_u32 s63, s35, 0
	s_add_i32 s64, s45, s29
	global_load_lds_dwordx4 v[234:235], off
	v_lshl_add_u64 v[236:237], s[62:63], 0, v[130:131]
	s_mov_b32 m0, s64
	v_lshl_add_u64 v[238:239], s[36:37], 0, v[132:133]
	global_load_lds_dwordx4 v[236:237], off
	v_lshl_add_u64 v[236:237], s[62:63], 0, v[134:135]
	s_add_i32 m0, s64, 0x2000
	s_nop 0
	global_load_lds_dwordx4 v[236:237], off
	v_lshl_add_u64 v[236:237], s[36:37], 0, v[128:129]
	s_mov_b32 m0, s30
	s_nop 0
	global_load_lds_dwordx4 v[236:237], off
	s_mov_b32 m0, s31
	s_nop 0
	global_load_lds_dwordx4 v[238:239], off
	s_cmp_lg_u32 s100, 0
	s_cbranch_scc1 .Lrw_g3_1
	s_waitcnt vmcnt(8)
.Lrw_g3_1:
	s_waitcnt lgkmcnt(0)
	s_barrier
	s_setprio 1
	s_waitcnt lgkmcnt(0)
	v_mfma_f32_16x16x32_bf16 v[60:63], v[146:149], v[194:197], v[60:63]
	v_mfma_f32_16x16x32_bf16 v[56:59], v[164:167], v[194:197], v[56:59]
	v_mfma_f32_16x16x32_bf16 v[44:47], v[146:149], v[210:213], v[44:47]
	v_mfma_f32_16x16x32_bf16 v[40:43], v[164:167], v[210:213], v[40:43]
	v_mfma_f32_16x16x32_bf16 v[28:31], v[146:149], v[218:221], v[28:31]
	v_mfma_f32_16x16x32_bf16 v[24:27], v[164:167], v[218:221], v[24:27]
	v_mfma_f32_16x16x32_bf16 v[12:15], v[146:149], v[226:229], v[12:15]
	v_mfma_f32_16x16x32_bf16 v[8:11], v[164:167], v[226:229], v[8:11]
	v_mfma_f32_16x16x32_bf16 v[60:63], v[160:163], v[206:209], v[60:63]
	v_mfma_f32_16x16x32_bf16 v[56:59], v[168:171], v[206:209], v[56:59]
	v_mfma_f32_16x16x32_bf16 v[44:47], v[160:163], v[214:217], v[44:47]
	v_mfma_f32_16x16x32_bf16 v[40:43], v[168:171], v[214:217], v[40:43]
	v_mfma_f32_16x16x32_bf16 v[28:31], v[160:163], v[222:225], v[28:31]
	v_mfma_f32_16x16x32_bf16 v[24:27], v[168:171], v[222:225], v[24:27]
	v_mfma_f32_16x16x32_bf16 v[12:15], v[160:163], v[230:233], v[12:15]
	v_mfma_f32_16x16x32_bf16 v[8:11], v[168:171], v[230:233], v[8:11]
	s_setprio 0
	s_setprio 1
	v_mfma_f32_16x16x32_bf16 v[52:55], v[172:175], v[194:197], v[52:55]
	v_mfma_f32_16x16x32_bf16 v[48:51], v[180:183], v[194:197], v[48:51]
	v_mfma_f32_16x16x32_bf16 v[36:39], v[172:175], v[210:213], v[36:39]
	v_mfma_f32_16x16x32_bf16 v[32:35], v[180:183], v[210:213], v[32:35]
	v_mfma_f32_16x16x32_bf16 v[20:23], v[172:175], v[218:221], v[20:23]
	v_mfma_f32_16x16x32_bf16 v[16:19], v[180:183], v[218:221], v[16:19]
	v_mfma_f32_16x16x32_bf16 v[4:7], v[172:175], v[226:229], v[4:7]
	v_mfma_f32_16x16x32_bf16 v[0:3], v[180:183], v[226:229], v[0:3]
	v_mfma_f32_16x16x32_bf16 v[52:55], v[176:179], v[206:209], v[52:55]
	v_mfma_f32_16x16x32_bf16 v[48:51], v[184:187], v[206:209], v[48:51]
	v_mfma_f32_16x16x32_bf16 v[36:39], v[176:179], v[214:217], v[36:39]
	v_mfma_f32_16x16x32_bf16 v[32:35], v[184:187], v[214:217], v[32:35]
	v_mfma_f32_16x16x32_bf16 v[20:23], v[176:179], v[222:225], v[20:23]
	v_mfma_f32_16x16x32_bf16 v[16:19], v[184:187], v[222:225], v[16:19]
	v_mfma_f32_16x16x32_bf16 v[4:7], v[176:179], v[230:233], v[4:7]
	v_mfma_f32_16x16x32_bf16 v[0:3], v[184:187], v[230:233], v[0:3]
	s_setprio 0
	s_barrier
	s_add_i32 s62, 0, 0x18000
	v_add_u32_e32 v159, s62, v151
	s_add_i32 s63, 0, 0x1c000
	ds_read_b128 v[146:149], v159
	ds_read_b128 v[160:163], v159 offset:1024
	ds_read_b128 v[164:167], v159 offset:2048
	ds_read_b128 v[168:171], v159 offset:3072
	v_add_u32_e32 v159, s63, v151
	ds_read_b128 v[172:175], v159
	ds_read_b128 v[176:179], v159 offset:1024
	ds_read_b128 v[180:183], v159 offset:2048
	ds_read_b128 v[184:187], v159 offset:3072
	s_add_u32 s36, s36, 0x40000
	s_addc_u32 s37, s37, 0
	s_mov_b32 m0, s33
	v_lshl_add_u64 v[240:241], s[36:37], 0, v[128:129]
	ds_read_b128 v[194:197], v155 offset:32768
	ds_read_b128 v[206:209], v155 offset:33792
	ds_read_b128 v[210:213], v155 offset:34816
	ds_read_b128 v[214:217], v155 offset:35840
	ds_read_b128 v[218:221], v155 offset:36864
	ds_read_b128 v[222:225], v155 offset:37888
	ds_read_b128 v[226:229], v155 offset:38912
	ds_read_b128 v[230:233], v155 offset:39936
	global_load_lds_dwordx4 v[240:241], off
	v_lshl_add_u64 v[240:241], s[36:37], 0, v[132:133]
	s_mov_b32 m0, s38
	s_nop 0
	global_load_lds_dwordx4 v[240:241], off
	s_waitcnt vmcnt(8)
	s_waitcnt lgkmcnt(0)
	s_barrier
	s_setprio 1
	s_waitcnt lgkmcnt(0)
	v_mfma_f32_16x16x32_bf16 v[124:127], v[146:149], v[194:197], v[124:127]
	v_mfma_f32_16x16x32_bf16 v[120:123], v[164:167], v[194:197], v[120:123]
	v_mfma_f32_16x16x32_bf16 v[108:111], v[146:149], v[210:213], v[108:111]
	v_mfma_f32_16x16x32_bf16 v[104:107], v[164:167], v[210:213], v[104:107]
	v_mfma_f32_16x16x32_bf16 v[92:95], v[146:149], v[218:221], v[92:95]
	v_mfma_f32_16x16x32_bf16 v[88:91], v[164:167], v[218:221], v[88:91]
	v_mfma_f32_16x16x32_bf16 v[76:79], v[146:149], v[226:229], v[76:79]
	v_mfma_f32_16x16x32_bf16 v[72:75], v[164:167], v[226:229], v[72:75]
	v_mfma_f32_16x16x32_bf16 v[124:127], v[160:163], v[206:209], v[124:127]
	v_mfma_f32_16x16x32_bf16 v[120:123], v[168:171], v[206:209], v[120:123]
	v_mfma_f32_16x16x32_bf16 v[108:111], v[160:163], v[214:217], v[108:111]
	v_mfma_f32_16x16x32_bf16 v[104:107], v[168:171], v[214:217], v[104:107]
	v_mfma_f32_16x16x32_bf16 v[92:95], v[160:163], v[222:225], v[92:95]
	v_mfma_f32_16x16x32_bf16 v[88:91], v[168:171], v[222:225], v[88:91]
	v_mfma_f32_16x16x32_bf16 v[76:79], v[160:163], v[230:233], v[76:79]
	v_mfma_f32_16x16x32_bf16 v[72:75], v[168:171], v[230:233], v[72:75]
	s_setprio 0
	s_setprio 1
	v_mfma_f32_16x16x32_bf16 v[116:119], v[172:175], v[194:197], v[116:119]
	v_mfma_f32_16x16x32_bf16 v[112:115], v[180:183], v[194:197], v[112:115]
	v_mfma_f32_16x16x32_bf16 v[100:103], v[172:175], v[210:213], v[100:103]
	v_mfma_f32_16x16x32_bf16 v[96:99], v[180:183], v[210:213], v[96:99]
	v_mfma_f32_16x16x32_bf16 v[84:87], v[172:175], v[218:221], v[84:87]
	v_mfma_f32_16x16x32_bf16 v[80:83], v[180:183], v[218:221], v[80:83]
	v_mfma_f32_16x16x32_bf16 v[68:71], v[172:175], v[226:229], v[68:71]
	v_mfma_f32_16x16x32_bf16 v[64:67], v[180:183], v[226:229], v[64:67]
	v_mfma_f32_16x16x32_bf16 v[116:119], v[176:179], v[206:209], v[116:119]
	v_mfma_f32_16x16x32_bf16 v[112:115], v[184:187], v[206:209], v[112:115]
	v_mfma_f32_16x16x32_bf16 v[100:103], v[176:179], v[214:217], v[100:103]
	v_mfma_f32_16x16x32_bf16 v[96:99], v[184:187], v[214:217], v[96:99]
	v_mfma_f32_16x16x32_bf16 v[84:87], v[176:179], v[222:225], v[84:87]
	v_mfma_f32_16x16x32_bf16 v[80:83], v[184:187], v[222:225], v[80:83]
	v_mfma_f32_16x16x32_bf16 v[68:71], v[176:179], v[230:233], v[68:71]
	v_mfma_f32_16x16x32_bf16 v[64:67], v[184:187], v[230:233], v[64:67]
	s_setprio 0
	s_barrier
	s_add_i32 s36, s62, s29
	v_lshl_add_u64 v[188:189], v[188:189], 0, s[12:13]
	s_mov_b32 m0, s36
	ds_read_b128 v[194:197], v155 offset:49152
	ds_read_b128 v[206:209], v155 offset:50176
	ds_read_b128 v[210:213], v155 offset:51200
	ds_read_b128 v[214:217], v155 offset:52224
	ds_read_b128 v[218:221], v155 offset:53248
	ds_read_b128 v[222:225], v155 offset:54272
	ds_read_b128 v[226:229], v155 offset:55296
	ds_read_b128 v[230:233], v155 offset:56320
	global_load_lds_dwordx4 v[188:189], off
	s_add_i32 m0, s36, 0x2000
	s_add_u32 s34, s34, 0x40080
	v_lshl_add_u64 v[188:189], v[234:235], 0, s[12:13]
	s_addc_u32 s35, s35, 0
	s_add_i32 s36, s63, s29
	global_load_lds_dwordx4 v[188:189], off
	v_lshl_add_u64 v[188:189], s[34:35], 0, v[130:131]
	s_mov_b32 m0, s36
	s_nop 0
	global_load_lds_dwordx4 v[188:189], off
	v_lshl_add_u64 v[188:189], s[34:35], 0, v[134:135]
	s_add_i32 m0, s36, 0x2000
	s_nop 0
	global_load_lds_dwordx4 v[188:189], off
	v_lshl_add_u64 v[188:189], v[236:237], 0, s[12:13]
	s_mov_b32 m0, s40
	s_nop 0
	global_load_lds_dwordx4 v[188:189], off
	v_lshl_add_u64 v[188:189], v[238:239], 0, s[12:13]
	s_mov_b32 m0, s41
	s_nop 0
	global_load_lds_dwordx4 v[188:189], off
	s_waitcnt vmcnt(8)
	s_waitcnt lgkmcnt(0)
	s_barrier
	s_setprio 1
	s_waitcnt lgkmcnt(0)
	v_mfma_f32_16x16x32_bf16 v[60:63], v[146:149], v[194:197], v[60:63]
	v_mfma_f32_16x16x32_bf16 v[56:59], v[164:167], v[194:197], v[56:59]
	v_mfma_f32_16x16x32_bf16 v[44:47], v[146:149], v[210:213], v[44:47]
	v_mfma_f32_16x16x32_bf16 v[40:43], v[164:167], v[210:213], v[40:43]
	v_mfma_f32_16x16x32_bf16 v[28:31], v[146:149], v[218:221], v[28:31]
	v_mfma_f32_16x16x32_bf16 v[24:27], v[164:167], v[218:221], v[24:27]
	v_mfma_f32_16x16x32_bf16 v[12:15], v[146:149], v[226:229], v[12:15]
	v_mfma_f32_16x16x32_bf16 v[8:11], v[164:167], v[226:229], v[8:11]
	v_mfma_f32_16x16x32_bf16 v[60:63], v[160:163], v[206:209], v[60:63]
	v_mfma_f32_16x16x32_bf16 v[56:59], v[168:171], v[206:209], v[56:59]
	v_mfma_f32_16x16x32_bf16 v[44:47], v[160:163], v[214:217], v[44:47]
	v_mfma_f32_16x16x32_bf16 v[40:43], v[168:171], v[214:217], v[40:43]
	v_mfma_f32_16x16x32_bf16 v[28:31], v[160:163], v[222:225], v[28:31]
	v_mfma_f32_16x16x32_bf16 v[24:27], v[168:171], v[222:225], v[24:27]
	v_mfma_f32_16x16x32_bf16 v[12:15], v[160:163], v[230:233], v[12:15]
	v_mfma_f32_16x16x32_bf16 v[8:11], v[168:171], v[230:233], v[8:11]
	s_setprio 0
	s_setprio 1
	v_mfma_f32_16x16x32_bf16 v[52:55], v[172:175], v[194:197], v[52:55]
	v_mfma_f32_16x16x32_bf16 v[48:51], v[180:183], v[194:197], v[48:51]
	v_mfma_f32_16x16x32_bf16 v[36:39], v[172:175], v[210:213], v[36:39]
	v_mfma_f32_16x16x32_bf16 v[32:35], v[180:183], v[210:213], v[32:35]
	v_mfma_f32_16x16x32_bf16 v[20:23], v[172:175], v[218:221], v[20:23]
	v_mfma_f32_16x16x32_bf16 v[16:19], v[180:183], v[218:221], v[16:19]
	v_mfma_f32_16x16x32_bf16 v[4:7], v[172:175], v[226:229], v[4:7]
	v_mfma_f32_16x16x32_bf16 v[0:3], v[180:183], v[226:229], v[0:3]
	v_mfma_f32_16x16x32_bf16 v[52:55], v[176:179], v[206:209], v[52:55]
	v_mfma_f32_16x16x32_bf16 v[48:51], v[184:187], v[206:209], v[48:51]
	v_mfma_f32_16x16x32_bf16 v[36:39], v[176:179], v[214:217], v[36:39]
	v_mfma_f32_16x16x32_bf16 v[32:35], v[184:187], v[214:217], v[32:35]
	v_mfma_f32_16x16x32_bf16 v[20:23], v[176:179], v[222:225], v[20:23]
	v_mfma_f32_16x16x32_bf16 v[16:19], v[184:187], v[222:225], v[16:19]
	v_mfma_f32_16x16x32_bf16 v[4:7], v[176:179], v[230:233], v[4:7]
	v_mfma_f32_16x16x32_bf16 v[0:3], v[184:187], v[230:233], v[0:3]
	s_setprio 0
	s_barrier
	s_add_i32 s51, s51, 2
	s_add_u32 s26, s26, 0x100
	s_addc_u32 s27, s27, 0
	s_add_u32 s49, s49, 0x100
	s_addc_u32 s50, s50, 0
	s_cmp_gt_u32 s51, 13
	s_cbranch_scc0 .LBB0_776
	s_and_b64 vcc, exec, s[14:15]
	s_cbranch_vccz .LBB0_779
	s_barrier

.LBB0_843:
	s_add_u32 s14, s56, 0x600000
	s_mov_b64 s[18:19], 0x80
	s_addc_u32 s15, s57, 0
	s_and_b32 s44, s1, 3
	s_add_i32 m0, s29, 0x18000
	v_lshl_add_u64 v[6:7], v[6:7], 0, s[18:19]
	s_lshl_b32 s1, s0, 13
	s_lshl_b32 s21, s44, 12
	s_ashr_i32 s45, s2, 31
	s_waitcnt vmcnt(2)
	s_barrier
	global_load_lds_dwordx4 v[6:7], off
	v_lshl_add_u64 v[4:5], v[4:5], 0, s[18:19]
	s_add_i32 m0, s29, 0x1a000
	s_add_i32 s46, s29, 0x8000
	s_add_i32 s47, s29, 0xa000
	global_load_lds_dwordx4 v[4:5], off
	v_lshl_add_u64 v[0:1], v[0:1], 0, s[18:19]
	s_mov_b32 m0, s46
	s_add_u32 s4, s40, 0x100080
	global_load_lds_dwordx4 v[0:1], off
	v_lshl_add_u64 v[0:1], v[2:3], 0, s[18:19]
	s_mov_b32 m0, s47
	s_addc_u32 s5, s41, 0
	global_load_lds_dwordx4 v[0:1], off
	s_add_i32 m0, s29, 0x1c000
	v_lshl_add_u64 v[0:1], s[4:5], 0, v[130:131]
	global_load_lds_dwordx4 v[0:1], off
	v_lshl_add_u64 v[0:1], s[4:5], 0, v[134:135]
	s_add_i32 m0, s29, 0x1e000
	v_lshlrev_b32_e32 v4, 2, v192
	global_load_lds_dwordx4 v[0:1], off
	v_bfe_u32 v0, v192, 4, 2
	v_and_b32_e32 v1, 15, v192
	v_lshlrev_b32_e32 v3, 4, v0
	v_lshl_or_b32 v148, s0, 6, v1
	v_lshl_or_b32 v1, v1, 6, v3
	v_and_b32_e32 v4, 32, v4
	v_lshlrev_b32_e32 v5, 6, v192
	s_movk_i32 s0, 0x3c0
	v_lshlrev_b32_e32 v2, 3, v0
	v_bitop3_b32 v1, v1, s1, v4 bitop3:0xde
	v_and_or_b32 v3, v5, s0, v3
	v_cmp_eq_u32_e64 s[0:1], 0, v0
	v_lshlrev_b32_e32 v0, 10, v192
	v_lshl_or_b32 v150, s44, 6, v2
	v_and_b32_e32 v0, 0xe0000, v0
	v_lshlrev_b32_e32 v2, 13, v10
	v_or3_b32 v0, v8, v0, v2
	v_add_u32_e32 v136, v0, v9
	v_lshlrev_b32_e32 v0, 6, v11
	v_and_b32_e32 v0, 0x1e0000, v0
	s_waitcnt vmcnt(6)
	s_cmpk_lt_u32 s20, 0x100
	v_or3_b32 v0, v8, v0, v2
	v_bitop3_b32 v149, s21, v3, v4 bitop3:0xf6
	s_cselect_b64 s[20:21], -1, 0
	v_add_u32_e32 v138, v0, v9
	s_add_i32 s50, 0, 0x10000
	s_add_i32 s51, 0, 0x14000
	v_mbcnt_lo_u32_b32 v0, -1, 0
	s_ashr_i32 s48, s60, 31
	s_mov_b32 s49, s60
	v_mov_b32_e32 v137, v131
	v_mov_b32_e32 v139, v131
	v_mov_b64_e32 v[140:141], 0x200
	v_mov_b64_e32 v[142:143], 0x1ff
	v_add_u32_e32 v151, s50, v149
	v_add_u32_e32 v152, s51, v149
	v_add_u32_e32 v153, 0, v1
	v_mbcnt_hi_u32_b32 v154, -1, v0
	s_mov_b32 s62, 0
	s_barrier
	s_branch .LBB0_846

.LBB0_853:
	s_cmp_eq_u32 s66, -2
	s_cselect_b32 s100, s101, 0
	ds_read_b128 v[144:147], v151
	ds_read_b128 v[156:159], v151 offset:1024
	ds_read_b128 v[160:163], v151 offset:2048
	ds_read_b128 v[164:167], v151 offset:3072
	ds_read_b128 v[168:171], v152
	ds_read_b128 v[172:175], v152 offset:1024
	ds_read_b128 v[176:179], v152 offset:2048
	ds_read_b128 v[180:183], v152 offset:3072
	s_add_u32 s40, s38, 0xfff00080
	s_addc_u32 s41, s39, -1
	s_cmp_eq_u32 s66, 60
	s_cselect_b32 s43, s23, s41
	s_cselect_b32 s42, s37, s40
	s_cselect_b32 s41, s25, s65
	s_cselect_b32 s40, s63, s64
	v_lshl_add_u64 v[188:189], s[38:39], 0, v[136:137]
	s_add_i32 m0, s29, 0xc000
	ds_read_b128 v[184:187], v153
	ds_read_b128 v[194:197], v153 offset:1024
	ds_read_b128 v[206:209], v153 offset:2048
	ds_read_b128 v[210:213], v153 offset:3072
	ds_read_b128 v[214:217], v153 offset:4096
	ds_read_b128 v[218:221], v153 offset:5120
	ds_read_b128 v[222:225], v153 offset:6144
	ds_read_b128 v[226:229], v153 offset:7168
	global_load_lds_dwordx4 v[188:189], off
	v_lshl_add_u64 v[188:189], s[38:39], 0, v[138:139]
	s_add_i32 m0, s29, 0xe000
	s_nop 0
	global_load_lds_dwordx4 v[188:189], off
	s_cmp_lg_u32 s100, 0
	s_cbranch_scc1 .Lrw_g4_0
	s_waitcnt vmcnt(8)
.Lrw_g4_0:
	s_waitcnt lgkmcnt(0)
	s_barrier
	s_setprio 1
	s_waitcnt lgkmcnt(0)
	v_mfma_f32_16x16x32_bf16 v[124:127], v[144:147], v[184:187], v[124:127]
	v_mfma_f32_16x16x32_bf16 v[120:123], v[160:163], v[184:187], v[120:123]
	v_mfma_f32_16x16x32_bf16 v[108:111], v[144:147], v[206:209], v[108:111]
	v_mfma_f32_16x16x32_bf16 v[104:107], v[160:163], v[206:209], v[104:107]
	v_mfma_f32_16x16x32_bf16 v[92:95], v[144:147], v[214:217], v[92:95]
	v_mfma_f32_16x16x32_bf16 v[88:91], v[160:163], v[214:217], v[88:91]
	v_mfma_f32_16x16x32_bf16 v[76:79], v[144:147], v[222:225], v[76:79]
	v_mfma_f32_16x16x32_bf16 v[72:75], v[160:163], v[222:225], v[72:75]
	v_mfma_f32_16x16x32_bf16 v[124:127], v[156:159], v[194:197], v[124:127]
	v_mfma_f32_16x16x32_bf16 v[120:123], v[164:167], v[194:197], v[120:123]
	v_mfma_f32_16x16x32_bf16 v[108:111], v[156:159], v[210:213], v[108:111]
	v_mfma_f32_16x16x32_bf16 v[104:107], v[164:167], v[210:213], v[104:107]
	v_mfma_f32_16x16x32_bf16 v[92:95], v[156:159], v[218:221], v[92:95]
	v_mfma_f32_16x16x32_bf16 v[88:91], v[164:167], v[218:221], v[88:91]
	v_mfma_f32_16x16x32_bf16 v[76:79], v[156:159], v[226:229], v[76:79]
	v_mfma_f32_16x16x32_bf16 v[72:75], v[164:167], v[226:229], v[72:75]
	s_setprio 0
	s_setprio 1
	v_mfma_f32_16x16x32_bf16 v[116:119], v[168:171], v[184:187], v[116:119]
	v_mfma_f32_16x16x32_bf16 v[112:115], v[176:179], v[184:187], v[112:115]
	v_mfma_f32_16x16x32_bf16 v[100:103], v[168:171], v[206:209], v[100:103]
	v_mfma_f32_16x16x32_bf16 v[96:99], v[176:179], v[206:209], v[96:99]
	v_mfma_f32_16x16x32_bf16 v[84:87], v[168:171], v[214:217], v[84:87]
	v_mfma_f32_16x16x32_bf16 v[80:83], v[176:179], v[214:217], v[80:83]
	v_mfma_f32_16x16x32_bf16 v[68:71], v[168:171], v[222:225], v[68:71]
	v_mfma_f32_16x16x32_bf16 v[64:67], v[176:179], v[222:225], v[64:67]
	v_mfma_f32_16x16x32_bf16 v[116:119], v[172:175], v[194:197], v[116:119]
	v_mfma_f32_16x16x32_bf16 v[112:115], v[180:183], v[194:197], v[112:115]
	v_mfma_f32_16x16x32_bf16 v[100:103], v[172:175], v[210:213], v[100:103]
	v_mfma_f32_16x16x32_bf16 v[96:99], v[180:183], v[210:213], v[96:99]
	v_mfma_f32_16x16x32_bf16 v[84:87], v[172:175], v[218:221], v[84:87]
	v_mfma_f32_16x16x32_bf16 v[80:83], v[180:183], v[218:221], v[80:83]
	v_mfma_f32_16x16x32_bf16 v[68:71], v[172:175], v[226:229], v[68:71]
	v_mfma_f32_16x16x32_bf16 v[64:67], v[180:183], v[226:229], v[64:67]
	s_setprio 0
	s_barrier
	s_add_i32 s67, s50, s3
	v_lshl_add_u64 v[188:189], s[40:41], 0, v[130:131]
	s_mov_b32 m0, s67
	ds_read_b128 v[184:187], v153 offset:16384
	ds_read_b128 v[194:197], v153 offset:17408
	ds_read_b128 v[206:209], v153 offset:18432
	ds_read_b128 v[210:213], v153 offset:19456
	ds_read_b128 v[214:217], v153 offset:20480
	ds_read_b128 v[218:221], v153 offset:21504
	ds_read_b128 v[222:225], v153 offset:22528
	ds_read_b128 v[226:229], v153 offset:23552
	global_load_lds_dwordx4 v[188:189], off
	s_add_i32 m0, s67, 0x2000
	s_add_u32 s68, s40, 0x100000
	v_lshl_add_u64 v[230:231], s[40:41], 0, v[134:135]
	s_addc_u32 s69, s41, 0
	s_add_i32 s67, s51, s3
	global_load_lds_dwordx4 v[230:231], off
	v_lshl_add_u64 v[232:233], s[68:69], 0, v[130:131]
	s_mov_b32 m0, s67
	v_lshl_add_u64 v[234:235], s[42:43], 0, v[132:133]
	global_load_lds_dwordx4 v[232:233], off
	v_lshl_add_u64 v[232:233], s[68:69], 0, v[134:135]
	s_add_i32 m0, s67, 0x2000
	s_nop 0
	global_load_lds_dwordx4 v[232:233], off
	v_lshl_add_u64 v[232:233], s[42:43], 0, v[128:129]
	s_mov_b32 m0, s29
	s_nop 0
	global_load_lds_dwordx4 v[232:233], off
	s_mov_b32 m0, s30
	s_nop 0
	global_load_lds_dwordx4 v[234:235], off
	s_cmp_lg_u32 s100, 0
	s_cbranch_scc1 .Lrw_g4_1
	s_waitcnt vmcnt(8)
.Lrw_g4_1:
	s_waitcnt lgkmcnt(0)
	s_barrier
	s_setprio 1
	s_waitcnt lgkmcnt(0)
	v_mfma_f32_16x16x32_bf16 v[60:63], v[144:147], v[184:187], v[60:63]
	v_mfma_f32_16x16x32_bf16 v[56:59], v[160:163], v[184:187], v[56:59]
	v_mfma_f32_16x16x32_bf16 v[44:47], v[144:147], v[206:209], v[44:47]
	v_mfma_f32_16x16x32_bf16 v[40:43], v[160:163], v[206:209], v[40:43]
	v_mfma_f32_16x16x32_bf16 v[28:31], v[144:147], v[214:217], v[28:31]
	v_mfma_f32_16x16x32_bf16 v[24:27], v[160:163], v[214:217], v[24:27]
	v_mfma_f32_16x16x32_bf16 v[12:15], v[144:147], v[222:225], v[12:15]
	v_mfma_f32_16x16x32_bf16 v[8:11], v[160:163], v[222:225], v[8:11]
	v_mfma_f32_16x16x32_bf16 v[60:63], v[156:159], v[194:197], v[60:63]
	v_mfma_f32_16x16x32_bf16 v[56:59], v[164:167], v[194:197], v[56:59]
	v_mfma_f32_16x16x32_bf16 v[44:47], v[156:159], v[210:213], v[44:47]
	v_mfma_f32_16x16x32_bf16 v[40:43], v[164:167], v[210:213], v[40:43]
	v_mfma_f32_16x16x32_bf16 v[28:31], v[156:159], v[218:221], v[28:31]
	v_mfma_f32_16x16x32_bf16 v[24:27], v[164:167], v[218:221], v[24:27]
	v_mfma_f32_16x16x32_bf16 v[12:15], v[156:159], v[226:229], v[12:15]
	v_mfma_f32_16x16x32_bf16 v[8:11], v[164:167], v[226:229], v[8:11]
	s_setprio 0
	s_setprio 1
	v_mfma_f32_16x16x32_bf16 v[52:55], v[168:171], v[184:187], v[52:55]
	v_mfma_f32_16x16x32_bf16 v[48:51], v[176:179], v[184:187], v[48:51]
	v_mfma_f32_16x16x32_bf16 v[36:39], v[168:171], v[206:209], v[36:39]
	v_mfma_f32_16x16x32_bf16 v[32:35], v[176:179], v[206:209], v[32:35]
	v_mfma_f32_16x16x32_bf16 v[20:23], v[168:171], v[214:217], v[20:23]
	v_mfma_f32_16x16x32_bf16 v[16:19], v[176:179], v[214:217], v[16:19]
	v_mfma_f32_16x16x32_bf16 v[4:7], v[168:171], v[222:225], v[4:7]
	v_mfma_f32_16x16x32_bf16 v[0:3], v[176:179], v[222:225], v[0:3]
	v_mfma_f32_16x16x32_bf16 v[52:55], v[172:175], v[194:197], v[52:55]
	v_mfma_f32_16x16x32_bf16 v[48:51], v[180:183], v[194:197], v[48:51]
	v_mfma_f32_16x16x32_bf16 v[36:39], v[172:175], v[210:213], v[36:39]
	v_mfma_f32_16x16x32_bf16 v[32:35], v[180:183], v[210:213], v[32:35]
	v_mfma_f32_16x16x32_bf16 v[20:23], v[172:175], v[218:221], v[20:23]
	v_mfma_f32_16x16x32_bf16 v[16:19], v[180:183], v[218:221], v[16:19]
	v_mfma_f32_16x16x32_bf16 v[4:7], v[172:175], v[226:229], v[4:7]
	v_mfma_f32_16x16x32_bf16 v[0:3], v[180:183], v[226:229], v[0:3]
	s_setprio 0
	s_barrier
	s_add_i32 s67, 0, 0x18000
	v_add_u32_e32 v155, s67, v149
	s_add_i32 s68, 0, 0x1c000
	ds_read_b128 v[144:147], v155
	ds_read_b128 v[156:159], v155 offset:1024
	ds_read_b128 v[160:163], v155 offset:2048
	ds_read_b128 v[164:167], v155 offset:3072
	v_add_u32_e32 v155, s68, v149
	ds_read_b128 v[168:171], v155
	ds_read_b128 v[172:175], v155 offset:1024
	ds_read_b128 v[176:179], v155 offset:2048
	ds_read_b128 v[180:183], v155 offset:3072
	s_add_u32 s42, s42, 0x100000
	s_addc_u32 s43, s43, 0
	s_mov_b32 m0, s31
	v_lshl_add_u64 v[236:237], s[42:43], 0, v[128:129]
	ds_read_b128 v[184:187], v153 offset:32768
	ds_read_b128 v[194:197], v153 offset:33792
	ds_read_b128 v[206:209], v153 offset:34816
	ds_read_b128 v[210:213], v153 offset:35840
	ds_read_b128 v[214:217], v153 offset:36864
	ds_read_b128 v[218:221], v153 offset:37888
	ds_read_b128 v[222:225], v153 offset:38912
	ds_read_b128 v[226:229], v153 offset:39936
	global_load_lds_dwordx4 v[236:237], off
	v_lshl_add_u64 v[236:237], s[42:43], 0, v[132:133]
	s_mov_b32 m0, s33
	s_nop 0
	global_load_lds_dwordx4 v[236:237], off
	s_waitcnt vmcnt(8)
	s_waitcnt lgkmcnt(0)
	s_barrier
	s_setprio 1
	s_waitcnt lgkmcnt(0)
	v_mfma_f32_16x16x32_bf16 v[124:127], v[144:147], v[184:187], v[124:127]
	v_mfma_f32_16x16x32_bf16 v[120:123], v[160:163], v[184:187], v[120:123]
	v_mfma_f32_16x16x32_bf16 v[108:111], v[144:147], v[206:209], v[108:111]
	v_mfma_f32_16x16x32_bf16 v[104:107], v[160:163], v[206:209], v[104:107]
	v_mfma_f32_16x16x32_bf16 v[92:95], v[144:147], v[214:217], v[92:95]
	v_mfma_f32_16x16x32_bf16 v[88:91], v[160:163], v[214:217], v[88:91]
	v_mfma_f32_16x16x32_bf16 v[76:79], v[144:147], v[222:225], v[76:79]
	v_mfma_f32_16x16x32_bf16 v[72:75], v[160:163], v[222:225], v[72:75]
	v_mfma_f32_16x16x32_bf16 v[124:127], v[156:159], v[194:197], v[124:127]
	v_mfma_f32_16x16x32_bf16 v[120:123], v[164:167], v[194:197], v[120:123]
	v_mfma_f32_16x16x32_bf16 v[108:111], v[156:159], v[210:213], v[108:111]
	v_mfma_f32_16x16x32_bf16 v[104:107], v[164:167], v[210:213], v[104:107]
	v_mfma_f32_16x16x32_bf16 v[92:95], v[156:159], v[218:221], v[92:95]
	v_mfma_f32_16x16x32_bf16 v[88:91], v[164:167], v[218:221], v[88:91]
	v_mfma_f32_16x16x32_bf16 v[76:79], v[156:159], v[226:229], v[76:79]
	v_mfma_f32_16x16x32_bf16 v[72:75], v[164:167], v[226:229], v[72:75]
	s_setprio 0
	s_setprio 1
	v_mfma_f32_16x16x32_bf16 v[116:119], v[168:171], v[184:187], v[116:119]
	v_mfma_f32_16x16x32_bf16 v[112:115], v[176:179], v[184:187], v[112:115]
	v_mfma_f32_16x16x32_bf16 v[100:103], v[168:171], v[206:209], v[100:103]
	v_mfma_f32_16x16x32_bf16 v[96:99], v[176:179], v[206:209], v[96:99]
	v_mfma_f32_16x16x32_bf16 v[84:87], v[168:171], v[214:217], v[84:87]
	v_mfma_f32_16x16x32_bf16 v[80:83], v[176:179], v[214:217], v[80:83]
	v_mfma_f32_16x16x32_bf16 v[68:71], v[168:171], v[222:225], v[68:71]
	v_mfma_f32_16x16x32_bf16 v[64:67], v[176:179], v[222:225], v[64:67]
	v_mfma_f32_16x16x32_bf16 v[116:119], v[172:175], v[194:197], v[116:119]
	v_mfma_f32_16x16x32_bf16 v[112:115], v[180:183], v[194:197], v[112:115]
	v_mfma_f32_16x16x32_bf16 v[100:103], v[172:175], v[210:213], v[100:103]
	v_mfma_f32_16x16x32_bf16 v[96:99], v[180:183], v[210:213], v[96:99]
	v_mfma_f32_16x16x32_bf16 v[84:87], v[172:175], v[218:221], v[84:87]
	v_mfma_f32_16x16x32_bf16 v[80:83], v[180:183], v[218:221], v[80:83]
	v_mfma_f32_16x16x32_bf16 v[68:71], v[172:175], v[226:229], v[68:71]
	v_mfma_f32_16x16x32_bf16 v[64:67], v[180:183], v[226:229], v[64:67]
	s_setprio 0
	s_barrier
	s_add_i32 s42, s67, s3
	v_lshl_add_u64 v[188:189], v[188:189], 0, s[18:19]
	s_mov_b32 m0, s42
	ds_read_b128 v[184:187], v153 offset:49152
	ds_read_b128 v[194:197], v153 offset:50176
	ds_read_b128 v[206:209], v153 offset:51200
	ds_read_b128 v[210:213], v153 offset:52224
	ds_read_b128 v[214:217], v153 offset:53248
	ds_read_b128 v[218:221], v153 offset:54272
	ds_read_b128 v[222:225], v153 offset:55296
	ds_read_b128 v[226:229], v153 offset:56320
	global_load_lds_dwordx4 v[188:189], off
	s_add_i32 m0, s42, 0x2000
	s_add_u32 s40, s40, 0x100080
	v_lshl_add_u64 v[188:189], v[230:231], 0, s[18:19]
	s_addc_u32 s41, s41, 0
	s_add_i32 s42, s68, s3
	global_load_lds_dwordx4 v[188:189], off
	v_lshl_add_u64 v[188:189], s[40:41], 0, v[130:131]
	s_mov_b32 m0, s42
	s_nop 0
	global_load_lds_dwordx4 v[188:189], off
	v_lshl_add_u64 v[188:189], s[40:41], 0, v[134:135]
	s_add_i32 m0, s42, 0x2000
	s_nop 0
	global_load_lds_dwordx4 v[188:189], off
	v_lshl_add_u64 v[188:189], v[232:233], 0, s[18:19]
	s_mov_b32 m0, s46
	s_nop 0
	global_load_lds_dwordx4 v[188:189], off
	v_lshl_add_u64 v[188:189], v[234:235], 0, s[18:19]
	s_mov_b32 m0, s47
	s_nop 0
	global_load_lds_dwordx4 v[188:189], off
	s_waitcnt vmcnt(8)
	s_waitcnt lgkmcnt(0)
	s_barrier
	s_setprio 1
	s_waitcnt lgkmcnt(0)
	v_mfma_f32_16x16x32_bf16 v[60:63], v[144:147], v[184:187], v[60:63]
	v_mfma_f32_16x16x32_bf16 v[56:59], v[160:163], v[184:187], v[56:59]
	v_mfma_f32_16x16x32_bf16 v[44:47], v[144:147], v[206:209], v[44:47]
	v_mfma_f32_16x16x32_bf16 v[40:43], v[160:163], v[206:209], v[40:43]
	v_mfma_f32_16x16x32_bf16 v[28:31], v[144:147], v[214:217], v[28:31]
	v_mfma_f32_16x16x32_bf16 v[24:27], v[160:163], v[214:217], v[24:27]
	v_mfma_f32_16x16x32_bf16 v[12:15], v[144:147], v[222:225], v[12:15]
	v_mfma_f32_16x16x32_bf16 v[8:11], v[160:163], v[222:225], v[8:11]
	v_mfma_f32_16x16x32_bf16 v[60:63], v[156:159], v[194:197], v[60:63]
	v_mfma_f32_16x16x32_bf16 v[56:59], v[164:167], v[194:197], v[56:59]
	v_mfma_f32_16x16x32_bf16 v[44:47], v[156:159], v[210:213], v[44:47]
	v_mfma_f32_16x16x32_bf16 v[40:43], v[164:167], v[210:213], v[40:43]
	v_mfma_f32_16x16x32_bf16 v[28:31], v[156:159], v[218:221], v[28:31]
	v_mfma_f32_16x16x32_bf16 v[24:27], v[164:167], v[218:221], v[24:27]
	v_mfma_f32_16x16x32_bf16 v[12:15], v[156:159], v[226:229], v[12:15]
	v_mfma_f32_16x16x32_bf16 v[8:11], v[164:167], v[226:229], v[8:11]
	s_setprio 0
	s_setprio 1
	v_mfma_f32_16x16x32_bf16 v[52:55], v[168:171], v[184:187], v[52:55]
	v_mfma_f32_16x16x32_bf16 v[48:51], v[176:179], v[184:187], v[48:51]
	v_mfma_f32_16x16x32_bf16 v[36:39], v[168:171], v[206:209], v[36:39]
	v_mfma_f32_16x16x32_bf16 v[32:35], v[176:179], v[206:209], v[32:35]
	v_mfma_f32_16x16x32_bf16 v[20:23], v[168:171], v[214:217], v[20:23]
	v_mfma_f32_16x16x32_bf16 v[16:19], v[176:179], v[214:217], v[16:19]
	v_mfma_f32_16x16x32_bf16 v[4:7], v[168:171], v[222:225], v[4:7]
	v_mfma_f32_16x16x32_bf16 v[0:3], v[176:179], v[222:225], v[0:3]
	v_mfma_f32_16x16x32_bf16 v[52:55], v[172:175], v[194:197], v[52:55]
	v_mfma_f32_16x16x32_bf16 v[48:51], v[180:183], v[194:197], v[48:51]
	v_mfma_f32_16x16x32_bf16 v[36:39], v[172:175], v[210:213], v[36:39]
	v_mfma_f32_16x16x32_bf16 v[32:35], v[180:183], v[210:213], v[32:35]
	v_mfma_f32_16x16x32_bf16 v[20:23], v[172:175], v[218:221], v[20:23]
	v_mfma_f32_16x16x32_bf16 v[16:19], v[180:183], v[218:221], v[16:19]
	v_mfma_f32_16x16x32_bf16 v[4:7], v[172:175], v[226:229], v[4:7]
	v_mfma_f32_16x16x32_bf16 v[0:3], v[180:183], v[226:229], v[0:3]
	s_setprio 0
	s_barrier
	s_add_i32 s66, s66, 2
	s_add_u32 s38, s38, 0x100
	s_addc_u32 s39, s39, 0
	s_add_u32 s64, s64, 0x100
	s_addc_u32 s65, s65, 0
	s_cmp_gt_u32 s66, 61
	s_cbranch_scc0 .LBB0_853
	s_and_b64 vcc, exec, s[20:21]
	s_cbranch_vccz .LBB0_856
	s_barrier

.LBB0_933:
	s_add_i32 s39, s39, 1
	s_cmp_gt_u32 s39, 1
	s_cselect_b32 s101, 1, 0
	s_mul_i32 s0, s39, s44
	s_mul_hi_u32 s1, s39, s45
	s_add_i32 s1, s1, s0
	s_mul_i32 s0, s39, s45
	s_add_u32 s22, s0, s2
	s_addc_u32 s23, s1, s41
	v_cmp_gt_i64_e32 vcc, s[22:23], v[146:147]
	v_cmp_lt_i64_e64 s[0:1], s[22:23], v[144:145]
	s_cbranch_vccnz .LBB0_935
	s_mul_i32 s21, s23, 0xaaaaaaab
	s_mul_hi_u32 s24, s22, 0xaaaaaaab
	s_mul_hi_u32 s20, s23, 0xaaaaaaab
	s_add_u32 s21, s21, s24
	s_mul_i32 s19, s22, 0x2aaaaaaa
	s_addc_u32 s20, s20, 0
	s_mul_hi_u32 s18, s22, 0x2aaaaaaa
	s_add_u32 s19, s19, s21
	s_addc_u32 s18, s18, 0
	s_add_u32 s18, s20, s18
	s_addc_u32 s19, 0, 0
	s_mul_i32 s21, s23, 0x2aaaaaaa
	s_mul_hi_u32 s20, s23, 0x2aaaaaaa
	s_add_u32 s18, s21, s18
	s_addc_u32 s19, s20, s19
	s_ashr_i32 s20, s23, 31
	s_mul_i32 s21, s20, 0x2aaaaaaa
	s_mul_hi_u32 s23, s20, 0xaaaaaaab
	s_add_i32 s21, s23, s21
	s_mul_i32 s20, s20, 0xaaaaaaab
	s_add_i32 s21, s21, s20
	s_add_u32 s18, s18, s20
	s_addc_u32 s19, s19, s21
	s_ashr_i64 s[20:21], s[18:19], 8
	s_lshr_b32 s18, s19, 31
	s_add_u32 s18, s20, s18
	s_mulk_i32 s18, 0x600
	s_sub_i32 s18, s22, s18
	s_sext_i32_i16 s19, s18
	s_bfe_u32 s19, s19, 0x3001c
	s_add_i32 s19, s18, s19
	s_sext_i32_i16 s20, s19
	s_and_b32 s19, s19, 0xfff8
	s_sub_i32 s18, s18, s19
	s_ashr_i32 s20, s20, 3
	s_sext_i32_i16 s19, s18
	s_cmp_lt_i32 s19, 0
	s_cselect_b32 s19, s29, 0xc0
	s_mul_i32 s18, s18, s19
	s_add_i32 s18, s18, s20
	s_sext_i32_i16 s19, s18
	s_mulk_i32 s19, 0x2aab
	s_lshr_b32 s20, s19, 31
	s_ashr_i32 s19, s19, 20
	s_add_i32 s19, s19, s20
	s_lshl_b32 s20, s19, 3
	s_mulk_i32 s19, 0x60
	s_sub_i32 s18, s18, s19
	s_bfe_i32 s19, s18, 0x80000
	s_bfe_u32 s19, s19, 0x3000c
	s_add_i32 s19, s18, s19
	s_bfe_i32 s21, s19, 0x80000
	s_and_b32 s19, s19, 0xf8
	s_sub_i32 s18, s18, s19
	s_sext_i32_i16 s21, s21
	s_sext_i32_i8 s18, s18
	s_add_i32 s18, s20, s18
	s_ashr_i32 s20, s21, 3

.LBB0_936:
	s_cmp_eq_u32 s64, -2
	s_cselect_b32 s100, s101, 0
	ds_read_b128 v[160:163], v152
	ds_read_b128 v[164:167], v152 offset:1024
	ds_read_b128 v[168:171], v152 offset:2048
	ds_read_b128 v[172:175], v152 offset:3072
	ds_read_b128 v[176:179], v153
	ds_read_b128 v[180:183], v153 offset:1024
	ds_read_b128 v[184:187], v153 offset:2048
	ds_read_b128 v[194:197], v153 offset:3072
	s_add_u32 s34, s26, 0xfffc0080
	s_addc_u32 s35, s27, -1
	s_cmp_eq_u32 s64, 12
	s_cselect_b32 s37, s19, s35
	s_cselect_b32 s36, s50, s34
	s_cselect_b32 s35, s21, s63
	s_cselect_b32 s34, s51, s62
	v_lshl_add_u64 v[148:149], s[26:27], 0, v[140:141]
	s_add_i32 m0, s30, 0xc000
	ds_read_b128 v[206:209], v154
	ds_read_b128 v[210:213], v154 offset:1024
	ds_read_b128 v[214:217], v154 offset:2048
	ds_read_b128 v[218:221], v154 offset:3072
	ds_read_b128 v[222:225], v154 offset:4096
	ds_read_b128 v[226:229], v154 offset:5120
	ds_read_b128 v[230:233], v154 offset:6144
	ds_read_b128 v[234:237], v154 offset:7168
	global_load_lds_dwordx4 v[148:149], off
	v_lshl_add_u64 v[148:149], s[26:27], 0, v[142:143]
	s_add_i32 m0, s30, 0xe000
	s_nop 0
	global_load_lds_dwordx4 v[148:149], off
	s_cmp_lg_u32 s100, 0
	s_cbranch_scc1 .Lrw_g5_0
	s_waitcnt vmcnt(8)
.Lrw_g5_0:
	s_waitcnt lgkmcnt(0)
	s_barrier
	s_setprio 1
	s_waitcnt lgkmcnt(0)
	v_mfma_f32_16x16x32_bf16 v[124:127], v[160:163], v[206:209], v[124:127]
	v_mfma_f32_16x16x32_bf16 v[120:123], v[168:171], v[206:209], v[120:123]
	v_mfma_f32_16x16x32_bf16 v[108:111], v[160:163], v[214:217], v[108:111]
	v_mfma_f32_16x16x32_bf16 v[104:107], v[168:171], v[214:217], v[104:107]
	v_mfma_f32_16x16x32_bf16 v[92:95], v[160:163], v[222:225], v[92:95]
	v_mfma_f32_16x16x32_bf16 v[88:91], v[168:171], v[222:225], v[88:91]
	v_mfma_f32_16x16x32_bf16 v[76:79], v[160:163], v[230:233], v[76:79]
	v_mfma_f32_16x16x32_bf16 v[72:75], v[168:171], v[230:233], v[72:75]
	v_mfma_f32_16x16x32_bf16 v[124:127], v[164:167], v[210:213], v[124:127]
	v_mfma_f32_16x16x32_bf16 v[120:123], v[172:175], v[210:213], v[120:123]
	v_mfma_f32_16x16x32_bf16 v[108:111], v[164:167], v[218:221], v[108:111]
	v_mfma_f32_16x16x32_bf16 v[104:107], v[172:175], v[218:221], v[104:107]
	v_mfma_f32_16x16x32_bf16 v[92:95], v[164:167], v[226:229], v[92:95]
	v_mfma_f32_16x16x32_bf16 v[88:91], v[172:175], v[226:229], v[88:91]
	v_mfma_f32_16x16x32_bf16 v[76:79], v[164:167], v[234:237], v[76:79]
	v_mfma_f32_16x16x32_bf16 v[72:75], v[172:175], v[234:237], v[72:75]
	s_setprio 0
	s_setprio 1
	v_mfma_f32_16x16x32_bf16 v[116:119], v[176:179], v[206:209], v[116:119]
	v_mfma_f32_16x16x32_bf16 v[112:115], v[184:187], v[206:209], v[112:115]
	v_mfma_f32_16x16x32_bf16 v[100:103], v[176:179], v[214:217], v[100:103]
	v_mfma_f32_16x16x32_bf16 v[96:99], v[184:187], v[214:217], v[96:99]
	v_mfma_f32_16x16x32_bf16 v[84:87], v[176:179], v[222:225], v[84:87]
	v_mfma_f32_16x16x32_bf16 v[80:83], v[184:187], v[222:225], v[80:83]
	v_mfma_f32_16x16x32_bf16 v[68:71], v[176:179], v[230:233], v[68:71]
	v_mfma_f32_16x16x32_bf16 v[64:67], v[184:187], v[230:233], v[64:67]
	v_mfma_f32_16x16x32_bf16 v[116:119], v[180:183], v[210:213], v[116:119]
	v_mfma_f32_16x16x32_bf16 v[112:115], v[194:197], v[210:213], v[112:115]
	v_mfma_f32_16x16x32_bf16 v[100:103], v[180:183], v[218:221], v[100:103]
	v_mfma_f32_16x16x32_bf16 v[96:99], v[194:197], v[218:221], v[96:99]
	v_mfma_f32_16x16x32_bf16 v[84:87], v[180:183], v[226:229], v[84:87]
	v_mfma_f32_16x16x32_bf16 v[80:83], v[194:197], v[226:229], v[80:83]
	v_mfma_f32_16x16x32_bf16 v[68:71], v[180:183], v[234:237], v[68:71]
	v_mfma_f32_16x16x32_bf16 v[64:67], v[194:197], v[234:237], v[64:67]
	s_setprio 0
	s_barrier
	s_add_i32 s65, s46, s3
	v_lshl_add_u64 v[148:149], s[34:35], 0, v[132:133]
	s_mov_b32 m0, s65
	ds_read_b128 v[206:209], v154 offset:16384
	ds_read_b128 v[210:213], v154 offset:17408
	ds_read_b128 v[214:217], v154 offset:18432
	ds_read_b128 v[218:221], v154 offset:19456
	ds_read_b128 v[222:225], v154 offset:20480
	ds_read_b128 v[226:229], v154 offset:21504
	ds_read_b128 v[230:233], v154 offset:22528
	ds_read_b128 v[234:237], v154 offset:23552
	global_load_lds_dwordx4 v[148:149], off
	s_add_i32 m0, s65, 0x2000
	s_add_u32 s66, s34, 0x40000
	v_lshl_add_u64 v[188:189], s[34:35], 0, v[128:129]
	s_addc_u32 s67, s35, 0
	s_add_i32 s65, s47, s3
	global_load_lds_dwordx4 v[188:189], off
	v_lshl_add_u64 v[238:239], s[66:67], 0, v[132:133]
	s_mov_b32 m0, s65
	v_lshl_add_u64 v[240:241], s[36:37], 0, v[130:131]
	global_load_lds_dwordx4 v[238:239], off
	v_lshl_add_u64 v[238:239], s[66:67], 0, v[128:129]
	s_add_i32 m0, s65, 0x2000
	s_nop 0
	global_load_lds_dwordx4 v[238:239], off
	v_lshl_add_u64 v[238:239], s[36:37], 0, v[134:135]
	s_mov_b32 m0, s30
	s_nop 0
	global_load_lds_dwordx4 v[238:239], off
	s_mov_b32 m0, s31
	s_nop 0
	global_load_lds_dwordx4 v[240:241], off
	s_cmp_lg_u32 s100, 0
	s_cbranch_scc1 .Lrw_g5_1
	s_waitcnt vmcnt(8)
.Lrw_g5_1:
	s_waitcnt lgkmcnt(0)
	s_barrier
	s_setprio 1
	s_waitcnt lgkmcnt(0)
	v_mfma_f32_16x16x32_bf16 v[60:63], v[160:163], v[206:209], v[60:63]
	v_mfma_f32_16x16x32_bf16 v[56:59], v[168:171], v[206:209], v[56:59]
	v_mfma_f32_16x16x32_bf16 v[44:47], v[160:163], v[214:217], v[44:47]
	v_mfma_f32_16x16x32_bf16 v[40:43], v[168:171], v[214:217], v[40:43]
	v_mfma_f32_16x16x32_bf16 v[28:31], v[160:163], v[222:225], v[28:31]
	v_mfma_f32_16x16x32_bf16 v[24:27], v[168:171], v[222:225], v[24:27]
	v_mfma_f32_16x16x32_bf16 v[12:15], v[160:163], v[230:233], v[12:15]
	v_mfma_f32_16x16x32_bf16 v[8:11], v[168:171], v[230:233], v[8:11]
	v_mfma_f32_16x16x32_bf16 v[60:63], v[164:167], v[210:213], v[60:63]
	v_mfma_f32_16x16x32_bf16 v[56:59], v[172:175], v[210:213], v[56:59]
	v_mfma_f32_16x16x32_bf16 v[44:47], v[164:167], v[218:221], v[44:47]
	v_mfma_f32_16x16x32_bf16 v[40:43], v[172:175], v[218:221], v[40:43]
	v_mfma_f32_16x16x32_bf16 v[28:31], v[164:167], v[226:229], v[28:31]
	v_mfma_f32_16x16x32_bf16 v[24:27], v[172:175], v[226:229], v[24:27]
	v_mfma_f32_16x16x32_bf16 v[12:15], v[164:167], v[234:237], v[12:15]
	v_mfma_f32_16x16x32_bf16 v[8:11], v[172:175], v[234:237], v[8:11]
	s_setprio 0
	s_setprio 1
	v_mfma_f32_16x16x32_bf16 v[52:55], v[176:179], v[206:209], v[52:55]
	v_mfma_f32_16x16x32_bf16 v[48:51], v[184:187], v[206:209], v[48:51]
	v_mfma_f32_16x16x32_bf16 v[36:39], v[176:179], v[214:217], v[36:39]
	v_mfma_f32_16x16x32_bf16 v[32:35], v[184:187], v[214:217], v[32:35]
	v_mfma_f32_16x16x32_bf16 v[20:23], v[176:179], v[222:225], v[20:23]
	v_mfma_f32_16x16x32_bf16 v[16:19], v[184:187], v[222:225], v[16:19]
	v_mfma_f32_16x16x32_bf16 v[4:7], v[176:179], v[230:233], v[4:7]
	v_mfma_f32_16x16x32_bf16 v[0:3], v[184:187], v[230:233], v[0:3]
	v_mfma_f32_16x16x32_bf16 v[52:55], v[180:183], v[210:213], v[52:55]
	v_mfma_f32_16x16x32_bf16 v[48:51], v[194:197], v[210:213], v[48:51]
	v_mfma_f32_16x16x32_bf16 v[36:39], v[180:183], v[218:221], v[36:39]
	v_mfma_f32_16x16x32_bf16 v[32:35], v[194:197], v[218:221], v[32:35]
	v_mfma_f32_16x16x32_bf16 v[20:23], v[180:183], v[226:229], v[20:23]
	v_mfma_f32_16x16x32_bf16 v[16:19], v[194:197], v[226:229], v[16:19]
	v_mfma_f32_16x16x32_bf16 v[4:7], v[180:183], v[234:237], v[4:7]
	v_mfma_f32_16x16x32_bf16 v[0:3], v[194:197], v[234:237], v[0:3]
	s_setprio 0
	s_barrier
	s_add_i32 s65, 0, 0x18000
	v_add_u32_e32 v159, s65, v151
	s_add_i32 s66, 0, 0x1c000
	ds_read_b128 v[160:163], v159
	ds_read_b128 v[164:167], v159 offset:1024
	ds_read_b128 v[168:171], v159 offset:2048
	ds_read_b128 v[172:175], v159 offset:3072
	v_add_u32_e32 v159, s66, v151
	ds_read_b128 v[176:179], v159
	ds_read_b128 v[180:183], v159 offset:1024
	ds_read_b128 v[184:187], v159 offset:2048
	ds_read_b128 v[194:197], v159 offset:3072
	s_add_u32 s36, s36, 0x40000
	s_addc_u32 s37, s37, 0
	s_mov_b32 m0, s33
	v_lshl_add_u64 v[242:243], s[36:37], 0, v[134:135]
	ds_read_b128 v[206:209], v154 offset:32768
	ds_read_b128 v[210:213], v154 offset:33792
	ds_read_b128 v[214:217], v154 offset:34816
	ds_read_b128 v[218:221], v154 offset:35840
	ds_read_b128 v[222:225], v154 offset:36864
	ds_read_b128 v[226:229], v154 offset:37888
	ds_read_b128 v[230:233], v154 offset:38912
	ds_read_b128 v[234:237], v154 offset:39936
	global_load_lds_dwordx4 v[242:243], off
	v_lshl_add_u64 v[242:243], s[36:37], 0, v[130:131]
	s_mov_b32 m0, s38
	s_nop 0
	global_load_lds_dwordx4 v[242:243], off
	s_waitcnt vmcnt(8)
	s_waitcnt lgkmcnt(0)
	s_barrier
	s_setprio 1
	s_waitcnt lgkmcnt(0)
	v_mfma_f32_16x16x32_bf16 v[124:127], v[160:163], v[206:209], v[124:127]
	v_mfma_f32_16x16x32_bf16 v[120:123], v[168:171], v[206:209], v[120:123]
	v_mfma_f32_16x16x32_bf16 v[108:111], v[160:163], v[214:217], v[108:111]
	v_mfma_f32_16x16x32_bf16 v[104:107], v[168:171], v[214:217], v[104:107]
	v_mfma_f32_16x16x32_bf16 v[92:95], v[160:163], v[222:225], v[92:95]
	v_mfma_f32_16x16x32_bf16 v[88:91], v[168:171], v[222:225], v[88:91]
	v_mfma_f32_16x16x32_bf16 v[76:79], v[160:163], v[230:233], v[76:79]
	v_mfma_f32_16x16x32_bf16 v[72:75], v[168:171], v[230:233], v[72:75]
	v_mfma_f32_16x16x32_bf16 v[124:127], v[164:167], v[210:213], v[124:127]
	v_mfma_f32_16x16x32_bf16 v[120:123], v[172:175], v[210:213], v[120:123]
	v_mfma_f32_16x16x32_bf16 v[108:111], v[164:167], v[218:221], v[108:111]
	v_mfma_f32_16x16x32_bf16 v[104:107], v[172:175], v[218:221], v[104:107]
	v_mfma_f32_16x16x32_bf16 v[92:95], v[164:167], v[226:229], v[92:95]
	v_mfma_f32_16x16x32_bf16 v[88:91], v[172:175], v[226:229], v[88:91]
	v_mfma_f32_16x16x32_bf16 v[76:79], v[164:167], v[234:237], v[76:79]
	v_mfma_f32_16x16x32_bf16 v[72:75], v[172:175], v[234:237], v[72:75]
	s_setprio 0
	s_setprio 1
	v_mfma_f32_16x16x32_bf16 v[116:119], v[176:179], v[206:209], v[116:119]
	v_mfma_f32_16x16x32_bf16 v[112:115], v[184:187], v[206:209], v[112:115]
	v_mfma_f32_16x16x32_bf16 v[100:103], v[176:179], v[214:217], v[100:103]
	v_mfma_f32_16x16x32_bf16 v[96:99], v[184:187], v[214:217], v[96:99]
	v_mfma_f32_16x16x32_bf16 v[84:87], v[176:179], v[222:225], v[84:87]
	v_mfma_f32_16x16x32_bf16 v[80:83], v[184:187], v[222:225], v[80:83]
	v_mfma_f32_16x16x32_bf16 v[68:71], v[176:179], v[230:233], v[68:71]
	v_mfma_f32_16x16x32_bf16 v[64:67], v[184:187], v[230:233], v[64:67]
	v_mfma_f32_16x16x32_bf16 v[116:119], v[180:183], v[210:213], v[116:119]
	v_mfma_f32_16x16x32_bf16 v[112:115], v[194:197], v[210:213], v[112:115]
	v_mfma_f32_16x16x32_bf16 v[100:103], v[180:183], v[218:221], v[100:103]
	v_mfma_f32_16x16x32_bf16 v[96:99], v[194:197], v[218:221], v[96:99]
	v_mfma_f32_16x16x32_bf16 v[84:87], v[180:183], v[226:229], v[84:87]
	v_mfma_f32_16x16x32_bf16 v[80:83], v[194:197], v[226:229], v[80:83]
	v_mfma_f32_16x16x32_bf16 v[68:71], v[180:183], v[234:237], v[68:71]
	v_mfma_f32_16x16x32_bf16 v[64:67], v[194:197], v[234:237], v[64:67]
	s_setprio 0
	s_barrier
	s_add_i32 s36, s65, s3
	v_lshl_add_u64 v[148:149], v[148:149], 0, s[12:13]
	s_mov_b32 m0, s36
	ds_read_b128 v[206:209], v154 offset:49152
	ds_read_b128 v[210:213], v154 offset:50176
	ds_read_b128 v[214:217], v154 offset:51200
	ds_read_b128 v[218:221], v154 offset:52224
	ds_read_b128 v[222:225], v154 offset:53248
	ds_read_b128 v[226:229], v154 offset:54272
	ds_read_b128 v[230:233], v154 offset:55296
	ds_read_b128 v[234:237], v154 offset:56320
	global_load_lds_dwordx4 v[148:149], off
	s_add_i32 m0, s36, 0x2000
	s_add_u32 s34, s34, 0x40080
	v_lshl_add_u64 v[148:149], v[188:189], 0, s[12:13]
	s_addc_u32 s35, s35, 0
	s_add_i32 s36, s66, s3
	global_load_lds_dwordx4 v[148:149], off
	v_lshl_add_u64 v[148:149], s[34:35], 0, v[132:133]
	s_mov_b32 m0, s36
	s_nop 0
	global_load_lds_dwordx4 v[148:149], off
	v_lshl_add_u64 v[148:149], s[34:35], 0, v[128:129]
	s_add_i32 m0, s36, 0x2000
	s_nop 0
	global_load_lds_dwordx4 v[148:149], off
	v_lshl_add_u64 v[148:149], v[238:239], 0, s[12:13]
	s_mov_b32 m0, s42
	s_nop 0
	global_load_lds_dwordx4 v[148:149], off
	v_lshl_add_u64 v[148:149], v[240:241], 0, s[12:13]
	s_mov_b32 m0, s43
	s_nop 0
	global_load_lds_dwordx4 v[148:149], off
	s_waitcnt vmcnt(8)
	s_waitcnt lgkmcnt(0)
	s_barrier
	s_setprio 1
	s_waitcnt lgkmcnt(0)
	v_mfma_f32_16x16x32_bf16 v[60:63], v[160:163], v[206:209], v[60:63]
	v_mfma_f32_16x16x32_bf16 v[56:59], v[168:171], v[206:209], v[56:59]
	v_mfma_f32_16x16x32_bf16 v[44:47], v[160:163], v[214:217], v[44:47]
	v_mfma_f32_16x16x32_bf16 v[40:43], v[168:171], v[214:217], v[40:43]
	v_mfma_f32_16x16x32_bf16 v[28:31], v[160:163], v[222:225], v[28:31]
	v_mfma_f32_16x16x32_bf16 v[24:27], v[168:171], v[222:225], v[24:27]
	v_mfma_f32_16x16x32_bf16 v[12:15], v[160:163], v[230:233], v[12:15]
	v_mfma_f32_16x16x32_bf16 v[8:11], v[168:171], v[230:233], v[8:11]
	v_mfma_f32_16x16x32_bf16 v[60:63], v[164:167], v[210:213], v[60:63]
	v_mfma_f32_16x16x32_bf16 v[56:59], v[172:175], v[210:213], v[56:59]
	v_mfma_f32_16x16x32_bf16 v[44:47], v[164:167], v[218:221], v[44:47]
	v_mfma_f32_16x16x32_bf16 v[40:43], v[172:175], v[218:221], v[40:43]
	v_mfma_f32_16x16x32_bf16 v[28:31], v[164:167], v[226:229], v[28:31]
	v_mfma_f32_16x16x32_bf16 v[24:27], v[172:175], v[226:229], v[24:27]
	v_mfma_f32_16x16x32_bf16 v[12:15], v[164:167], v[234:237], v[12:15]
	v_mfma_f32_16x16x32_bf16 v[8:11], v[172:175], v[234:237], v[8:11]
	s_setprio 0
	s_setprio 1
	v_mfma_f32_16x16x32_bf16 v[52:55], v[176:179], v[206:209], v[52:55]
	v_mfma_f32_16x16x32_bf16 v[48:51], v[184:187], v[206:209], v[48:51]
	v_mfma_f32_16x16x32_bf16 v[36:39], v[176:179], v[214:217], v[36:39]
	v_mfma_f32_16x16x32_bf16 v[32:35], v[184:187], v[214:217], v[32:35]
	v_mfma_f32_16x16x32_bf16 v[20:23], v[176:179], v[222:225], v[20:23]
	v_mfma_f32_16x16x32_bf16 v[16:19], v[184:187], v[222:225], v[16:19]
	v_mfma_f32_16x16x32_bf16 v[4:7], v[176:179], v[230:233], v[4:7]
	v_mfma_f32_16x16x32_bf16 v[0:3], v[184:187], v[230:233], v[0:3]
	v_mfma_f32_16x16x32_bf16 v[52:55], v[180:183], v[210:213], v[52:55]
	v_mfma_f32_16x16x32_bf16 v[48:51], v[194:197], v[210:213], v[48:51]
	v_mfma_f32_16x16x32_bf16 v[36:39], v[180:183], v[218:221], v[36:39]
	v_mfma_f32_16x16x32_bf16 v[32:35], v[194:197], v[218:221], v[32:35]
	v_mfma_f32_16x16x32_bf16 v[20:23], v[180:183], v[226:229], v[20:23]
	v_mfma_f32_16x16x32_bf16 v[16:19], v[194:197], v[226:229], v[16:19]
	v_mfma_f32_16x16x32_bf16 v[4:7], v[180:183], v[234:237], v[4:7]
	v_mfma_f32_16x16x32_bf16 v[0:3], v[194:197], v[234:237], v[0:3]
	s_setprio 0
	s_barrier
	s_add_i32 s64, s64, 2
	s_add_u32 s26, s26, 0x100
	s_addc_u32 s27, s27, 0
	s_add_u32 s62, s62, 0x100
	s_addc_u32 s63, s63, 0
	s_cmp_gt_u32 s64, 13
	s_cbranch_scc0 .LBB0_936
	s_and_b64 vcc, exec, s[14:15]
	s_cbranch_vccz .LBB0_939
	s_barrier

.LBB0_1148:
	s_add_u32 s14, s56, 0x800000
	s_mov_b64 s[18:19], 0x80
	s_addc_u32 s15, s57, 0
	s_and_b32 s46, s1, 3
	s_add_i32 m0, s31, 0x18000
	v_lshl_add_u64 v[6:7], v[6:7], 0, s[18:19]
	s_lshl_b32 s1, s0, 13
	s_lshl_b32 s21, s46, 12
	s_ashr_i32 s47, s2, 31
	s_waitcnt vmcnt(2)
	s_barrier
	global_load_lds_dwordx4 v[6:7], off
	v_lshl_add_u64 v[4:5], v[4:5], 0, s[18:19]
	s_add_i32 m0, s31, 0x1a000
	s_add_i32 s48, s31, 0x8000
	s_add_i32 s49, s31, 0xa000
	global_load_lds_dwordx4 v[4:5], off
	v_lshl_add_u64 v[0:1], v[0:1], 0, s[18:19]
	s_mov_b32 m0, s48
	s_add_u32 s4, s40, 0x40080
	global_load_lds_dwordx4 v[0:1], off
	v_lshl_add_u64 v[0:1], v[2:3], 0, s[18:19]
	s_mov_b32 m0, s49
	s_addc_u32 s5, s41, 0
	global_load_lds_dwordx4 v[0:1], off
	s_add_i32 m0, s31, 0x1c000
	v_lshl_add_u64 v[0:1], s[4:5], 0, v[130:131]
	global_load_lds_dwordx4 v[0:1], off
	v_lshl_add_u64 v[0:1], s[4:5], 0, v[134:135]
	s_add_i32 m0, s31, 0x1e000
	v_lshlrev_b32_e32 v4, 2, v192
	global_load_lds_dwordx4 v[0:1], off
	v_bfe_u32 v0, v192, 4, 2
	v_and_b32_e32 v1, 15, v192
	v_lshlrev_b32_e32 v3, 4, v0
	v_lshl_or_b32 v148, s0, 6, v1
	v_lshl_or_b32 v1, v1, 6, v3
	v_and_b32_e32 v4, 32, v4
	v_lshlrev_b32_e32 v5, 6, v192
	s_movk_i32 s0, 0x3c0
	v_lshlrev_b32_e32 v2, 3, v0
	v_bitop3_b32 v1, v1, s1, v4 bitop3:0xde
	v_and_or_b32 v3, v5, s0, v3
	v_cmp_eq_u32_e64 s[0:1], 0, v0
	v_lshlrev_b32_e32 v0, 8, v192
	v_lshl_or_b32 v150, s46, 6, v2
	v_and_b32_e32 v0, 0x38000, v0
	v_lshlrev_b32_e32 v2, 11, v10
	v_or3_b32 v0, v8, v0, v2
	v_add_u32_e32 v136, v0, v9
	v_lshlrev_b32_e32 v0, 4, v11
	v_and_b32_e32 v0, 0x78000, v0
	s_waitcnt vmcnt(6)
	s_cmpk_lt_u32 s20, 0x100
	v_or3_b32 v0, v8, v0, v2
	v_bitop3_b32 v149, s21, v3, v4 bitop3:0xf6
	s_cselect_b64 s[20:21], -1, 0
	v_add_u32_e32 v138, v0, v9
	s_add_i32 s62, 0, 0x10000
	s_add_i32 s63, 0, 0x14000
	v_mbcnt_lo_u32_b32 v0, -1, 0
	s_ashr_i32 s50, s60, 31
	s_mov_b32 s51, s60
	v_mov_b32_e32 v137, v131
	v_mov_b32_e32 v139, v131
	v_mov_b64_e32 v[140:141], 0x200
	v_mov_b64_e32 v[142:143], 0x1ff
	v_add_u32_e32 v151, s62, v149
	v_add_u32_e32 v152, s63, v149
	v_add_u32_e32 v153, 0, v1
	v_mbcnt_hi_u32_b32 v154, -1, v0
	s_mov_b32 s64, 0
	s_barrier
	s_branch .LBB0_1151

.LBB0_1151:
	s_add_i32 s64, s64, 1
	s_cmp_gt_u32 s64, 1
	s_cselect_b32 s101, 1, 0
	s_mul_i32 s4, s64, s50
	s_mul_hi_u32 s5, s64, s51
	s_add_i32 s5, s5, s4
	s_mul_i32 s4, s64, s51
	s_add_u32 s26, s4, s2
	s_addc_u32 s27, s5, s47
	v_cmp_gt_i64_e32 vcc, s[26:27], v[142:143]
	v_cmp_lt_i64_e64 s[4:5], s[26:27], v[140:141]
	s_cbranch_vccnz .LBB0_1157
	s_ashr_i32 s22, s27, 31
	s_lshr_b32 s22, s22, 23
	s_add_i32 s22, s26, s22
	s_and_b32 s22, s22, 0xfe00
	s_sub_i32 s22, s26, s22
	s_sext_i32_i16 s23, s22
	s_bfe_u32 s23, s23, 0x3001c
	s_add_i32 s24, s22, s23
	s_and_b32 s23, s24, 0xfff8
	s_sub_i32 s26, s22, s23
	s_sext_i32_i16 s22, s26
	s_cmp_gt_i32 s22, -1
	s_mov_b64 s[22:23], -1
	s_cbranch_scc0 .LBB0_1154
	s_lshl_b32 s25, s26, 6
	s_mov_b64 s[22:23], 0

.LBB0_1158:
	s_cmp_eq_u32 s68, -2
	s_cselect_b32 s100, s101, 0
	ds_read_b128 v[144:147], v151
	ds_read_b128 v[156:159], v151 offset:1024
	ds_read_b128 v[160:163], v151 offset:2048
	ds_read_b128 v[164:167], v151 offset:3072
	ds_read_b128 v[168:171], v152
	ds_read_b128 v[172:175], v152 offset:1024
	ds_read_b128 v[176:179], v152 offset:2048
	ds_read_b128 v[180:183], v152 offset:3072
	s_add_u32 s40, s38, 0xfffc0080
	s_addc_u32 s41, s39, -1
	s_cmp_eq_u32 s68, 12
	s_cselect_b32 s43, s23, s41
	s_cselect_b32 s42, s37, s40
	s_cselect_b32 s41, s25, s67
	s_cselect_b32 s40, s65, s66
	v_lshl_add_u64 v[188:189], s[38:39], 0, v[136:137]
	s_add_i32 m0, s31, 0xc000
	ds_read_b128 v[184:187], v153
	ds_read_b128 v[194:197], v153 offset:1024
	ds_read_b128 v[198:201], v153 offset:2048
	ds_read_b128 v[202:205], v153 offset:3072
	ds_read_b128 v[206:209], v153 offset:4096
	ds_read_b128 v[210:213], v153 offset:5120
	ds_read_b128 v[214:217], v153 offset:6144
	ds_read_b128 v[218:221], v153 offset:7168
	global_load_lds_dwordx4 v[188:189], off
	v_lshl_add_u64 v[188:189], s[38:39], 0, v[138:139]
	s_add_i32 m0, s31, 0xe000
	s_nop 0
	global_load_lds_dwordx4 v[188:189], off
	s_cmp_lg_u32 s100, 0
	s_cbranch_scc1 .Lrw_g6_0
	s_waitcnt vmcnt(8)
.Lrw_g6_0:
	s_waitcnt lgkmcnt(0)
	s_barrier
	s_setprio 1
	s_waitcnt lgkmcnt(0)
	v_mfma_f32_16x16x32_bf16 v[124:127], v[144:147], v[184:187], v[124:127]
	v_mfma_f32_16x16x32_bf16 v[120:123], v[160:163], v[184:187], v[120:123]
	v_mfma_f32_16x16x32_bf16 v[108:111], v[144:147], v[198:201], v[108:111]
	v_mfma_f32_16x16x32_bf16 v[104:107], v[160:163], v[198:201], v[104:107]
	v_mfma_f32_16x16x32_bf16 v[92:95], v[144:147], v[206:209], v[92:95]
	v_mfma_f32_16x16x32_bf16 v[88:91], v[160:163], v[206:209], v[88:91]
	v_mfma_f32_16x16x32_bf16 v[76:79], v[144:147], v[214:217], v[76:79]
	v_mfma_f32_16x16x32_bf16 v[72:75], v[160:163], v[214:217], v[72:75]
	v_mfma_f32_16x16x32_bf16 v[124:127], v[156:159], v[194:197], v[124:127]
	v_mfma_f32_16x16x32_bf16 v[120:123], v[164:167], v[194:197], v[120:123]
	v_mfma_f32_16x16x32_bf16 v[108:111], v[156:159], v[202:205], v[108:111]
	v_mfma_f32_16x16x32_bf16 v[104:107], v[164:167], v[202:205], v[104:107]
	v_mfma_f32_16x16x32_bf16 v[92:95], v[156:159], v[210:213], v[92:95]
	v_mfma_f32_16x16x32_bf16 v[88:91], v[164:167], v[210:213], v[88:91]
	v_mfma_f32_16x16x32_bf16 v[76:79], v[156:159], v[218:221], v[76:79]
	v_mfma_f32_16x16x32_bf16 v[72:75], v[164:167], v[218:221], v[72:75]
	s_setprio 0
	s_setprio 1
	v_mfma_f32_16x16x32_bf16 v[116:119], v[168:171], v[184:187], v[116:119]
	v_mfma_f32_16x16x32_bf16 v[112:115], v[176:179], v[184:187], v[112:115]
	v_mfma_f32_16x16x32_bf16 v[100:103], v[168:171], v[198:201], v[100:103]
	v_mfma_f32_16x16x32_bf16 v[96:99], v[176:179], v[198:201], v[96:99]
	v_mfma_f32_16x16x32_bf16 v[84:87], v[168:171], v[206:209], v[84:87]
	v_mfma_f32_16x16x32_bf16 v[80:83], v[176:179], v[206:209], v[80:83]
	v_mfma_f32_16x16x32_bf16 v[68:71], v[168:171], v[214:217], v[68:71]
	v_mfma_f32_16x16x32_bf16 v[64:67], v[176:179], v[214:217], v[64:67]
	v_mfma_f32_16x16x32_bf16 v[116:119], v[172:175], v[194:197], v[116:119]
	v_mfma_f32_16x16x32_bf16 v[112:115], v[180:183], v[194:197], v[112:115]
	v_mfma_f32_16x16x32_bf16 v[100:103], v[172:175], v[202:205], v[100:103]
	v_mfma_f32_16x16x32_bf16 v[96:99], v[180:183], v[202:205], v[96:99]
	v_mfma_f32_16x16x32_bf16 v[84:87], v[172:175], v[210:213], v[84:87]
	v_mfma_f32_16x16x32_bf16 v[80:83], v[180:183], v[210:213], v[80:83]
	v_mfma_f32_16x16x32_bf16 v[68:71], v[172:175], v[218:221], v[68:71]
	v_mfma_f32_16x16x32_bf16 v[64:67], v[180:183], v[218:221], v[64:67]
	s_setprio 0
	s_barrier
	s_add_i32 s69, s62, s30
	v_lshl_add_u64 v[188:189], s[40:41], 0, v[130:131]
	s_mov_b32 m0, s69
	ds_read_b128 v[184:187], v153 offset:16384
	ds_read_b128 v[194:197], v153 offset:17408
	ds_read_b128 v[198:201], v153 offset:18432
	ds_read_b128 v[202:205], v153 offset:19456
	ds_read_b128 v[206:209], v153 offset:20480
	ds_read_b128 v[210:213], v153 offset:21504
	ds_read_b128 v[214:217], v153 offset:22528
	ds_read_b128 v[218:221], v153 offset:23552
	global_load_lds_dwordx4 v[188:189], off
	s_add_i32 m0, s69, 0x2000
	s_add_u32 s70, s40, 0x40000
	v_lshl_add_u64 v[222:223], s[40:41], 0, v[134:135]
	s_addc_u32 s71, s41, 0
	s_add_i32 s69, s63, s30
	global_load_lds_dwordx4 v[222:223], off
	v_lshl_add_u64 v[224:225], s[70:71], 0, v[130:131]
	s_mov_b32 m0, s69
	v_lshl_add_u64 v[226:227], s[42:43], 0, v[132:133]
	global_load_lds_dwordx4 v[224:225], off
	v_lshl_add_u64 v[224:225], s[70:71], 0, v[134:135]
	s_add_i32 m0, s69, 0x2000
	s_nop 0
	global_load_lds_dwordx4 v[224:225], off
	v_lshl_add_u64 v[224:225], s[42:43], 0, v[128:129]
	s_mov_b32 m0, s31
	s_nop 0
	global_load_lds_dwordx4 v[224:225], off
	s_mov_b32 m0, s33
	s_nop 0
	global_load_lds_dwordx4 v[226:227], off
	s_cmp_lg_u32 s100, 0
	s_cbranch_scc1 .Lrw_g6_1
	s_waitcnt vmcnt(8)
.Lrw_g6_1:
	s_waitcnt lgkmcnt(0)
	s_barrier
	s_setprio 1
	s_waitcnt lgkmcnt(0)
	v_mfma_f32_16x16x32_bf16 v[60:63], v[144:147], v[184:187], v[60:63]
	v_mfma_f32_16x16x32_bf16 v[56:59], v[160:163], v[184:187], v[56:59]
	v_mfma_f32_16x16x32_bf16 v[44:47], v[144:147], v[198:201], v[44:47]
	v_mfma_f32_16x16x32_bf16 v[40:43], v[160:163], v[198:201], v[40:43]
	v_mfma_f32_16x16x32_bf16 v[28:31], v[144:147], v[206:209], v[28:31]
	v_mfma_f32_16x16x32_bf16 v[24:27], v[160:163], v[206:209], v[24:27]
	v_mfma_f32_16x16x32_bf16 v[12:15], v[144:147], v[214:217], v[12:15]
	v_mfma_f32_16x16x32_bf16 v[8:11], v[160:163], v[214:217], v[8:11]
	v_mfma_f32_16x16x32_bf16 v[60:63], v[156:159], v[194:197], v[60:63]
	v_mfma_f32_16x16x32_bf16 v[56:59], v[164:167], v[194:197], v[56:59]
	v_mfma_f32_16x16x32_bf16 v[44:47], v[156:159], v[202:205], v[44:47]
	v_mfma_f32_16x16x32_bf16 v[40:43], v[164:167], v[202:205], v[40:43]
	v_mfma_f32_16x16x32_bf16 v[28:31], v[156:159], v[210:213], v[28:31]
	v_mfma_f32_16x16x32_bf16 v[24:27], v[164:167], v[210:213], v[24:27]
	v_mfma_f32_16x16x32_bf16 v[12:15], v[156:159], v[218:221], v[12:15]
	v_mfma_f32_16x16x32_bf16 v[8:11], v[164:167], v[218:221], v[8:11]
	s_setprio 0
	s_setprio 1
	v_mfma_f32_16x16x32_bf16 v[52:55], v[168:171], v[184:187], v[52:55]
	v_mfma_f32_16x16x32_bf16 v[48:51], v[176:179], v[184:187], v[48:51]
	v_mfma_f32_16x16x32_bf16 v[36:39], v[168:171], v[198:201], v[36:39]
	v_mfma_f32_16x16x32_bf16 v[32:35], v[176:179], v[198:201], v[32:35]
	v_mfma_f32_16x16x32_bf16 v[20:23], v[168:171], v[206:209], v[20:23]
	v_mfma_f32_16x16x32_bf16 v[16:19], v[176:179], v[206:209], v[16:19]
	v_mfma_f32_16x16x32_bf16 v[4:7], v[168:171], v[214:217], v[4:7]
	v_mfma_f32_16x16x32_bf16 v[0:3], v[176:179], v[214:217], v[0:3]
	v_mfma_f32_16x16x32_bf16 v[52:55], v[172:175], v[194:197], v[52:55]
	v_mfma_f32_16x16x32_bf16 v[48:51], v[180:183], v[194:197], v[48:51]
	v_mfma_f32_16x16x32_bf16 v[36:39], v[172:175], v[202:205], v[36:39]
	v_mfma_f32_16x16x32_bf16 v[32:35], v[180:183], v[202:205], v[32:35]
	v_mfma_f32_16x16x32_bf16 v[20:23], v[172:175], v[210:213], v[20:23]
	v_mfma_f32_16x16x32_bf16 v[16:19], v[180:183], v[210:213], v[16:19]
	v_mfma_f32_16x16x32_bf16 v[4:7], v[172:175], v[218:221], v[4:7]
	v_mfma_f32_16x16x32_bf16 v[0:3], v[180:183], v[218:221], v[0:3]
	s_setprio 0
	s_barrier
	s_add_i32 s69, 0, 0x18000
	v_add_u32_e32 v155, s69, v149
	s_add_i32 s70, 0, 0x1c000
	ds_read_b128 v[144:147], v155
	ds_read_b128 v[156:159], v155 offset:1024
	ds_read_b128 v[160:163], v155 offset:2048
	ds_read_b128 v[164:167], v155 offset:3072
	v_add_u32_e32 v155, s70, v149
	ds_read_b128 v[168:171], v155
	ds_read_b128 v[172:175], v155 offset:1024
	ds_read_b128 v[176:179], v155 offset:2048
	ds_read_b128 v[180:183], v155 offset:3072
	s_add_u32 s42, s42, 0x40000
	s_addc_u32 s43, s43, 0
	s_mov_b32 m0, s44
	v_lshl_add_u64 v[228:229], s[42:43], 0, v[128:129]
	ds_read_b128 v[184:187], v153 offset:32768
	ds_read_b128 v[194:197], v153 offset:33792
	ds_read_b128 v[198:201], v153 offset:34816
	ds_read_b128 v[202:205], v153 offset:35840
	ds_read_b128 v[206:209], v153 offset:36864
	ds_read_b128 v[210:213], v153 offset:37888
	ds_read_b128 v[214:217], v153 offset:38912
	ds_read_b128 v[218:221], v153 offset:39936
	global_load_lds_dwordx4 v[228:229], off
	v_lshl_add_u64 v[228:229], s[42:43], 0, v[132:133]
	s_mov_b32 m0, s45
	s_nop 0
	global_load_lds_dwordx4 v[228:229], off
	s_waitcnt vmcnt(8)
	s_waitcnt lgkmcnt(0)
	s_barrier
	s_setprio 1
	s_waitcnt lgkmcnt(0)
	v_mfma_f32_16x16x32_bf16 v[124:127], v[144:147], v[184:187], v[124:127]
	v_mfma_f32_16x16x32_bf16 v[120:123], v[160:163], v[184:187], v[120:123]
	v_mfma_f32_16x16x32_bf16 v[108:111], v[144:147], v[198:201], v[108:111]
	v_mfma_f32_16x16x32_bf16 v[104:107], v[160:163], v[198:201], v[104:107]
	v_mfma_f32_16x16x32_bf16 v[92:95], v[144:147], v[206:209], v[92:95]
	v_mfma_f32_16x16x32_bf16 v[88:91], v[160:163], v[206:209], v[88:91]
	v_mfma_f32_16x16x32_bf16 v[76:79], v[144:147], v[214:217], v[76:79]
	v_mfma_f32_16x16x32_bf16 v[72:75], v[160:163], v[214:217], v[72:75]
	v_mfma_f32_16x16x32_bf16 v[124:127], v[156:159], v[194:197], v[124:127]
	v_mfma_f32_16x16x32_bf16 v[120:123], v[164:167], v[194:197], v[120:123]
	v_mfma_f32_16x16x32_bf16 v[108:111], v[156:159], v[202:205], v[108:111]
	v_mfma_f32_16x16x32_bf16 v[104:107], v[164:167], v[202:205], v[104:107]
	v_mfma_f32_16x16x32_bf16 v[92:95], v[156:159], v[210:213], v[92:95]
	v_mfma_f32_16x16x32_bf16 v[88:91], v[164:167], v[210:213], v[88:91]
	v_mfma_f32_16x16x32_bf16 v[76:79], v[156:159], v[218:221], v[76:79]
	v_mfma_f32_16x16x32_bf16 v[72:75], v[164:167], v[218:221], v[72:75]
	s_setprio 0
	s_setprio 1
	v_mfma_f32_16x16x32_bf16 v[116:119], v[168:171], v[184:187], v[116:119]
	v_mfma_f32_16x16x32_bf16 v[112:115], v[176:179], v[184:187], v[112:115]
	v_mfma_f32_16x16x32_bf16 v[100:103], v[168:171], v[198:201], v[100:103]
	v_mfma_f32_16x16x32_bf16 v[96:99], v[176:179], v[198:201], v[96:99]
	v_mfma_f32_16x16x32_bf16 v[84:87], v[168:171], v[206:209], v[84:87]
	v_mfma_f32_16x16x32_bf16 v[80:83], v[176:179], v[206:209], v[80:83]
	v_mfma_f32_16x16x32_bf16 v[68:71], v[168:171], v[214:217], v[68:71]
	v_mfma_f32_16x16x32_bf16 v[64:67], v[176:179], v[214:217], v[64:67]
	v_mfma_f32_16x16x32_bf16 v[116:119], v[172:175], v[194:197], v[116:119]
	v_mfma_f32_16x16x32_bf16 v[112:115], v[180:183], v[194:197], v[112:115]
	v_mfma_f32_16x16x32_bf16 v[100:103], v[172:175], v[202:205], v[100:103]
	v_mfma_f32_16x16x32_bf16 v[96:99], v[180:183], v[202:205], v[96:99]
	v_mfma_f32_16x16x32_bf16 v[84:87], v[172:175], v[210:213], v[84:87]
	v_mfma_f32_16x16x32_bf16 v[80:83], v[180:183], v[210:213], v[80:83]
	v_mfma_f32_16x16x32_bf16 v[68:71], v[172:175], v[218:221], v[68:71]
	v_mfma_f32_16x16x32_bf16 v[64:67], v[180:183], v[218:221], v[64:67]
	s_setprio 0
	s_barrier
	s_add_i32 s42, s69, s30
	v_lshl_add_u64 v[188:189], v[188:189], 0, s[18:19]
	s_mov_b32 m0, s42
	ds_read_b128 v[184:187], v153 offset:49152
	ds_read_b128 v[194:197], v153 offset:50176
	ds_read_b128 v[198:201], v153 offset:51200
	ds_read_b128 v[202:205], v153 offset:52224
	ds_read_b128 v[206:209], v153 offset:53248
	ds_read_b128 v[210:213], v153 offset:54272
	ds_read_b128 v[214:217], v153 offset:55296
	ds_read_b128 v[218:221], v153 offset:56320
	global_load_lds_dwordx4 v[188:189], off
	s_add_i32 m0, s42, 0x2000
	s_add_u32 s40, s40, 0x40080
	v_lshl_add_u64 v[188:189], v[222:223], 0, s[18:19]
	s_addc_u32 s41, s41, 0
	s_add_i32 s42, s70, s30
	global_load_lds_dwordx4 v[188:189], off
	v_lshl_add_u64 v[188:189], s[40:41], 0, v[130:131]
	s_mov_b32 m0, s42
	s_nop 0
	global_load_lds_dwordx4 v[188:189], off
	v_lshl_add_u64 v[188:189], s[40:41], 0, v[134:135]
	s_add_i32 m0, s42, 0x2000
	s_nop 0
	global_load_lds_dwordx4 v[188:189], off
	v_lshl_add_u64 v[188:189], v[224:225], 0, s[18:19]
	s_mov_b32 m0, s48
	s_nop 0
	global_load_lds_dwordx4 v[188:189], off
	v_lshl_add_u64 v[188:189], v[226:227], 0, s[18:19]
	s_mov_b32 m0, s49
	s_nop 0
	global_load_lds_dwordx4 v[188:189], off
	s_waitcnt vmcnt(8)
	s_waitcnt lgkmcnt(0)
	s_barrier
	s_setprio 1
	s_waitcnt lgkmcnt(0)
	v_mfma_f32_16x16x32_bf16 v[60:63], v[144:147], v[184:187], v[60:63]
	v_mfma_f32_16x16x32_bf16 v[56:59], v[160:163], v[184:187], v[56:59]
	v_mfma_f32_16x16x32_bf16 v[44:47], v[144:147], v[198:201], v[44:47]
	v_mfma_f32_16x16x32_bf16 v[40:43], v[160:163], v[198:201], v[40:43]
	v_mfma_f32_16x16x32_bf16 v[28:31], v[144:147], v[206:209], v[28:31]
	v_mfma_f32_16x16x32_bf16 v[24:27], v[160:163], v[206:209], v[24:27]
	v_mfma_f32_16x16x32_bf16 v[12:15], v[144:147], v[214:217], v[12:15]
	v_mfma_f32_16x16x32_bf16 v[8:11], v[160:163], v[214:217], v[8:11]
	v_mfma_f32_16x16x32_bf16 v[60:63], v[156:159], v[194:197], v[60:63]
	v_mfma_f32_16x16x32_bf16 v[56:59], v[164:167], v[194:197], v[56:59]
	v_mfma_f32_16x16x32_bf16 v[44:47], v[156:159], v[202:205], v[44:47]
	v_mfma_f32_16x16x32_bf16 v[40:43], v[164:167], v[202:205], v[40:43]
	v_mfma_f32_16x16x32_bf16 v[28:31], v[156:159], v[210:213], v[28:31]
	v_mfma_f32_16x16x32_bf16 v[24:27], v[164:167], v[210:213], v[24:27]
	v_mfma_f32_16x16x32_bf16 v[12:15], v[156:159], v[218:221], v[12:15]
	v_mfma_f32_16x16x32_bf16 v[8:11], v[164:167], v[218:221], v[8:11]
	s_setprio 0
	s_setprio 1
	v_mfma_f32_16x16x32_bf16 v[52:55], v[168:171], v[184:187], v[52:55]
	v_mfma_f32_16x16x32_bf16 v[48:51], v[176:179], v[184:187], v[48:51]
	v_mfma_f32_16x16x32_bf16 v[36:39], v[168:171], v[198:201], v[36:39]
	v_mfma_f32_16x16x32_bf16 v[32:35], v[176:179], v[198:201], v[32:35]
	v_mfma_f32_16x16x32_bf16 v[20:23], v[168:171], v[206:209], v[20:23]
	v_mfma_f32_16x16x32_bf16 v[16:19], v[176:179], v[206:209], v[16:19]
	v_mfma_f32_16x16x32_bf16 v[4:7], v[168:171], v[214:217], v[4:7]
	v_mfma_f32_16x16x32_bf16 v[0:3], v[176:179], v[214:217], v[0:3]
	v_mfma_f32_16x16x32_bf16 v[52:55], v[172:175], v[194:197], v[52:55]
	v_mfma_f32_16x16x32_bf16 v[48:51], v[180:183], v[194:197], v[48:51]
	v_mfma_f32_16x16x32_bf16 v[36:39], v[172:175], v[202:205], v[36:39]
	v_mfma_f32_16x16x32_bf16 v[32:35], v[180:183], v[202:205], v[32:35]
	v_mfma_f32_16x16x32_bf16 v[20:23], v[172:175], v[210:213], v[20:23]
	v_mfma_f32_16x16x32_bf16 v[16:19], v[180:183], v[210:213], v[16:19]
	v_mfma_f32_16x16x32_bf16 v[4:7], v[172:175], v[218:221], v[4:7]
	v_mfma_f32_16x16x32_bf16 v[0:3], v[180:183], v[218:221], v[0:3]
	s_setprio 0
	s_barrier
	s_add_i32 s68, s68, 2
	s_add_u32 s38, s38, 0x100
	s_addc_u32 s39, s39, 0
	s_add_u32 s66, s66, 0x100
	s_addc_u32 s67, s67, 0
	s_cmp_gt_u32 s68, 13
	s_cbranch_scc0 .LBB0_1158
	s_and_b64 vcc, exec, s[20:21]
	s_cbranch_vccz .LBB0_1161
	s_barrier
.LBB0_1161:
	v_lshl_add_u32 v146, s36, 8, v148
	v_ashrrev_i32_e32 v147, 31, v146
	v_lshl_or_b32 v144, s8, 8, v150
	v_lshlrev_b64 v[156:157], 11, v[146:147]
	v_ashrrev_i32_e32 v145, 31, v144
	v_lshl_add_u64 v[156:157], s[16:17], 0, v[156:157]
	v_lshl_add_u64 v[160:161], v[144:145], 1, v[156:157]
	global_load_dwordx4 v[156:159], v[160:161], off
	v_xor_b32_e32 v155, 32, v154
	s_lshl_b32 s36, s8, 2
	s_ashr_i32 s37, s36, 31
	s_waitcnt vmcnt(0)
	v_lshlrev_b32_e32 v162, 16, v156
	v_and_b32_e32 v163, 0xffff0000, v156
	v_lshlrev_b32_e32 v156, 16, v157
	v_and_b32_e32 v157, 0xffff0000, v157
	v_lshlrev_b32_e32 v164, 16, v158
	v_and_b32_e32 v165, 0xffff0000, v158
	v_lshlrev_b32_e32 v158, 16, v159
	v_and_b32_e32 v159, 0xffff0000, v159
	v_pk_add_f32 v[126:127], v[126:127], v[156:157]
	v_pk_add_f32 v[162:163], v[124:125], v[162:163]
	v_pk_add_f32 v[166:167], v[122:123], v[158:159]
	v_pk_add_f32 v[164:165], v[120:121], v[164:165]
	v_cvt_pk_bf16_f32 v122, v162, v163
	v_cvt_pk_bf16_f32 v123, v126, v127
	v_mul_f32_e32 v163, v163, v163
	v_cvt_pk_bf16_f32 v124, v164, v165
	v_cvt_pk_bf16_f32 v125, v166, v167
	global_load_dwordx4 v[156:159], v[160:161], off offset:64
	v_mul_f32_e32 v127, v127, v127
	v_mul_f32_e32 v165, v165, v165
	v_fmac_f32_e32 v163, v162, v162
	v_fmac_f32_e32 v127, v126, v126
	v_mul_f32_e32 v167, v167, v167
	v_fmac_f32_e32 v165, v164, v164
	v_add_f32_e32 v126, v163, v127
	v_fmac_f32_e32 v167, v166, v166
	v_add_f32_e32 v126, v165, v126
	v_add_f32_e32 v164, v167, v126
	v_and_b32_e32 v121, 64, v154
	v_xor_b32_e32 v120, 16, v154
	v_add_u32_e32 v121, 64, v121
	v_cmp_lt_i32_e32 vcc, v120, v121
	global_store_dwordx4 v[160:161], v[122:125], off
	s_waitcnt vmcnt(1)
	v_lshlrev_b32_e32 v162, 16, v156
	v_and_b32_e32 v163, 0xffff0000, v156
	v_lshlrev_b32_e32 v156, 16, v157
	v_and_b32_e32 v157, 0xffff0000, v157
	v_lshlrev_b32_e32 v126, 16, v158
	v_and_b32_e32 v127, 0xffff0000, v158
	v_pk_add_f32 v[118:119], v[118:119], v[156:157]
	v_pk_add_f32 v[116:117], v[116:117], v[162:163]
	v_lshlrev_b32_e32 v158, 16, v159
	v_and_b32_e32 v159, 0xffff0000, v159
	v_pk_add_f32 v[126:127], v[112:113], v[126:127]
	v_mul_f32_e32 v112, v117, v117
	v_mul_f32_e32 v113, v119, v119
	v_pk_add_f32 v[156:157], v[114:115], v[158:159]
	v_mul_f32_e32 v114, v127, v127
	v_fmac_f32_e32 v112, v116, v116
	v_fmac_f32_e32 v113, v118, v118
	v_mul_f32_e32 v115, v157, v157
	v_fmac_f32_e32 v114, v126, v126
	v_add_f32_e32 v112, v112, v113
	v_fmac_f32_e32 v115, v156, v156
	v_add_f32_e32 v112, v112, v114
	v_cndmask_b32_e32 v120, v154, v120, vcc
	v_add_f32_e32 v112, v115, v112
	v_lshlrev_b32_e32 v120, 2, v120
	v_add_f32_e32 v112, v164, v112
	ds_bpermute_b32 v113, v120, v112
	v_cmp_lt_i32_e32 vcc, v155, v121
	v_cvt_pk_bf16_f32 v116, v116, v117
	v_cvt_pk_bf16_f32 v117, v118, v119
	v_cvt_pk_bf16_f32 v118, v126, v127
	s_waitcnt lgkmcnt(0)
	v_add_f32_e32 v112, v112, v113
	v_cvt_pk_bf16_f32 v119, v156, v157
	v_cndmask_b32_e32 v114, v154, v155, vcc
	v_lshlrev_b32_e32 v114, 2, v114
	ds_bpermute_b32 v113, v114, v112
	global_store_dwordx4 v[160:161], v[116:119], off offset:64
	s_and_saveexec_b64 s[38:39], s[0:1]
	s_cbranch_execz .LBB0_1163
	v_lshlrev_b64 v[116:117], 6, v[146:147]
	v_lshl_add_u64 v[116:117], s[14:15], 0, v[116:117]
	v_lshl_add_u64 v[116:117], s[36:37], 2, v[116:117]
	s_lshl_b32 s8, s46, 2
	v_lshl_add_u64 v[116:117], v[116:117], 0, s[8:9]
	s_waitcnt lgkmcnt(0)
	v_add_f32_e32 v112, v112, v113
	global_store_dword v[116:117], v112, off
.LBB0_1163:
	s_or_b64 exec, exec, s[38:39]
	v_or_b32_e32 v112, 16, v146
	s_waitcnt lgkmcnt(0)
	v_ashrrev_i32_e32 v113, 31, v112
	v_lshlrev_b64 v[116:117], 11, v[112:113]
	v_lshl_add_u64 v[116:117], s[16:17], 0, v[116:117]
	v_lshl_add_u64 v[122:123], v[144:145], 1, v[116:117]
	global_load_dwordx4 v[116:119], v[122:123], off
	s_waitcnt vmcnt(0)
	v_lshlrev_b32_e32 v124, 16, v116
	v_and_b32_e32 v125, 0xffff0000, v116
	v_lshlrev_b32_e32 v116, 16, v117
	v_and_b32_e32 v117, 0xffff0000, v117
	v_lshlrev_b32_e32 v126, 16, v118
	v_and_b32_e32 v127, 0xffff0000, v118
	v_lshlrev_b32_e32 v118, 16, v119
	v_and_b32_e32 v119, 0xffff0000, v119
	v_pk_add_f32 v[116:117], v[110:111], v[116:117]
	v_pk_add_f32 v[124:125], v[108:109], v[124:125]
	v_pk_add_f32 v[118:119], v[106:107], v[118:119]
	v_pk_add_f32 v[126:127], v[104:105], v[126:127]
	v_cvt_pk_bf16_f32 v104, v124, v125
	v_cvt_pk_bf16_f32 v105, v116, v117
	v_mul_f32_e32 v115, v125, v125
	v_cvt_pk_bf16_f32 v106, v126, v127
	v_cvt_pk_bf16_f32 v107, v118, v119
	global_load_dwordx4 v[108:111], v[122:123], off offset:64
	v_mul_f32_e32 v117, v117, v117
	v_mul_f32_e32 v121, v127, v127
	v_fmac_f32_e32 v115, v124, v124
	v_fmac_f32_e32 v117, v116, v116
	v_mul_f32_e32 v119, v119, v119
	v_fmac_f32_e32 v121, v126, v126
	v_add_f32_e32 v115, v115, v117
	v_fmac_f32_e32 v119, v118, v118
	v_add_f32_e32 v115, v121, v115
	v_add_f32_e32 v115, v119, v115
	global_store_dwordx4 v[122:123], v[104:107], off
	s_waitcnt vmcnt(1)
	v_lshlrev_b32_e32 v118, 16, v108
	v_and_b32_e32 v119, 0xffff0000, v108
	v_lshlrev_b32_e32 v108, 16, v109
	v_and_b32_e32 v109, 0xffff0000, v109
	v_lshlrev_b32_e32 v116, 16, v110
	v_and_b32_e32 v117, 0xffff0000, v110
	v_lshlrev_b32_e32 v110, 16, v111
	v_and_b32_e32 v111, 0xffff0000, v111
	v_pk_add_f32 v[102:103], v[102:103], v[108:109]
	v_pk_add_f32 v[100:101], v[100:101], v[118:119]
	v_pk_add_f32 v[108:109], v[98:99], v[110:111]
	v_pk_add_f32 v[110:111], v[96:97], v[116:117]
	v_mul_f32_e32 v96, v101, v101
	v_mul_f32_e32 v97, v103, v103
	v_mul_f32_e32 v98, v111, v111
	v_fmac_f32_e32 v96, v100, v100
	v_fmac_f32_e32 v97, v102, v102
	v_mul_f32_e32 v99, v109, v109
	v_fmac_f32_e32 v98, v110, v110
	v_add_f32_e32 v96, v96, v97
	v_add_f32_e32 v96, v96, v98
	v_fmac_f32_e32 v99, v108, v108
	v_add_f32_e32 v96, v99, v96
	v_add_f32_e32 v96, v115, v96
	ds_bpermute_b32 v97, v120, v96
	v_cvt_pk_bf16_f32 v98, v100, v101
	v_cvt_pk_bf16_f32 v99, v102, v103
	v_cvt_pk_bf16_f32 v100, v110, v111
	v_cvt_pk_bf16_f32 v101, v108, v109
	s_waitcnt lgkmcnt(0)
	v_add_f32_e32 v96, v96, v97
	ds_bpermute_b32 v97, v114, v96
	global_store_dwordx4 v[122:123], v[98:101], off offset:64
	s_and_saveexec_b64 s[38:39], s[0:1]
	s_cbranch_execz .LBB0_1165
	v_lshlrev_b64 v[98:99], 6, v[112:113]
	v_lshl_add_u64 v[98:99], s[14:15], 0, v[98:99]
	v_lshl_add_u64 v[98:99], s[36:37], 2, v[98:99]
	s_lshl_b32 s8, s46, 2
	v_lshl_add_u64 v[98:99], v[98:99], 0, s[8:9]
	s_waitcnt lgkmcnt(0)
	v_add_f32_e32 v96, v96, v97
	global_store_dword v[98:99], v96, off
.LBB0_1165:
	s_or_b64 exec, exec, s[38:39]
	v_or_b32_e32 v96, 32, v146
	s_waitcnt lgkmcnt(0)
	v_ashrrev_i32_e32 v97, 31, v96
	v_lshlrev_b64 v[98:99], 11, v[96:97]
	v_lshl_add_u64 v[98:99], s[16:17], 0, v[98:99]
	v_lshl_add_u64 v[102:103], v[144:145], 1, v[98:99]
	global_load_dwordx4 v[98:101], v[102:103], off
	s_waitcnt vmcnt(0)
	v_lshlrev_b32_e32 v104, 16, v98
	v_and_b32_e32 v105, 0xffff0000, v98
	v_lshlrev_b32_e32 v98, 16, v99
	v_and_b32_e32 v99, 0xffff0000, v99
	v_lshlrev_b32_e32 v106, 16, v100
	v_and_b32_e32 v107, 0xffff0000, v100
	v_lshlrev_b32_e32 v100, 16, v101
	v_and_b32_e32 v101, 0xffff0000, v101
	v_pk_add_f32 v[98:99], v[94:95], v[98:99]
	v_pk_add_f32 v[104:105], v[92:93], v[104:105]
	v_pk_add_f32 v[100:101], v[90:91], v[100:101]
	v_pk_add_f32 v[106:107], v[88:89], v[106:107]
	v_cvt_pk_bf16_f32 v88, v104, v105
	v_cvt_pk_bf16_f32 v89, v98, v99
	v_mul_f32_e32 v105, v105, v105
	v_cvt_pk_bf16_f32 v90, v106, v107
	v_cvt_pk_bf16_f32 v91, v100, v101
	global_load_dwordx4 v[92:95], v[102:103], off offset:64
	v_mul_f32_e32 v99, v99, v99
	v_mul_f32_e32 v107, v107, v107
	v_fmac_f32_e32 v105, v104, v104
	v_fmac_f32_e32 v99, v98, v98
	v_mul_f32_e32 v101, v101, v101
	v_fmac_f32_e32 v107, v106, v106
	v_add_f32_e32 v98, v105, v99
	v_fmac_f32_e32 v101, v100, v100
	v_add_f32_e32 v98, v107, v98
	v_add_f32_e32 v104, v101, v98
	global_store_dwordx4 v[102:103], v[88:91], off
	s_waitcnt vmcnt(1)
	v_lshlrev_b32_e32 v100, 16, v92
	v_and_b32_e32 v101, 0xffff0000, v92
	v_lshlrev_b32_e32 v92, 16, v93
	v_and_b32_e32 v93, 0xffff0000, v93
	v_lshlrev_b32_e32 v98, 16, v94
	v_and_b32_e32 v99, 0xffff0000, v94
	v_lshlrev_b32_e32 v94, 16, v95
	v_and_b32_e32 v95, 0xffff0000, v95
	v_pk_add_f32 v[86:87], v[86:87], v[92:93]
	v_pk_add_f32 v[84:85], v[84:85], v[100:101]
	v_pk_add_f32 v[92:93], v[82:83], v[94:95]
	v_pk_add_f32 v[94:95], v[80:81], v[98:99]
	v_mul_f32_e32 v80, v85, v85
	v_mul_f32_e32 v81, v87, v87
	v_mul_f32_e32 v82, v95, v95
	v_fmac_f32_e32 v80, v84, v84
	v_fmac_f32_e32 v81, v86, v86
	v_mul_f32_e32 v83, v93, v93
	v_fmac_f32_e32 v82, v94, v94
	v_add_f32_e32 v80, v80, v81
	v_add_f32_e32 v80, v80, v82
	v_fmac_f32_e32 v83, v92, v92
	v_add_f32_e32 v80, v83, v80
	v_add_f32_e32 v80, v104, v80
	ds_bpermute_b32 v81, v120, v80
	v_cvt_pk_bf16_f32 v82, v84, v85
	v_cvt_pk_bf16_f32 v83, v86, v87
	v_cvt_pk_bf16_f32 v84, v94, v95
	v_cvt_pk_bf16_f32 v85, v92, v93
	s_waitcnt lgkmcnt(0)
	v_add_f32_e32 v80, v80, v81
	ds_bpermute_b32 v81, v114, v80
	global_store_dwordx4 v[102:103], v[82:85], off offset:64
	s_and_saveexec_b64 s[38:39], s[0:1]
	s_cbranch_execz .LBB0_1167
	v_lshlrev_b64 v[82:83], 6, v[96:97]
	v_lshl_add_u64 v[82:83], s[14:15], 0, v[82:83]
	v_lshl_add_u64 v[82:83], s[36:37], 2, v[82:83]
	s_lshl_b32 s8, s46, 2
	v_lshl_add_u64 v[82:83], v[82:83], 0, s[8:9]
	s_waitcnt lgkmcnt(0)
	v_add_f32_e32 v80, v80, v81
	global_store_dword v[82:83], v80, off
.LBB0_1167:
	s_or_b64 exec, exec, s[38:39]
	v_or_b32_e32 v80, 48, v146
	s_waitcnt lgkmcnt(0)
	v_ashrrev_i32_e32 v81, 31, v80
	v_lshlrev_b64 v[82:83], 11, v[80:81]
	v_lshl_add_u64 v[82:83], s[16:17], 0, v[82:83]
	v_lshl_add_u64 v[86:87], v[144:145], 1, v[82:83]
	global_load_dwordx4 v[82:85], v[86:87], off
	s_waitcnt vmcnt(0)
	v_lshlrev_b32_e32 v88, 16, v82
	v_and_b32_e32 v89, 0xffff0000, v82
	v_lshlrev_b32_e32 v82, 16, v83
	v_and_b32_e32 v83, 0xffff0000, v83
	v_lshlrev_b32_e32 v90, 16, v84
	v_and_b32_e32 v91, 0xffff0000, v84
	v_lshlrev_b32_e32 v84, 16, v85
	v_and_b32_e32 v85, 0xffff0000, v85
	v_pk_add_f32 v[82:83], v[78:79], v[82:83]
	v_pk_add_f32 v[88:89], v[76:77], v[88:89]
	v_pk_add_f32 v[84:85], v[74:75], v[84:85]
	v_pk_add_f32 v[90:91], v[72:73], v[90:91]
	v_cvt_pk_bf16_f32 v72, v88, v89
	v_cvt_pk_bf16_f32 v73, v82, v83
	v_mul_f32_e32 v89, v89, v89
	v_cvt_pk_bf16_f32 v74, v90, v91
	v_cvt_pk_bf16_f32 v75, v84, v85
	global_load_dwordx4 v[76:79], v[86:87], off offset:64
	v_mul_f32_e32 v83, v83, v83
	v_mul_f32_e32 v91, v91, v91
	v_fmac_f32_e32 v89, v88, v88
	v_fmac_f32_e32 v83, v82, v82
	v_mul_f32_e32 v85, v85, v85
	v_fmac_f32_e32 v91, v90, v90
	v_add_f32_e32 v82, v89, v83
	v_fmac_f32_e32 v85, v84, v84
	v_add_f32_e32 v82, v91, v82
	v_add_f32_e32 v88, v85, v82
	global_store_dwordx4 v[86:87], v[72:75], off
	s_waitcnt vmcnt(1)
	v_lshlrev_b32_e32 v84, 16, v76
	v_and_b32_e32 v85, 0xffff0000, v76
	v_lshlrev_b32_e32 v76, 16, v77
	v_and_b32_e32 v77, 0xffff0000, v77
	v_lshlrev_b32_e32 v82, 16, v78
	v_and_b32_e32 v83, 0xffff0000, v78
	v_lshlrev_b32_e32 v78, 16, v79
	v_and_b32_e32 v79, 0xffff0000, v79
	v_pk_add_f32 v[70:71], v[70:71], v[76:77]
	v_pk_add_f32 v[68:69], v[68:69], v[84:85]
	v_pk_add_f32 v[76:77], v[66:67], v[78:79]
	v_pk_add_f32 v[78:79], v[64:65], v[82:83]
	v_mul_f32_e32 v64, v69, v69
	v_mul_f32_e32 v65, v71, v71
	v_mul_f32_e32 v66, v79, v79
	v_fmac_f32_e32 v64, v68, v68
	v_fmac_f32_e32 v65, v70, v70
	v_mul_f32_e32 v67, v77, v77
	v_fmac_f32_e32 v66, v78, v78
	v_add_f32_e32 v64, v64, v65
	v_add_f32_e32 v64, v64, v66
	v_fmac_f32_e32 v67, v76, v76
	v_add_f32_e32 v64, v67, v64
	v_add_f32_e32 v64, v88, v64
	ds_bpermute_b32 v65, v120, v64
	v_cvt_pk_bf16_f32 v66, v68, v69
	v_cvt_pk_bf16_f32 v67, v70, v71
	v_cvt_pk_bf16_f32 v68, v78, v79
	v_cvt_pk_bf16_f32 v69, v76, v77
	s_waitcnt lgkmcnt(0)
	v_add_f32_e32 v64, v64, v65
	ds_bpermute_b32 v65, v114, v64
	global_store_dwordx4 v[86:87], v[66:69], off offset:64
	s_and_saveexec_b64 s[38:39], s[0:1]
	s_cbranch_execz .LBB0_1169
	v_lshlrev_b64 v[66:67], 6, v[80:81]
	v_lshl_add_u64 v[66:67], s[14:15], 0, v[66:67]
	v_lshl_add_u64 v[66:67], s[36:37], 2, v[66:67]
	s_lshl_b32 s8, s46, 2
	v_lshl_add_u64 v[66:67], v[66:67], 0, s[8:9]
	s_waitcnt lgkmcnt(0)
	v_add_f32_e32 v64, v64, v65
	global_store_dword v[66:67], v64, off
.LBB0_1169:
	s_or_b64 exec, exec, s[38:39]
	v_add_u32_e32 v64, 0x80, v146
	s_waitcnt lgkmcnt(0)
	v_ashrrev_i32_e32 v65, 31, v64
	v_lshlrev_b64 v[66:67], 11, v[64:65]
	v_lshl_add_u64 v[66:67], s[16:17], 0, v[66:67]
	v_lshl_add_u64 v[70:71], v[144:145], 1, v[66:67]
	global_load_dwordx4 v[66:69], v[70:71], off
	s_waitcnt vmcnt(0)
	v_lshlrev_b32_e32 v72, 16, v66
	v_and_b32_e32 v73, 0xffff0000, v66
	v_lshlrev_b32_e32 v66, 16, v67
	v_and_b32_e32 v67, 0xffff0000, v67
	v_lshlrev_b32_e32 v74, 16, v68
	v_and_b32_e32 v75, 0xffff0000, v68
	v_lshlrev_b32_e32 v68, 16, v69
	v_and_b32_e32 v69, 0xffff0000, v69
	v_pk_add_f32 v[66:67], v[62:63], v[66:67]
	v_pk_add_f32 v[72:73], v[60:61], v[72:73]
	v_pk_add_f32 v[68:69], v[58:59], v[68:69]
	v_pk_add_f32 v[74:75], v[56:57], v[74:75]
	v_cvt_pk_bf16_f32 v56, v72, v73
	v_cvt_pk_bf16_f32 v57, v66, v67
	v_mul_f32_e32 v73, v73, v73
	v_cvt_pk_bf16_f32 v58, v74, v75
	v_cvt_pk_bf16_f32 v59, v68, v69
	global_load_dwordx4 v[60:63], v[70:71], off offset:64
	v_mul_f32_e32 v67, v67, v67
	v_mul_f32_e32 v75, v75, v75
	v_fmac_f32_e32 v73, v72, v72
	v_fmac_f32_e32 v67, v66, v66
	v_mul_f32_e32 v69, v69, v69
	v_fmac_f32_e32 v75, v74, v74
	v_add_f32_e32 v66, v73, v67
	v_fmac_f32_e32 v69, v68, v68
	v_add_f32_e32 v66, v75, v66
	v_add_f32_e32 v72, v69, v66
	global_store_dwordx4 v[70:71], v[56:59], off
	s_waitcnt vmcnt(1)
	v_lshlrev_b32_e32 v68, 16, v60
	v_and_b32_e32 v69, 0xffff0000, v60
	v_lshlrev_b32_e32 v60, 16, v61
	v_and_b32_e32 v61, 0xffff0000, v61
	v_lshlrev_b32_e32 v66, 16, v62
	v_and_b32_e32 v67, 0xffff0000, v62
	v_lshlrev_b32_e32 v62, 16, v63
	v_and_b32_e32 v63, 0xffff0000, v63
	v_pk_add_f32 v[54:55], v[54:55], v[60:61]
	v_pk_add_f32 v[52:53], v[52:53], v[68:69]
	v_pk_add_f32 v[60:61], v[50:51], v[62:63]
	v_pk_add_f32 v[62:63], v[48:49], v[66:67]
	v_mul_f32_e32 v48, v53, v53
	v_mul_f32_e32 v49, v55, v55
	v_mul_f32_e32 v50, v63, v63
	v_fmac_f32_e32 v48, v52, v52
	v_fmac_f32_e32 v49, v54, v54
	v_mul_f32_e32 v51, v61, v61
	v_fmac_f32_e32 v50, v62, v62
	v_add_f32_e32 v48, v48, v49
	v_add_f32_e32 v48, v48, v50
	v_fmac_f32_e32 v51, v60, v60
	v_add_f32_e32 v48, v51, v48
	v_add_f32_e32 v48, v72, v48
	ds_bpermute_b32 v49, v120, v48
	v_cvt_pk_bf16_f32 v50, v52, v53
	v_cvt_pk_bf16_f32 v51, v54, v55
	v_cvt_pk_bf16_f32 v52, v62, v63
	v_cvt_pk_bf16_f32 v53, v60, v61
	s_waitcnt lgkmcnt(0)
	v_add_f32_e32 v48, v48, v49
	ds_bpermute_b32 v49, v114, v48
	global_store_dwordx4 v[70:71], v[50:53], off offset:64
	s_and_saveexec_b64 s[38:39], s[0:1]
	s_cbranch_execz .LBB0_1171
	v_lshlrev_b64 v[50:51], 6, v[64:65]
	v_lshl_add_u64 v[50:51], s[14:15], 0, v[50:51]
	v_lshl_add_u64 v[50:51], s[36:37], 2, v[50:51]
	s_lshl_b32 s8, s46, 2
	v_lshl_add_u64 v[50:51], v[50:51], 0, s[8:9]
	s_waitcnt lgkmcnt(0)
	v_add_f32_e32 v48, v48, v49
	global_store_dword v[50:51], v48, off
.LBB0_1171:
	s_or_b64 exec, exec, s[38:39]
	v_add_u32_e32 v48, 0x90, v146
	s_waitcnt lgkmcnt(0)
	v_ashrrev_i32_e32 v49, 31, v48
	v_lshlrev_b64 v[50:51], 11, v[48:49]
	v_lshl_add_u64 v[50:51], s[16:17], 0, v[50:51]
	v_lshl_add_u64 v[54:55], v[144:145], 1, v[50:51]
	global_load_dwordx4 v[50:53], v[54:55], off
	s_waitcnt vmcnt(0)
	v_lshlrev_b32_e32 v56, 16, v50
	v_and_b32_e32 v57, 0xffff0000, v50
	v_lshlrev_b32_e32 v50, 16, v51
	v_and_b32_e32 v51, 0xffff0000, v51
	v_lshlrev_b32_e32 v58, 16, v52
	v_and_b32_e32 v59, 0xffff0000, v52
	v_lshlrev_b32_e32 v52, 16, v53
	v_and_b32_e32 v53, 0xffff0000, v53
	v_pk_add_f32 v[50:51], v[46:47], v[50:51]
	v_pk_add_f32 v[56:57], v[44:45], v[56:57]
	v_pk_add_f32 v[52:53], v[42:43], v[52:53]
	v_pk_add_f32 v[58:59], v[40:41], v[58:59]
	v_cvt_pk_bf16_f32 v40, v56, v57
	v_cvt_pk_bf16_f32 v41, v50, v51
	v_mul_f32_e32 v57, v57, v57
	v_cvt_pk_bf16_f32 v42, v58, v59
	v_cvt_pk_bf16_f32 v43, v52, v53
	global_load_dwordx4 v[44:47], v[54:55], off offset:64
	v_mul_f32_e32 v51, v51, v51
	v_mul_f32_e32 v59, v59, v59
	v_fmac_f32_e32 v57, v56, v56
	v_fmac_f32_e32 v51, v50, v50
	v_mul_f32_e32 v53, v53, v53
	v_fmac_f32_e32 v59, v58, v58
	v_add_f32_e32 v50, v57, v51
	v_fmac_f32_e32 v53, v52, v52
	v_add_f32_e32 v50, v59, v50
	v_add_f32_e32 v56, v53, v50
	global_store_dwordx4 v[54:55], v[40:43], off
	s_waitcnt vmcnt(1)
	v_lshlrev_b32_e32 v52, 16, v44
	v_and_b32_e32 v53, 0xffff0000, v44
	v_lshlrev_b32_e32 v44, 16, v45
	v_and_b32_e32 v45, 0xffff0000, v45
	v_lshlrev_b32_e32 v50, 16, v46
	v_and_b32_e32 v51, 0xffff0000, v46
	v_lshlrev_b32_e32 v46, 16, v47
	v_and_b32_e32 v47, 0xffff0000, v47
	v_pk_add_f32 v[38:39], v[38:39], v[44:45]
	v_pk_add_f32 v[36:37], v[36:37], v[52:53]
	v_pk_add_f32 v[44:45], v[34:35], v[46:47]
	v_pk_add_f32 v[46:47], v[32:33], v[50:51]
	v_mul_f32_e32 v32, v37, v37
	v_mul_f32_e32 v33, v39, v39
	v_mul_f32_e32 v34, v47, v47
	v_fmac_f32_e32 v32, v36, v36
	v_fmac_f32_e32 v33, v38, v38
	v_mul_f32_e32 v35, v45, v45
	v_fmac_f32_e32 v34, v46, v46
	v_add_f32_e32 v32, v32, v33
	v_add_f32_e32 v32, v32, v34
	v_fmac_f32_e32 v35, v44, v44
	v_add_f32_e32 v32, v35, v32
	v_add_f32_e32 v32, v56, v32
	ds_bpermute_b32 v33, v120, v32
	v_cvt_pk_bf16_f32 v34, v36, v37
	v_cvt_pk_bf16_f32 v35, v38, v39
	v_cvt_pk_bf16_f32 v36, v46, v47
	v_cvt_pk_bf16_f32 v37, v44, v45
	s_waitcnt lgkmcnt(0)
	v_add_f32_e32 v32, v32, v33
	ds_bpermute_b32 v33, v114, v32
	global_store_dwordx4 v[54:55], v[34:37], off offset:64
	s_and_saveexec_b64 s[38:39], s[0:1]
	s_cbranch_execz .LBB0_1173
	v_lshlrev_b64 v[34:35], 6, v[48:49]
	v_lshl_add_u64 v[34:35], s[14:15], 0, v[34:35]
	v_lshl_add_u64 v[34:35], s[36:37], 2, v[34:35]
	s_lshl_b32 s8, s46, 2
	v_lshl_add_u64 v[34:35], v[34:35], 0, s[8:9]
	s_waitcnt lgkmcnt(0)
	v_add_f32_e32 v32, v32, v33
	global_store_dword v[34:35], v32, off
.LBB0_1173:
	s_or_b64 exec, exec, s[38:39]
	v_add_u32_e32 v32, 0xa0, v146
	s_waitcnt lgkmcnt(0)
	v_ashrrev_i32_e32 v33, 31, v32
	v_lshlrev_b64 v[34:35], 11, v[32:33]
	v_lshl_add_u64 v[34:35], s[16:17], 0, v[34:35]
	v_lshl_add_u64 v[38:39], v[144:145], 1, v[34:35]
	global_load_dwordx4 v[34:37], v[38:39], off
	s_waitcnt vmcnt(0)
	v_lshlrev_b32_e32 v40, 16, v34
	v_and_b32_e32 v41, 0xffff0000, v34
	v_lshlrev_b32_e32 v34, 16, v35
	v_and_b32_e32 v35, 0xffff0000, v35
	v_lshlrev_b32_e32 v42, 16, v36
	v_and_b32_e32 v43, 0xffff0000, v36
	v_lshlrev_b32_e32 v36, 16, v37
	v_and_b32_e32 v37, 0xffff0000, v37
	v_pk_add_f32 v[34:35], v[30:31], v[34:35]
	v_pk_add_f32 v[40:41], v[28:29], v[40:41]
	v_pk_add_f32 v[36:37], v[26:27], v[36:37]
	v_pk_add_f32 v[42:43], v[24:25], v[42:43]
	v_cvt_pk_bf16_f32 v24, v40, v41
	v_cvt_pk_bf16_f32 v25, v34, v35
	v_mul_f32_e32 v41, v41, v41
	v_cvt_pk_bf16_f32 v26, v42, v43
	v_cvt_pk_bf16_f32 v27, v36, v37
	global_load_dwordx4 v[28:31], v[38:39], off offset:64
	v_mul_f32_e32 v35, v35, v35
	v_mul_f32_e32 v43, v43, v43
	v_fmac_f32_e32 v41, v40, v40
	v_fmac_f32_e32 v35, v34, v34
	v_mul_f32_e32 v37, v37, v37
	v_fmac_f32_e32 v43, v42, v42
	v_add_f32_e32 v34, v41, v35
	v_fmac_f32_e32 v37, v36, v36
	v_add_f32_e32 v34, v43, v34
	v_add_f32_e32 v40, v37, v34
	global_store_dwordx4 v[38:39], v[24:27], off
	s_waitcnt vmcnt(1)
	v_lshlrev_b32_e32 v36, 16, v28
	v_and_b32_e32 v37, 0xffff0000, v28
	v_lshlrev_b32_e32 v28, 16, v29
	v_and_b32_e32 v29, 0xffff0000, v29
	v_lshlrev_b32_e32 v34, 16, v30
	v_and_b32_e32 v35, 0xffff0000, v30
	v_lshlrev_b32_e32 v30, 16, v31
	v_and_b32_e32 v31, 0xffff0000, v31
	v_pk_add_f32 v[22:23], v[22:23], v[28:29]
	v_pk_add_f32 v[20:21], v[20:21], v[36:37]
	v_pk_add_f32 v[28:29], v[18:19], v[30:31]
	v_pk_add_f32 v[30:31], v[16:17], v[34:35]
	v_mul_f32_e32 v16, v21, v21
	v_mul_f32_e32 v17, v23, v23
	v_mul_f32_e32 v18, v31, v31
	v_fmac_f32_e32 v16, v20, v20
	v_fmac_f32_e32 v17, v22, v22
	v_mul_f32_e32 v19, v29, v29
	v_fmac_f32_e32 v18, v30, v30
	v_add_f32_e32 v16, v16, v17
	v_add_f32_e32 v16, v16, v18
	v_fmac_f32_e32 v19, v28, v28
	v_add_f32_e32 v16, v19, v16
	v_add_f32_e32 v16, v40, v16
	ds_bpermute_b32 v17, v120, v16
	v_cvt_pk_bf16_f32 v18, v20, v21
	v_cvt_pk_bf16_f32 v19, v22, v23
	v_cvt_pk_bf16_f32 v20, v30, v31
	v_cvt_pk_bf16_f32 v21, v28, v29
	s_waitcnt lgkmcnt(0)
	v_add_f32_e32 v16, v16, v17
	ds_bpermute_b32 v17, v114, v16
	global_store_dwordx4 v[38:39], v[18:21], off offset:64
	s_and_saveexec_b64 s[38:39], s[0:1]
	s_cbranch_execz .LBB0_1175
	v_lshlrev_b64 v[18:19], 6, v[32:33]
	v_lshl_add_u64 v[18:19], s[14:15], 0, v[18:19]
	v_lshl_add_u64 v[18:19], s[36:37], 2, v[18:19]
	s_lshl_b32 s8, s46, 2
	v_lshl_add_u64 v[18:19], v[18:19], 0, s[8:9]
	s_waitcnt lgkmcnt(0)
	v_add_f32_e32 v16, v16, v17
	global_store_dword v[18:19], v16, off
.LBB0_1175:
	s_or_b64 exec, exec, s[38:39]
	v_add_u32_e32 v16, 0xb0, v146
	s_waitcnt lgkmcnt(0)
	v_ashrrev_i32_e32 v17, 31, v16
	v_lshlrev_b64 v[18:19], 11, v[16:17]
	v_lshl_add_u64 v[18:19], s[16:17], 0, v[18:19]
	v_lshl_add_u64 v[22:23], v[144:145], 1, v[18:19]
	global_load_dwordx4 v[18:21], v[22:23], off
	s_waitcnt vmcnt(0)
	v_lshlrev_b32_e32 v24, 16, v18
	v_and_b32_e32 v25, 0xffff0000, v18
	v_lshlrev_b32_e32 v18, 16, v19
	v_and_b32_e32 v19, 0xffff0000, v19
	v_lshlrev_b32_e32 v26, 16, v20
	v_and_b32_e32 v27, 0xffff0000, v20
	v_lshlrev_b32_e32 v20, 16, v21
	v_and_b32_e32 v21, 0xffff0000, v21
	v_pk_add_f32 v[18:19], v[14:15], v[18:19]
	v_pk_add_f32 v[24:25], v[12:13], v[24:25]
	v_pk_add_f32 v[20:21], v[10:11], v[20:21]
	v_pk_add_f32 v[26:27], v[8:9], v[26:27]
	v_cvt_pk_bf16_f32 v8, v24, v25
	v_cvt_pk_bf16_f32 v9, v18, v19
	v_mul_f32_e32 v25, v25, v25
	v_cvt_pk_bf16_f32 v10, v26, v27
	v_cvt_pk_bf16_f32 v11, v20, v21
	global_load_dwordx4 v[12:15], v[22:23], off offset:64
	v_mul_f32_e32 v19, v19, v19
	v_mul_f32_e32 v27, v27, v27
	v_fmac_f32_e32 v25, v24, v24
	v_fmac_f32_e32 v19, v18, v18
	v_mul_f32_e32 v21, v21, v21
	v_fmac_f32_e32 v27, v26, v26
	v_add_f32_e32 v18, v25, v19
	v_fmac_f32_e32 v21, v20, v20
	v_add_f32_e32 v18, v27, v18
	v_add_f32_e32 v24, v21, v18
	global_store_dwordx4 v[22:23], v[8:11], off
	s_waitcnt vmcnt(1)
	v_lshlrev_b32_e32 v20, 16, v12
	v_and_b32_e32 v21, 0xffff0000, v12
	v_lshlrev_b32_e32 v12, 16, v13
	v_and_b32_e32 v13, 0xffff0000, v13
	v_lshlrev_b32_e32 v18, 16, v14
	v_and_b32_e32 v19, 0xffff0000, v14
	v_lshlrev_b32_e32 v14, 16, v15
	v_and_b32_e32 v15, 0xffff0000, v15
	v_pk_add_f32 v[6:7], v[6:7], v[12:13]
	v_pk_add_f32 v[4:5], v[4:5], v[20:21]
	v_pk_add_f32 v[12:13], v[2:3], v[14:15]
	v_pk_add_f32 v[14:15], v[0:1], v[18:19]
	v_mul_f32_e32 v0, v5, v5
	v_mul_f32_e32 v1, v7, v7
	v_mul_f32_e32 v2, v15, v15
	v_fmac_f32_e32 v0, v4, v4
	v_fmac_f32_e32 v1, v6, v6
	v_mul_f32_e32 v3, v13, v13
	v_fmac_f32_e32 v2, v14, v14
	v_add_f32_e32 v0, v0, v1
	v_add_f32_e32 v0, v0, v2
	v_fmac_f32_e32 v3, v12, v12
	v_add_f32_e32 v0, v3, v0
	v_add_f32_e32 v0, v24, v0
	ds_bpermute_b32 v1, v120, v0
	v_cvt_pk_bf16_f32 v2, v4, v5
	v_cvt_pk_bf16_f32 v3, v6, v7
	v_cvt_pk_bf16_f32 v4, v14, v15
	v_cvt_pk_bf16_f32 v5, v12, v13
	s_waitcnt lgkmcnt(0)
	v_add_f32_e32 v0, v0, v1
	ds_bpermute_b32 v1, v114, v0
	global_store_dwordx4 v[22:23], v[2:5], off offset:64
	s_and_saveexec_b64 s[38:39], s[0:1]
	s_cbranch_execz .LBB0_1177
	v_lshlrev_b64 v[2:3], 6, v[16:17]
	v_lshl_add_u64 v[2:3], s[14:15], 0, v[2:3]
	v_lshl_add_u64 v[2:3], s[36:37], 2, v[2:3]
	s_lshl_b32 s8, s46, 2
	v_lshl_add_u64 v[2:3], v[2:3], 0, s[8:9]
	s_waitcnt lgkmcnt(0)
	v_add_f32_e32 v0, v0, v1
	global_store_dword v[2:3], v0, off

.LBB0_1249:
	s_cmp_eq_u32 s51, -2
	s_cselect_b32 s100, s101, 0
	ds_read_b128 v[146:149], v153
	ds_read_b128 v[160:163], v153 offset:1024
	ds_read_b128 v[164:167], v153 offset:2048
	ds_read_b128 v[168:171], v153 offset:3072
	ds_read_b128 v[172:175], v154
	ds_read_b128 v[176:179], v154 offset:1024
	ds_read_b128 v[180:183], v154 offset:2048
	ds_read_b128 v[184:187], v154 offset:3072
	s_add_u32 s34, s26, 0xfffc0080
	s_addc_u32 s35, s27, -1
	s_cmp_eq_u32 s51, 12
	s_cselect_b32 s37, s19, s35
	s_cselect_b32 s36, s47, s34
	s_cselect_b32 s35, s21, s50
	s_cselect_b32 s34, s48, s49
	v_lshl_add_u64 v[188:189], s[26:27], 0, v[138:139]
	s_add_i32 m0, s30, 0xc000
	ds_read_b128 v[194:197], v155
	ds_read_b128 v[198:201], v155 offset:1024
	ds_read_b128 v[202:205], v155 offset:2048
	ds_read_b128 v[206:209], v155 offset:3072
	ds_read_b128 v[210:213], v155 offset:4096
	ds_read_b128 v[214:217], v155 offset:5120
	ds_read_b128 v[218:221], v155 offset:6144
	ds_read_b128 v[222:225], v155 offset:7168
	global_load_lds_dwordx4 v[188:189], off
	v_lshl_add_u64 v[188:189], s[26:27], 0, v[140:141]
	s_add_i32 m0, s30, 0xe000
	s_nop 0
	global_load_lds_dwordx4 v[188:189], off
	s_cmp_lg_u32 s100, 0
	s_cbranch_scc1 .Lrw_g7_0
	s_waitcnt vmcnt(8)
.Lrw_g7_0:
	s_waitcnt lgkmcnt(0)
	s_barrier
	s_setprio 1
	s_waitcnt lgkmcnt(0)
	v_mfma_f32_16x16x32_bf16 v[124:127], v[146:149], v[194:197], v[124:127]
	v_mfma_f32_16x16x32_bf16 v[120:123], v[164:167], v[194:197], v[120:123]
	v_mfma_f32_16x16x32_bf16 v[108:111], v[146:149], v[202:205], v[108:111]
	v_mfma_f32_16x16x32_bf16 v[104:107], v[164:167], v[202:205], v[104:107]
	v_mfma_f32_16x16x32_bf16 v[92:95], v[146:149], v[210:213], v[92:95]
	v_mfma_f32_16x16x32_bf16 v[88:91], v[164:167], v[210:213], v[88:91]
	v_mfma_f32_16x16x32_bf16 v[76:79], v[146:149], v[218:221], v[76:79]
	v_mfma_f32_16x16x32_bf16 v[72:75], v[164:167], v[218:221], v[72:75]
	v_mfma_f32_16x16x32_bf16 v[124:127], v[160:163], v[198:201], v[124:127]
	v_mfma_f32_16x16x32_bf16 v[120:123], v[168:171], v[198:201], v[120:123]
	v_mfma_f32_16x16x32_bf16 v[108:111], v[160:163], v[206:209], v[108:111]
	v_mfma_f32_16x16x32_bf16 v[104:107], v[168:171], v[206:209], v[104:107]
	v_mfma_f32_16x16x32_bf16 v[92:95], v[160:163], v[214:217], v[92:95]
	v_mfma_f32_16x16x32_bf16 v[88:91], v[168:171], v[214:217], v[88:91]
	v_mfma_f32_16x16x32_bf16 v[76:79], v[160:163], v[222:225], v[76:79]
	v_mfma_f32_16x16x32_bf16 v[72:75], v[168:171], v[222:225], v[72:75]
	s_setprio 0
	s_setprio 1
	v_mfma_f32_16x16x32_bf16 v[116:119], v[172:175], v[194:197], v[116:119]
	v_mfma_f32_16x16x32_bf16 v[112:115], v[180:183], v[194:197], v[112:115]
	v_mfma_f32_16x16x32_bf16 v[100:103], v[172:175], v[202:205], v[100:103]
	v_mfma_f32_16x16x32_bf16 v[96:99], v[180:183], v[202:205], v[96:99]
	v_mfma_f32_16x16x32_bf16 v[84:87], v[172:175], v[210:213], v[84:87]
	v_mfma_f32_16x16x32_bf16 v[80:83], v[180:183], v[210:213], v[80:83]
	v_mfma_f32_16x16x32_bf16 v[68:71], v[172:175], v[218:221], v[68:71]
	v_mfma_f32_16x16x32_bf16 v[64:67], v[180:183], v[218:221], v[64:67]
	v_mfma_f32_16x16x32_bf16 v[116:119], v[176:179], v[198:201], v[116:119]
	v_mfma_f32_16x16x32_bf16 v[112:115], v[184:187], v[198:201], v[112:115]
	v_mfma_f32_16x16x32_bf16 v[100:103], v[176:179], v[206:209], v[100:103]
	v_mfma_f32_16x16x32_bf16 v[96:99], v[184:187], v[206:209], v[96:99]
	v_mfma_f32_16x16x32_bf16 v[84:87], v[176:179], v[214:217], v[84:87]
	v_mfma_f32_16x16x32_bf16 v[80:83], v[184:187], v[214:217], v[80:83]
	v_mfma_f32_16x16x32_bf16 v[68:71], v[176:179], v[222:225], v[68:71]
	v_mfma_f32_16x16x32_bf16 v[64:67], v[184:187], v[222:225], v[64:67]
	s_setprio 0
	s_barrier
	s_add_i32 s62, s44, s29
	v_lshl_add_u64 v[188:189], s[34:35], 0, v[130:131]
	s_mov_b32 m0, s62
	ds_read_b128 v[194:197], v155 offset:16384
	ds_read_b128 v[198:201], v155 offset:17408
	ds_read_b128 v[202:205], v155 offset:18432
	ds_read_b128 v[206:209], v155 offset:19456
	ds_read_b128 v[210:213], v155 offset:20480
	ds_read_b128 v[214:217], v155 offset:21504
	ds_read_b128 v[218:221], v155 offset:22528
	ds_read_b128 v[222:225], v155 offset:23552
	global_load_lds_dwordx4 v[188:189], off
	s_add_i32 m0, s62, 0x2000
	s_add_u32 s62, s34, 0x40000
	v_lshl_add_u64 v[226:227], s[34:35], 0, v[134:135]
	s_addc_u32 s63, s35, 0
	s_add_i32 s64, s45, s29
	global_load_lds_dwordx4 v[226:227], off
	v_lshl_add_u64 v[228:229], s[62:63], 0, v[130:131]
	s_mov_b32 m0, s64
	v_lshl_add_u64 v[230:231], s[36:37], 0, v[132:133]
	global_load_lds_dwordx4 v[228:229], off
	v_lshl_add_u64 v[228:229], s[62:63], 0, v[134:135]
	s_add_i32 m0, s64, 0x2000
	s_nop 0
	global_load_lds_dwordx4 v[228:229], off
	v_lshl_add_u64 v[228:229], s[36:37], 0, v[128:129]
	s_mov_b32 m0, s30
	s_nop 0
	global_load_lds_dwordx4 v[228:229], off
	s_mov_b32 m0, s31
	s_nop 0
	global_load_lds_dwordx4 v[230:231], off
	s_cmp_lg_u32 s100, 0
	s_cbranch_scc1 .Lrw_g7_1
	s_waitcnt vmcnt(8)
.Lrw_g7_1:
	s_waitcnt lgkmcnt(0)
	s_barrier
	s_setprio 1
	s_waitcnt lgkmcnt(0)
	v_mfma_f32_16x16x32_bf16 v[60:63], v[146:149], v[194:197], v[60:63]
	v_mfma_f32_16x16x32_bf16 v[56:59], v[164:167], v[194:197], v[56:59]
	v_mfma_f32_16x16x32_bf16 v[44:47], v[146:149], v[202:205], v[44:47]
	v_mfma_f32_16x16x32_bf16 v[40:43], v[164:167], v[202:205], v[40:43]
	v_mfma_f32_16x16x32_bf16 v[28:31], v[146:149], v[210:213], v[28:31]
	v_mfma_f32_16x16x32_bf16 v[24:27], v[164:167], v[210:213], v[24:27]
	v_mfma_f32_16x16x32_bf16 v[12:15], v[146:149], v[218:221], v[12:15]
	v_mfma_f32_16x16x32_bf16 v[8:11], v[164:167], v[218:221], v[8:11]
	v_mfma_f32_16x16x32_bf16 v[60:63], v[160:163], v[198:201], v[60:63]
	v_mfma_f32_16x16x32_bf16 v[56:59], v[168:171], v[198:201], v[56:59]
	v_mfma_f32_16x16x32_bf16 v[44:47], v[160:163], v[206:209], v[44:47]
	v_mfma_f32_16x16x32_bf16 v[40:43], v[168:171], v[206:209], v[40:43]
	v_mfma_f32_16x16x32_bf16 v[28:31], v[160:163], v[214:217], v[28:31]
	v_mfma_f32_16x16x32_bf16 v[24:27], v[168:171], v[214:217], v[24:27]
	v_mfma_f32_16x16x32_bf16 v[12:15], v[160:163], v[222:225], v[12:15]
	v_mfma_f32_16x16x32_bf16 v[8:11], v[168:171], v[222:225], v[8:11]
	s_setprio 0
	s_setprio 1
	v_mfma_f32_16x16x32_bf16 v[52:55], v[172:175], v[194:197], v[52:55]
	v_mfma_f32_16x16x32_bf16 v[48:51], v[180:183], v[194:197], v[48:51]
	v_mfma_f32_16x16x32_bf16 v[36:39], v[172:175], v[202:205], v[36:39]
	v_mfma_f32_16x16x32_bf16 v[32:35], v[180:183], v[202:205], v[32:35]
	v_mfma_f32_16x16x32_bf16 v[20:23], v[172:175], v[210:213], v[20:23]
	v_mfma_f32_16x16x32_bf16 v[16:19], v[180:183], v[210:213], v[16:19]
	v_mfma_f32_16x16x32_bf16 v[4:7], v[172:175], v[218:221], v[4:7]
	v_mfma_f32_16x16x32_bf16 v[0:3], v[180:183], v[218:221], v[0:3]
	v_mfma_f32_16x16x32_bf16 v[52:55], v[176:179], v[198:201], v[52:55]
	v_mfma_f32_16x16x32_bf16 v[48:51], v[184:187], v[198:201], v[48:51]
	v_mfma_f32_16x16x32_bf16 v[36:39], v[176:179], v[206:209], v[36:39]
	v_mfma_f32_16x16x32_bf16 v[32:35], v[184:187], v[206:209], v[32:35]
	v_mfma_f32_16x16x32_bf16 v[20:23], v[176:179], v[214:217], v[20:23]
	v_mfma_f32_16x16x32_bf16 v[16:19], v[184:187], v[214:217], v[16:19]
	v_mfma_f32_16x16x32_bf16 v[4:7], v[176:179], v[222:225], v[4:7]
	v_mfma_f32_16x16x32_bf16 v[0:3], v[184:187], v[222:225], v[0:3]
	s_setprio 0
	s_barrier
	s_add_i32 s62, 0, 0x18000
	v_add_u32_e32 v159, s62, v151
	s_add_i32 s63, 0, 0x1c000
	ds_read_b128 v[146:149], v159
	ds_read_b128 v[160:163], v159 offset:1024
	ds_read_b128 v[164:167], v159 offset:2048
	ds_read_b128 v[168:171], v159 offset:3072
	v_add_u32_e32 v159, s63, v151
	ds_read_b128 v[172:175], v159
	ds_read_b128 v[176:179], v159 offset:1024
	ds_read_b128 v[180:183], v159 offset:2048
	ds_read_b128 v[184:187], v159 offset:3072
	s_add_u32 s36, s36, 0x40000
	s_addc_u32 s37, s37, 0
	s_mov_b32 m0, s33
	v_lshl_add_u64 v[232:233], s[36:37], 0, v[128:129]
	ds_read_b128 v[194:197], v155 offset:32768
	ds_read_b128 v[198:201], v155 offset:33792
	ds_read_b128 v[202:205], v155 offset:34816
	ds_read_b128 v[206:209], v155 offset:35840
	ds_read_b128 v[210:213], v155 offset:36864
	ds_read_b128 v[214:217], v155 offset:37888
	ds_read_b128 v[218:221], v155 offset:38912
	ds_read_b128 v[222:225], v155 offset:39936
	global_load_lds_dwordx4 v[232:233], off
	v_lshl_add_u64 v[232:233], s[36:37], 0, v[132:133]
	s_mov_b32 m0, s38
	s_nop 0
	global_load_lds_dwordx4 v[232:233], off
	s_waitcnt vmcnt(8)
	s_waitcnt lgkmcnt(0)
	s_barrier
	s_setprio 1
	s_waitcnt lgkmcnt(0)
	v_mfma_f32_16x16x32_bf16 v[124:127], v[146:149], v[194:197], v[124:127]
	v_mfma_f32_16x16x32_bf16 v[120:123], v[164:167], v[194:197], v[120:123]
	v_mfma_f32_16x16x32_bf16 v[108:111], v[146:149], v[202:205], v[108:111]
	v_mfma_f32_16x16x32_bf16 v[104:107], v[164:167], v[202:205], v[104:107]
	v_mfma_f32_16x16x32_bf16 v[92:95], v[146:149], v[210:213], v[92:95]
	v_mfma_f32_16x16x32_bf16 v[88:91], v[164:167], v[210:213], v[88:91]
	v_mfma_f32_16x16x32_bf16 v[76:79], v[146:149], v[218:221], v[76:79]
	v_mfma_f32_16x16x32_bf16 v[72:75], v[164:167], v[218:221], v[72:75]
	v_mfma_f32_16x16x32_bf16 v[124:127], v[160:163], v[198:201], v[124:127]
	v_mfma_f32_16x16x32_bf16 v[120:123], v[168:171], v[198:201], v[120:123]
	v_mfma_f32_16x16x32_bf16 v[108:111], v[160:163], v[206:209], v[108:111]
	v_mfma_f32_16x16x32_bf16 v[104:107], v[168:171], v[206:209], v[104:107]
	v_mfma_f32_16x16x32_bf16 v[92:95], v[160:163], v[214:217], v[92:95]
	v_mfma_f32_16x16x32_bf16 v[88:91], v[168:171], v[214:217], v[88:91]
	v_mfma_f32_16x16x32_bf16 v[76:79], v[160:163], v[222:225], v[76:79]
	v_mfma_f32_16x16x32_bf16 v[72:75], v[168:171], v[222:225], v[72:75]
	s_setprio 0
	s_setprio 1
	v_mfma_f32_16x16x32_bf16 v[116:119], v[172:175], v[194:197], v[116:119]
	v_mfma_f32_16x16x32_bf16 v[112:115], v[180:183], v[194:197], v[112:115]
	v_mfma_f32_16x16x32_bf16 v[100:103], v[172:175], v[202:205], v[100:103]
	v_mfma_f32_16x16x32_bf16 v[96:99], v[180:183], v[202:205], v[96:99]
	v_mfma_f32_16x16x32_bf16 v[84:87], v[172:175], v[210:213], v[84:87]
	v_mfma_f32_16x16x32_bf16 v[80:83], v[180:183], v[210:213], v[80:83]
	v_mfma_f32_16x16x32_bf16 v[68:71], v[172:175], v[218:221], v[68:71]
	v_mfma_f32_16x16x32_bf16 v[64:67], v[180:183], v[218:221], v[64:67]
	v_mfma_f32_16x16x32_bf16 v[116:119], v[176:179], v[198:201], v[116:119]
	v_mfma_f32_16x16x32_bf16 v[112:115], v[184:187], v[198:201], v[112:115]
	v_mfma_f32_16x16x32_bf16 v[100:103], v[176:179], v[206:209], v[100:103]
	v_mfma_f32_16x16x32_bf16 v[96:99], v[184:187], v[206:209], v[96:99]
	v_mfma_f32_16x16x32_bf16 v[84:87], v[176:179], v[214:217], v[84:87]
	v_mfma_f32_16x16x32_bf16 v[80:83], v[184:187], v[214:217], v[80:83]
	v_mfma_f32_16x16x32_bf16 v[68:71], v[176:179], v[222:225], v[68:71]
	v_mfma_f32_16x16x32_bf16 v[64:67], v[184:187], v[222:225], v[64:67]
	s_setprio 0
	s_barrier
	s_add_i32 s36, s62, s29
	v_lshl_add_u64 v[188:189], v[188:189], 0, s[12:13]
	s_mov_b32 m0, s36
	ds_read_b128 v[194:197], v155 offset:49152
	ds_read_b128 v[198:201], v155 offset:50176
	ds_read_b128 v[202:205], v155 offset:51200
	ds_read_b128 v[206:209], v155 offset:52224
	ds_read_b128 v[210:213], v155 offset:53248
	ds_read_b128 v[214:217], v155 offset:54272
	ds_read_b128 v[218:221], v155 offset:55296
	ds_read_b128 v[222:225], v155 offset:56320
	global_load_lds_dwordx4 v[188:189], off
	s_add_i32 m0, s36, 0x2000
	s_add_u32 s34, s34, 0x40080
	v_lshl_add_u64 v[188:189], v[226:227], 0, s[12:13]
	s_addc_u32 s35, s35, 0
	s_add_i32 s36, s63, s29
	global_load_lds_dwordx4 v[188:189], off
	v_lshl_add_u64 v[188:189], s[34:35], 0, v[130:131]
	s_mov_b32 m0, s36
	s_nop 0
	global_load_lds_dwordx4 v[188:189], off
	v_lshl_add_u64 v[188:189], s[34:35], 0, v[134:135]
	s_add_i32 m0, s36, 0x2000
	s_nop 0
	global_load_lds_dwordx4 v[188:189], off
	v_lshl_add_u64 v[188:189], v[228:229], 0, s[12:13]
	s_mov_b32 m0, s40
	s_nop 0
	global_load_lds_dwordx4 v[188:189], off
	v_lshl_add_u64 v[188:189], v[230:231], 0, s[12:13]
	s_mov_b32 m0, s41
	s_nop 0
	global_load_lds_dwordx4 v[188:189], off
	s_waitcnt vmcnt(8)
	s_waitcnt lgkmcnt(0)
	s_barrier
	s_setprio 1
	s_waitcnt lgkmcnt(0)
	v_mfma_f32_16x16x32_bf16 v[60:63], v[146:149], v[194:197], v[60:63]
	v_mfma_f32_16x16x32_bf16 v[56:59], v[164:167], v[194:197], v[56:59]
	v_mfma_f32_16x16x32_bf16 v[44:47], v[146:149], v[202:205], v[44:47]
	v_mfma_f32_16x16x32_bf16 v[40:43], v[164:167], v[202:205], v[40:43]
	v_mfma_f32_16x16x32_bf16 v[28:31], v[146:149], v[210:213], v[28:31]
	v_mfma_f32_16x16x32_bf16 v[24:27], v[164:167], v[210:213], v[24:27]
	v_mfma_f32_16x16x32_bf16 v[12:15], v[146:149], v[218:221], v[12:15]
	v_mfma_f32_16x16x32_bf16 v[8:11], v[164:167], v[218:221], v[8:11]
	v_mfma_f32_16x16x32_bf16 v[60:63], v[160:163], v[198:201], v[60:63]
	v_mfma_f32_16x16x32_bf16 v[56:59], v[168:171], v[198:201], v[56:59]
	v_mfma_f32_16x16x32_bf16 v[44:47], v[160:163], v[206:209], v[44:47]
	v_mfma_f32_16x16x32_bf16 v[40:43], v[168:171], v[206:209], v[40:43]
	v_mfma_f32_16x16x32_bf16 v[28:31], v[160:163], v[214:217], v[28:31]
	v_mfma_f32_16x16x32_bf16 v[24:27], v[168:171], v[214:217], v[24:27]
	v_mfma_f32_16x16x32_bf16 v[12:15], v[160:163], v[222:225], v[12:15]
	v_mfma_f32_16x16x32_bf16 v[8:11], v[168:171], v[222:225], v[8:11]
	s_setprio 0
	s_setprio 1
	v_mfma_f32_16x16x32_bf16 v[52:55], v[172:175], v[194:197], v[52:55]
	v_mfma_f32_16x16x32_bf16 v[48:51], v[180:183], v[194:197], v[48:51]
	v_mfma_f32_16x16x32_bf16 v[36:39], v[172:175], v[202:205], v[36:39]
	v_mfma_f32_16x16x32_bf16 v[32:35], v[180:183], v[202:205], v[32:35]
	v_mfma_f32_16x16x32_bf16 v[20:23], v[172:175], v[210:213], v[20:23]
	v_mfma_f32_16x16x32_bf16 v[16:19], v[180:183], v[210:213], v[16:19]
	v_mfma_f32_16x16x32_bf16 v[4:7], v[172:175], v[218:221], v[4:7]
	v_mfma_f32_16x16x32_bf16 v[0:3], v[180:183], v[218:221], v[0:3]
	v_mfma_f32_16x16x32_bf16 v[52:55], v[176:179], v[198:201], v[52:55]
	v_mfma_f32_16x16x32_bf16 v[48:51], v[184:187], v[198:201], v[48:51]
	v_mfma_f32_16x16x32_bf16 v[36:39], v[176:179], v[206:209], v[36:39]
	v_mfma_f32_16x16x32_bf16 v[32:35], v[184:187], v[206:209], v[32:35]
	v_mfma_f32_16x16x32_bf16 v[20:23], v[176:179], v[214:217], v[20:23]
	v_mfma_f32_16x16x32_bf16 v[16:19], v[184:187], v[214:217], v[16:19]
	v_mfma_f32_16x16x32_bf16 v[4:7], v[176:179], v[222:225], v[4:7]
	v_mfma_f32_16x16x32_bf16 v[0:3], v[184:187], v[222:225], v[0:3]
	s_setprio 0
	s_barrier
	s_add_i32 s51, s51, 2
	s_add_u32 s26, s26, 0x100
	s_addc_u32 s27, s27, 0
	s_add_u32 s49, s49, 0x100
	s_addc_u32 s50, s50, 0
	s_cmp_gt_u32 s51, 13
	s_cbranch_scc0 .LBB0_1249
	s_and_b64 vcc, exec, s[14:15]
	s_cbranch_vccz .LBB0_1252
	s_barrier

.LBB0_1316:
	s_add_u32 s14, s56, 0xa00000
	s_mov_b64 s[18:19], 0x80
	s_addc_u32 s15, s57, 0
	s_and_b32 s44, s1, 3
	s_add_i32 m0, s29, 0x18000
	v_lshl_add_u64 v[6:7], v[6:7], 0, s[18:19]
	s_lshl_b32 s1, s0, 13
	s_lshl_b32 s21, s44, 12
	s_ashr_i32 s45, s2, 31
	s_waitcnt vmcnt(2)
	s_barrier
	global_load_lds_dwordx4 v[6:7], off
	v_lshl_add_u64 v[4:5], v[4:5], 0, s[18:19]
	s_add_i32 m0, s29, 0x1a000
	s_add_i32 s46, s29, 0x8000
	s_add_i32 s47, s29, 0xa000
	global_load_lds_dwordx4 v[4:5], off
	v_lshl_add_u64 v[0:1], v[0:1], 0, s[18:19]
	s_mov_b32 m0, s46
	s_add_u32 s4, s40, 0x100080
	global_load_lds_dwordx4 v[0:1], off
	v_lshl_add_u64 v[0:1], v[2:3], 0, s[18:19]
	s_mov_b32 m0, s47
	s_addc_u32 s5, s41, 0
	global_load_lds_dwordx4 v[0:1], off
	s_add_i32 m0, s29, 0x1c000
	v_lshl_add_u64 v[0:1], s[4:5], 0, v[130:131]
	global_load_lds_dwordx4 v[0:1], off
	v_lshl_add_u64 v[0:1], s[4:5], 0, v[134:135]
	s_add_i32 m0, s29, 0x1e000
	v_lshlrev_b32_e32 v4, 2, v192
	global_load_lds_dwordx4 v[0:1], off
	v_bfe_u32 v0, v192, 4, 2
	v_and_b32_e32 v1, 15, v192
	v_lshlrev_b32_e32 v3, 4, v0
	v_lshl_or_b32 v148, s0, 6, v1
	v_lshl_or_b32 v1, v1, 6, v3
	v_and_b32_e32 v4, 32, v4
	v_lshlrev_b32_e32 v5, 6, v192
	s_movk_i32 s0, 0x3c0
	v_lshlrev_b32_e32 v2, 3, v0
	v_bitop3_b32 v1, v1, s1, v4 bitop3:0xde
	v_and_or_b32 v3, v5, s0, v3
	v_cmp_eq_u32_e64 s[0:1], 0, v0
	v_lshlrev_b32_e32 v0, 10, v192
	v_lshl_or_b32 v150, s44, 6, v2
	v_and_b32_e32 v0, 0xe0000, v0
	v_lshlrev_b32_e32 v2, 13, v10
	v_or3_b32 v0, v8, v0, v2
	v_add_u32_e32 v136, v0, v9
	v_lshlrev_b32_e32 v0, 6, v11
	v_and_b32_e32 v0, 0x1e0000, v0
	s_waitcnt vmcnt(6)
	s_cmpk_lt_u32 s20, 0x100
	v_or3_b32 v0, v8, v0, v2
	v_bitop3_b32 v149, s21, v3, v4 bitop3:0xf6
	s_cselect_b64 s[20:21], -1, 0
	v_add_u32_e32 v138, v0, v9
	s_add_i32 s50, 0, 0x10000
	s_add_i32 s51, 0, 0x14000
	v_mbcnt_lo_u32_b32 v0, -1, 0
	s_ashr_i32 s48, s60, 31
	s_mov_b32 s49, s60
	v_mov_b32_e32 v137, v131
	v_mov_b32_e32 v139, v131
	v_mov_b64_e32 v[140:141], 0x200
	v_mov_b64_e32 v[142:143], 0x1ff
	v_add_u32_e32 v151, s50, v149
	v_add_u32_e32 v152, s51, v149
	v_add_u32_e32 v153, 0, v1
	v_mbcnt_hi_u32_b32 v154, -1, v0
	s_mov_b32 s62, 0
	s_barrier
	s_branch .LBB0_1319

.LBB0_1326:
	s_cmp_eq_u32 s66, -2
	s_cselect_b32 s100, s101, 0
	ds_read_b128 v[144:147], v151
	ds_read_b128 v[156:159], v151 offset:1024
	ds_read_b128 v[160:163], v151 offset:2048
	ds_read_b128 v[164:167], v151 offset:3072
	ds_read_b128 v[168:171], v152
	ds_read_b128 v[172:175], v152 offset:1024
	ds_read_b128 v[176:179], v152 offset:2048
	ds_read_b128 v[180:183], v152 offset:3072
	s_add_u32 s40, s38, 0xfff00080
	s_addc_u32 s41, s39, -1
	s_cmp_eq_u32 s66, 60
	s_cselect_b32 s43, s23, s41
	s_cselect_b32 s42, s37, s40
	s_cselect_b32 s41, s25, s65
	s_cselect_b32 s40, s63, s64
	v_lshl_add_u64 v[188:189], s[38:39], 0, v[136:137]
	s_add_i32 m0, s29, 0xc000
	ds_read_b128 v[184:187], v153
	ds_read_b128 v[194:197], v153 offset:1024
	ds_read_b128 v[198:201], v153 offset:2048
	ds_read_b128 v[202:205], v153 offset:3072
	ds_read_b128 v[206:209], v153 offset:4096
	ds_read_b128 v[210:213], v153 offset:5120
	ds_read_b128 v[214:217], v153 offset:6144
	ds_read_b128 v[218:221], v153 offset:7168
	global_load_lds_dwordx4 v[188:189], off
	v_lshl_add_u64 v[188:189], s[38:39], 0, v[138:139]
	s_add_i32 m0, s29, 0xe000
	s_nop 0
	global_load_lds_dwordx4 v[188:189], off
	s_cmp_lg_u32 s100, 0
	s_cbranch_scc1 .Lrw_g8_0
	s_waitcnt vmcnt(8)
.Lrw_g8_0:
	s_waitcnt lgkmcnt(0)
	s_barrier
	s_setprio 1
	s_waitcnt lgkmcnt(0)
	v_mfma_f32_16x16x32_bf16 v[124:127], v[144:147], v[184:187], v[124:127]
	v_mfma_f32_16x16x32_bf16 v[120:123], v[160:163], v[184:187], v[120:123]
	v_mfma_f32_16x16x32_bf16 v[108:111], v[144:147], v[198:201], v[108:111]
	v_mfma_f32_16x16x32_bf16 v[104:107], v[160:163], v[198:201], v[104:107]
	v_mfma_f32_16x16x32_bf16 v[92:95], v[144:147], v[206:209], v[92:95]
	v_mfma_f32_16x16x32_bf16 v[88:91], v[160:163], v[206:209], v[88:91]
	v_mfma_f32_16x16x32_bf16 v[76:79], v[144:147], v[214:217], v[76:79]
	v_mfma_f32_16x16x32_bf16 v[72:75], v[160:163], v[214:217], v[72:75]
	v_mfma_f32_16x16x32_bf16 v[124:127], v[156:159], v[194:197], v[124:127]
	v_mfma_f32_16x16x32_bf16 v[120:123], v[164:167], v[194:197], v[120:123]
	v_mfma_f32_16x16x32_bf16 v[108:111], v[156:159], v[202:205], v[108:111]
	v_mfma_f32_16x16x32_bf16 v[104:107], v[164:167], v[202:205], v[104:107]
	v_mfma_f32_16x16x32_bf16 v[92:95], v[156:159], v[210:213], v[92:95]
	v_mfma_f32_16x16x32_bf16 v[88:91], v[164:167], v[210:213], v[88:91]
	v_mfma_f32_16x16x32_bf16 v[76:79], v[156:159], v[218:221], v[76:79]
	v_mfma_f32_16x16x32_bf16 v[72:75], v[164:167], v[218:221], v[72:75]
	s_setprio 0
	s_setprio 1
	v_mfma_f32_16x16x32_bf16 v[116:119], v[168:171], v[184:187], v[116:119]
	v_mfma_f32_16x16x32_bf16 v[112:115], v[176:179], v[184:187], v[112:115]
	v_mfma_f32_16x16x32_bf16 v[100:103], v[168:171], v[198:201], v[100:103]
	v_mfma_f32_16x16x32_bf16 v[96:99], v[176:179], v[198:201], v[96:99]
	v_mfma_f32_16x16x32_bf16 v[84:87], v[168:171], v[206:209], v[84:87]
	v_mfma_f32_16x16x32_bf16 v[80:83], v[176:179], v[206:209], v[80:83]
	v_mfma_f32_16x16x32_bf16 v[68:71], v[168:171], v[214:217], v[68:71]
	v_mfma_f32_16x16x32_bf16 v[64:67], v[176:179], v[214:217], v[64:67]
	v_mfma_f32_16x16x32_bf16 v[116:119], v[172:175], v[194:197], v[116:119]
	v_mfma_f32_16x16x32_bf16 v[112:115], v[180:183], v[194:197], v[112:115]
	v_mfma_f32_16x16x32_bf16 v[100:103], v[172:175], v[202:205], v[100:103]
	v_mfma_f32_16x16x32_bf16 v[96:99], v[180:183], v[202:205], v[96:99]
	v_mfma_f32_16x16x32_bf16 v[84:87], v[172:175], v[210:213], v[84:87]
	v_mfma_f32_16x16x32_bf16 v[80:83], v[180:183], v[210:213], v[80:83]
	v_mfma_f32_16x16x32_bf16 v[68:71], v[172:175], v[218:221], v[68:71]
	v_mfma_f32_16x16x32_bf16 v[64:67], v[180:183], v[218:221], v[64:67]
	s_setprio 0
	s_barrier
	s_add_i32 s67, s50, s3
	v_lshl_add_u64 v[188:189], s[40:41], 0, v[130:131]
	s_mov_b32 m0, s67
	ds_read_b128 v[184:187], v153 offset:16384
	ds_read_b128 v[194:197], v153 offset:17408
	ds_read_b128 v[198:201], v153 offset:18432
	ds_read_b128 v[202:205], v153 offset:19456
	ds_read_b128 v[206:209], v153 offset:20480
	ds_read_b128 v[210:213], v153 offset:21504
	ds_read_b128 v[214:217], v153 offset:22528
	ds_read_b128 v[218:221], v153 offset:23552
	global_load_lds_dwordx4 v[188:189], off
	s_add_i32 m0, s67, 0x2000
	s_add_u32 s68, s40, 0x100000
	v_lshl_add_u64 v[222:223], s[40:41], 0, v[134:135]
	s_addc_u32 s69, s41, 0
	s_add_i32 s67, s51, s3
	global_load_lds_dwordx4 v[222:223], off
	v_lshl_add_u64 v[224:225], s[68:69], 0, v[130:131]
	s_mov_b32 m0, s67
	v_lshl_add_u64 v[226:227], s[42:43], 0, v[132:133]
	global_load_lds_dwordx4 v[224:225], off
	v_lshl_add_u64 v[224:225], s[68:69], 0, v[134:135]
	s_add_i32 m0, s67, 0x2000
	s_nop 0
	global_load_lds_dwordx4 v[224:225], off
	v_lshl_add_u64 v[224:225], s[42:43], 0, v[128:129]
	s_mov_b32 m0, s29
	s_nop 0
	global_load_lds_dwordx4 v[224:225], off
	s_mov_b32 m0, s30
	s_nop 0
	global_load_lds_dwordx4 v[226:227], off
	s_cmp_lg_u32 s100, 0
	s_cbranch_scc1 .Lrw_g8_1
	s_waitcnt vmcnt(8)
.Lrw_g8_1:
	s_waitcnt lgkmcnt(0)
	s_barrier
	s_setprio 1
	s_waitcnt lgkmcnt(0)
	v_mfma_f32_16x16x32_bf16 v[60:63], v[144:147], v[184:187], v[60:63]
	v_mfma_f32_16x16x32_bf16 v[56:59], v[160:163], v[184:187], v[56:59]
	v_mfma_f32_16x16x32_bf16 v[44:47], v[144:147], v[198:201], v[44:47]
	v_mfma_f32_16x16x32_bf16 v[40:43], v[160:163], v[198:201], v[40:43]
	v_mfma_f32_16x16x32_bf16 v[28:31], v[144:147], v[206:209], v[28:31]
	v_mfma_f32_16x16x32_bf16 v[24:27], v[160:163], v[206:209], v[24:27]
	v_mfma_f32_16x16x32_bf16 v[12:15], v[144:147], v[214:217], v[12:15]
	v_mfma_f32_16x16x32_bf16 v[8:11], v[160:163], v[214:217], v[8:11]
	v_mfma_f32_16x16x32_bf16 v[60:63], v[156:159], v[194:197], v[60:63]
	v_mfma_f32_16x16x32_bf16 v[56:59], v[164:167], v[194:197], v[56:59]
	v_mfma_f32_16x16x32_bf16 v[44:47], v[156:159], v[202:205], v[44:47]
	v_mfma_f32_16x16x32_bf16 v[40:43], v[164:167], v[202:205], v[40:43]
	v_mfma_f32_16x16x32_bf16 v[28:31], v[156:159], v[210:213], v[28:31]
	v_mfma_f32_16x16x32_bf16 v[24:27], v[164:167], v[210:213], v[24:27]
	v_mfma_f32_16x16x32_bf16 v[12:15], v[156:159], v[218:221], v[12:15]
	v_mfma_f32_16x16x32_bf16 v[8:11], v[164:167], v[218:221], v[8:11]
	s_setprio 0
	s_setprio 1
	v_mfma_f32_16x16x32_bf16 v[52:55], v[168:171], v[184:187], v[52:55]
	v_mfma_f32_16x16x32_bf16 v[48:51], v[176:179], v[184:187], v[48:51]
	v_mfma_f32_16x16x32_bf16 v[36:39], v[168:171], v[198:201], v[36:39]
	v_mfma_f32_16x16x32_bf16 v[32:35], v[176:179], v[198:201], v[32:35]
	v_mfma_f32_16x16x32_bf16 v[20:23], v[168:171], v[206:209], v[20:23]
	v_mfma_f32_16x16x32_bf16 v[16:19], v[176:179], v[206:209], v[16:19]
	v_mfma_f32_16x16x32_bf16 v[4:7], v[168:171], v[214:217], v[4:7]
	v_mfma_f32_16x16x32_bf16 v[0:3], v[176:179], v[214:217], v[0:3]
	v_mfma_f32_16x16x32_bf16 v[52:55], v[172:175], v[194:197], v[52:55]
	v_mfma_f32_16x16x32_bf16 v[48:51], v[180:183], v[194:197], v[48:51]
	v_mfma_f32_16x16x32_bf16 v[36:39], v[172:175], v[202:205], v[36:39]
	v_mfma_f32_16x16x32_bf16 v[32:35], v[180:183], v[202:205], v[32:35]
	v_mfma_f32_16x16x32_bf16 v[20:23], v[172:175], v[210:213], v[20:23]
	v_mfma_f32_16x16x32_bf16 v[16:19], v[180:183], v[210:213], v[16:19]
	v_mfma_f32_16x16x32_bf16 v[4:7], v[172:175], v[218:221], v[4:7]
	v_mfma_f32_16x16x32_bf16 v[0:3], v[180:183], v[218:221], v[0:3]
	s_setprio 0
	s_barrier
	s_add_i32 s67, 0, 0x18000
	v_add_u32_e32 v155, s67, v149
	s_add_i32 s68, 0, 0x1c000
	ds_read_b128 v[144:147], v155
	ds_read_b128 v[156:159], v155 offset:1024
	ds_read_b128 v[160:163], v155 offset:2048
	ds_read_b128 v[164:167], v155 offset:3072
	v_add_u32_e32 v155, s68, v149
	ds_read_b128 v[168:171], v155
	ds_read_b128 v[172:175], v155 offset:1024
	ds_read_b128 v[176:179], v155 offset:2048
	ds_read_b128 v[180:183], v155 offset:3072
	s_add_u32 s42, s42, 0x100000
	s_addc_u32 s43, s43, 0
	s_mov_b32 m0, s31
	v_lshl_add_u64 v[228:229], s[42:43], 0, v[128:129]
	ds_read_b128 v[184:187], v153 offset:32768
	ds_read_b128 v[194:197], v153 offset:33792
	ds_read_b128 v[198:201], v153 offset:34816
	ds_read_b128 v[202:205], v153 offset:35840
	ds_read_b128 v[206:209], v153 offset:36864
	ds_read_b128 v[210:213], v153 offset:37888
	ds_read_b128 v[214:217], v153 offset:38912
	ds_read_b128 v[218:221], v153 offset:39936
	global_load_lds_dwordx4 v[228:229], off
	v_lshl_add_u64 v[228:229], s[42:43], 0, v[132:133]
	s_mov_b32 m0, s33
	s_nop 0
	global_load_lds_dwordx4 v[228:229], off
	s_waitcnt vmcnt(8)
	s_waitcnt lgkmcnt(0)
	s_barrier
	s_setprio 1
	s_waitcnt lgkmcnt(0)
	v_mfma_f32_16x16x32_bf16 v[124:127], v[144:147], v[184:187], v[124:127]
	v_mfma_f32_16x16x32_bf16 v[120:123], v[160:163], v[184:187], v[120:123]
	v_mfma_f32_16x16x32_bf16 v[108:111], v[144:147], v[198:201], v[108:111]
	v_mfma_f32_16x16x32_bf16 v[104:107], v[160:163], v[198:201], v[104:107]
	v_mfma_f32_16x16x32_bf16 v[92:95], v[144:147], v[206:209], v[92:95]
	v_mfma_f32_16x16x32_bf16 v[88:91], v[160:163], v[206:209], v[88:91]
	v_mfma_f32_16x16x32_bf16 v[76:79], v[144:147], v[214:217], v[76:79]
	v_mfma_f32_16x16x32_bf16 v[72:75], v[160:163], v[214:217], v[72:75]
	v_mfma_f32_16x16x32_bf16 v[124:127], v[156:159], v[194:197], v[124:127]
	v_mfma_f32_16x16x32_bf16 v[120:123], v[164:167], v[194:197], v[120:123]
	v_mfma_f32_16x16x32_bf16 v[108:111], v[156:159], v[202:205], v[108:111]
	v_mfma_f32_16x16x32_bf16 v[104:107], v[164:167], v[202:205], v[104:107]
	v_mfma_f32_16x16x32_bf16 v[92:95], v[156:159], v[210:213], v[92:95]
	v_mfma_f32_16x16x32_bf16 v[88:91], v[164:167], v[210:213], v[88:91]
	v_mfma_f32_16x16x32_bf16 v[76:79], v[156:159], v[218:221], v[76:79]
	v_mfma_f32_16x16x32_bf16 v[72:75], v[164:167], v[218:221], v[72:75]
	s_setprio 0
	s_setprio 1
	v_mfma_f32_16x16x32_bf16 v[116:119], v[168:171], v[184:187], v[116:119]
	v_mfma_f32_16x16x32_bf16 v[112:115], v[176:179], v[184:187], v[112:115]
	v_mfma_f32_16x16x32_bf16 v[100:103], v[168:171], v[198:201], v[100:103]
	v_mfma_f32_16x16x32_bf16 v[96:99], v[176:179], v[198:201], v[96:99]
	v_mfma_f32_16x16x32_bf16 v[84:87], v[168:171], v[206:209], v[84:87]
	v_mfma_f32_16x16x32_bf16 v[80:83], v[176:179], v[206:209], v[80:83]
	v_mfma_f32_16x16x32_bf16 v[68:71], v[168:171], v[214:217], v[68:71]
	v_mfma_f32_16x16x32_bf16 v[64:67], v[176:179], v[214:217], v[64:67]
	v_mfma_f32_16x16x32_bf16 v[116:119], v[172:175], v[194:197], v[116:119]
	v_mfma_f32_16x16x32_bf16 v[112:115], v[180:183], v[194:197], v[112:115]
	v_mfma_f32_16x16x32_bf16 v[100:103], v[172:175], v[202:205], v[100:103]
	v_mfma_f32_16x16x32_bf16 v[96:99], v[180:183], v[202:205], v[96:99]
	v_mfma_f32_16x16x32_bf16 v[84:87], v[172:175], v[210:213], v[84:87]
	v_mfma_f32_16x16x32_bf16 v[80:83], v[180:183], v[210:213], v[80:83]
	v_mfma_f32_16x16x32_bf16 v[68:71], v[172:175], v[218:221], v[68:71]
	v_mfma_f32_16x16x32_bf16 v[64:67], v[180:183], v[218:221], v[64:67]
	s_setprio 0
	s_barrier
	s_add_i32 s42, s67, s3
	v_lshl_add_u64 v[188:189], v[188:189], 0, s[18:19]
	s_mov_b32 m0, s42
	ds_read_b128 v[184:187], v153 offset:49152
	ds_read_b128 v[194:197], v153 offset:50176
	ds_read_b128 v[198:201], v153 offset:51200
	ds_read_b128 v[202:205], v153 offset:52224
	ds_read_b128 v[206:209], v153 offset:53248
	ds_read_b128 v[210:213], v153 offset:54272
	ds_read_b128 v[214:217], v153 offset:55296
	ds_read_b128 v[218:221], v153 offset:56320
	global_load_lds_dwordx4 v[188:189], off
	s_add_i32 m0, s42, 0x2000
	s_add_u32 s40, s40, 0x100080
	v_lshl_add_u64 v[188:189], v[222:223], 0, s[18:19]
	s_addc_u32 s41, s41, 0
	s_add_i32 s42, s68, s3
	global_load_lds_dwordx4 v[188:189], off
	v_lshl_add_u64 v[188:189], s[40:41], 0, v[130:131]
	s_mov_b32 m0, s42
	s_nop 0
	global_load_lds_dwordx4 v[188:189], off
	v_lshl_add_u64 v[188:189], s[40:41], 0, v[134:135]
	s_add_i32 m0, s42, 0x2000
	s_nop 0
	global_load_lds_dwordx4 v[188:189], off
	v_lshl_add_u64 v[188:189], v[224:225], 0, s[18:19]
	s_mov_b32 m0, s46
	s_nop 0
	global_load_lds_dwordx4 v[188:189], off
	v_lshl_add_u64 v[188:189], v[226:227], 0, s[18:19]
	s_mov_b32 m0, s47
	s_nop 0
	global_load_lds_dwordx4 v[188:189], off
	s_waitcnt vmcnt(8)
	s_waitcnt lgkmcnt(0)
	s_barrier
	s_setprio 1
	s_waitcnt lgkmcnt(0)
	v_mfma_f32_16x16x32_bf16 v[60:63], v[144:147], v[184:187], v[60:63]
	v_mfma_f32_16x16x32_bf16 v[56:59], v[160:163], v[184:187], v[56:59]
	v_mfma_f32_16x16x32_bf16 v[44:47], v[144:147], v[198:201], v[44:47]
	v_mfma_f32_16x16x32_bf16 v[40:43], v[160:163], v[198:201], v[40:43]
	v_mfma_f32_16x16x32_bf16 v[28:31], v[144:147], v[206:209], v[28:31]
	v_mfma_f32_16x16x32_bf16 v[24:27], v[160:163], v[206:209], v[24:27]
	v_mfma_f32_16x16x32_bf16 v[12:15], v[144:147], v[214:217], v[12:15]
	v_mfma_f32_16x16x32_bf16 v[8:11], v[160:163], v[214:217], v[8:11]
	v_mfma_f32_16x16x32_bf16 v[60:63], v[156:159], v[194:197], v[60:63]
	v_mfma_f32_16x16x32_bf16 v[56:59], v[164:167], v[194:197], v[56:59]
	v_mfma_f32_16x16x32_bf16 v[44:47], v[156:159], v[202:205], v[44:47]
	v_mfma_f32_16x16x32_bf16 v[40:43], v[164:167], v[202:205], v[40:43]
	v_mfma_f32_16x16x32_bf16 v[28:31], v[156:159], v[210:213], v[28:31]
	v_mfma_f32_16x16x32_bf16 v[24:27], v[164:167], v[210:213], v[24:27]
	v_mfma_f32_16x16x32_bf16 v[12:15], v[156:159], v[218:221], v[12:15]
	v_mfma_f32_16x16x32_bf16 v[8:11], v[164:167], v[218:221], v[8:11]
	s_setprio 0
	s_setprio 1
	v_mfma_f32_16x16x32_bf16 v[52:55], v[168:171], v[184:187], v[52:55]
	v_mfma_f32_16x16x32_bf16 v[48:51], v[176:179], v[184:187], v[48:51]
	v_mfma_f32_16x16x32_bf16 v[36:39], v[168:171], v[198:201], v[36:39]
	v_mfma_f32_16x16x32_bf16 v[32:35], v[176:179], v[198:201], v[32:35]
	v_mfma_f32_16x16x32_bf16 v[20:23], v[168:171], v[206:209], v[20:23]
	v_mfma_f32_16x16x32_bf16 v[16:19], v[176:179], v[206:209], v[16:19]
	v_mfma_f32_16x16x32_bf16 v[4:7], v[168:171], v[214:217], v[4:7]
	v_mfma_f32_16x16x32_bf16 v[0:3], v[176:179], v[214:217], v[0:3]
	v_mfma_f32_16x16x32_bf16 v[52:55], v[172:175], v[194:197], v[52:55]
	v_mfma_f32_16x16x32_bf16 v[48:51], v[180:183], v[194:197], v[48:51]
	v_mfma_f32_16x16x32_bf16 v[36:39], v[172:175], v[202:205], v[36:39]
	v_mfma_f32_16x16x32_bf16 v[32:35], v[180:183], v[202:205], v[32:35]
	v_mfma_f32_16x16x32_bf16 v[20:23], v[172:175], v[210:213], v[20:23]
	v_mfma_f32_16x16x32_bf16 v[16:19], v[180:183], v[210:213], v[16:19]
	v_mfma_f32_16x16x32_bf16 v[4:7], v[172:175], v[218:221], v[4:7]
	v_mfma_f32_16x16x32_bf16 v[0:3], v[180:183], v[218:221], v[0:3]
	s_setprio 0
	s_barrier
	s_add_i32 s66, s66, 2
	s_add_u32 s38, s38, 0x100
	s_addc_u32 s39, s39, 0
	s_add_u32 s64, s64, 0x100
	s_addc_u32 s65, s65, 0
	s_cmp_gt_u32 s66, 61
	s_cbranch_scc0 .LBB0_1326
	s_and_b64 vcc, exec, s[20:21]
	s_cbranch_vccz .LBB0_1329
	s_barrier

	.amdhsa_kernel _Z10fwd_kernel4Args
		.amdhsa_group_segment_fixed_size 0
		.amdhsa_private_segment_fixed_size 0
		.amdhsa_kernarg_size 416
		.amdhsa_user_sgpr_count 2
		.amdhsa_user_sgpr_dispatch_ptr 0
		.amdhsa_user_sgpr_queue_ptr 0
		.amdhsa_user_sgpr_kernarg_segment_ptr 1
		.amdhsa_user_sgpr_dispatch_id 0
		.amdhsa_user_sgpr_kernarg_preload_length 0
		.amdhsa_user_sgpr_kernarg_preload_offset 0
		.amdhsa_user_sgpr_private_segment_size 0
		.amdhsa_uses_dynamic_stack 0
		.amdhsa_enable_private_segment 0
		.amdhsa_system_sgpr_workgroup_id_x 1
		.amdhsa_system_sgpr_workgroup_id_y 0
		.amdhsa_system_sgpr_workgroup_id_z 0
		.amdhsa_system_sgpr_workgroup_info 0
		.amdhsa_system_vgpr_workitem_id 2
		.amdhsa_next_free_vgpr 255
		.amdhsa_next_free_sgpr 102
		.amdhsa_accum_offset 256
		.amdhsa_reserve_vcc 1
		.amdhsa_float_round_mode_32 0
		.amdhsa_float_round_mode_16_64 0
		.amdhsa_float_denorm_mode_32 3
		.amdhsa_float_denorm_mode_16_64 3
		.amdhsa_dx10_clamp 1
		.amdhsa_ieee_mode 1
		.amdhsa_fp16_overflow 0
		.amdhsa_tg_split 0
		.amdhsa_exception_fp_ieee_invalid_op 0
		.amdhsa_exception_fp_denorm_src 0
		.amdhsa_exception_fp_ieee_div_zero 0
		.amdhsa_exception_fp_ieee_overflow 0
		.amdhsa_exception_fp_ieee_underflow 0
		.amdhsa_exception_fp_ieee_inexact 0
		.amdhsa_exception_int_div_zero 0
	.end_amdhsa_kernel

amdhsa.kernels:
  - .agpr_count:     0
    .args:
      - .offset:         0
        .size:           160
        .value_kind:     by_value
      - .offset:         160
        .size:           4
        .value_kind:     hidden_block_count_x
      - .offset:         164
        .size:           4
        .value_kind:     hidden_block_count_y
      - .offset:         168
        .size:           4
        .value_kind:     hidden_block_count_z
      - .offset:         172
        .size:           2
        .value_kind:     hidden_group_size_x
      - .offset:         174
        .size:           2
        .value_kind:     hidden_group_size_y
      - .offset:         176
        .size:           2
        .value_kind:     hidden_group_size_z
      - .offset:         178
        .size:           2
        .value_kind:     hidden_remainder_x
      - .offset:         180
        .size:           2
        .value_kind:     hidden_remainder_y
      - .offset:         182
        .size:           2
        .value_kind:     hidden_remainder_z
      - .offset:         200
        .size:           8
        .value_kind:     hidden_global_offset_x
      - .offset:         208
        .size:           8
        .value_kind:     hidden_global_offset_y
      - .offset:         216
        .size:           8
        .value_kind:     hidden_global_offset_z
      - .offset:         224
        .size:           2
        .value_kind:     hidden_grid_dims
      - .offset:         248
        .size:           8
        .value_kind:     hidden_multigrid_sync_arg
      - .offset:         280
        .size:           4
        .value_kind:     hidden_dynamic_lds_size
    .group_segment_fixed_size: 0
    .kernarg_segment_align: 8
    .kernarg_segment_size: 416
    .language:       OpenCL C
    .language_version:
      - 2
      - 0
    .max_flat_workgroup_size: 512
    .name:           _Z10fwd_kernel4Args
    .private_segment_fixed_size: 0
    .sgpr_count:     108
    .sgpr_spill_count: 60
    .symbol:         _Z10fwd_kernel4Args.kd
    .uniform_work_group_size: 1
    .uses_dynamic_stack: false
    .vgpr_count:     255
    .vgpr_spill_count: 0
    .wavefront_size: 64
